# v36 + post-barrier lgkmcnt(0) taken off the barrier->first-MFMA path: counted lgkmcnt(N) before the barrier for the first chain's operands, first chain issued right after the barrier, full wait behind
# speedup vs baseline: 1.0129x; 1.0044x over previous
; #define PG8_WAIT_V(n) asm volatile("s_waitcnt vmcnt(" #n ")" ::: "memory")
; #define PG8_WAIT_L(n) asm volatile("s_waitcnt lgkmcnt(" #n ")" ::: "memory")
; #define PG8_BAR __builtin_amdgcn_s_barrier()
; #define PG8_SCHED __builtin_amdgcn_sched_barrier(0)
; template <class Epi, class AddrA, class AddrB>
; __device__ __forceinline__ void gemm_phase(const Sched S, const int lda, const int ldb, const int K, const AddrA addrA,
;                                            const AddrB addrB, const Epi E) {
;     ...
;     const bool has_next = S.next(ui + 1, nxt);
;     const char* nA = has_next ? addrA(nxt) : cA;
;     const char* nB = has_next ? addrB(nxt) : cB;
;     for (int t = 0; t < nt; t += 2) {
;       const bool last = (t == nt - 2);
;       const char* a1 = cA + (size_t)(t + 1) * kstep;
;       const char* a2 = last ? nA : cA + (size_t)(t + 2) * kstep;
;       const char* b2 = last ? nB : cB + (size_t)(t + 2) * kstep;
;       const char* a3 = a2 + kstep;
;       const char* b3 = b2 + kstep;
;       PG8_LDB(B0, 0, 0); PG8_SCHED; PG8_LDA(At, 0, 0); PG8_STAGE(PG8_SA(1, 1), a1 + hstepA, voffA);
;       PG8_WAIT_L(8); PG8_BAR; PG8_WAIT_L(0); PG8_MMA(0, 0, At, B0); PG8_BAR; PG8_SCHED;
;       PG8_LDB(B1, 0, 1); PG8_STAGE(PG8_SB(0, 0), b2, voffB);
;       PG8_BAR; PG8_WAIT_L(0); PG8_MMA(0, 1, At, B1); PG8_BAR;
;       PG8_LDA(At, 0, 1); PG8_STAGE(PG8_SA(0, 0), a2, voffA);
;       PG8_BAR; PG8_WAIT_L(0); PG8_MMA(1, 0, At, B0); PG8_BAR; PG8_SCHED;
;       PG8_STAGE(PG8_SB(0, 1), b2 + hstepB, voffB);
;       PG8_WAIT_V(6); PG8_BAR; PG8_MMA(1, 1, At, B1); PG8_BAR;
.LBB0_108:
	s_ashr_i32 s1, s0, 31
	s_lshl_b64 s[6:7], s[0:1], 20
	s_add_u32 s6, s20, s6
	s_addc_u32 s7, s21, s7
	s_and_b64 s[8:9], s[16:17], exec
	s_cselect_b32 s1, s7, s15
	s_cselect_b32 s11, s6, s14
	s_ashr_i32 s3, s2, 31
	s_lshl_b64 s[8:9], s[2:3], 20
	s_add_u32 s8, s22, s8
	s_addc_u32 s9, s23, s9
	s_and_b64 s[16:17], s[16:17], exec
	s_cselect_b32 s3, s9, s13
	s_cselect_b32 s36, s8, s12
	s_add_u32 s37, s12, 0x100
	s_addc_u32 s38, s13, 0
	s_add_u32 s12, s14, 0x80080
	s_addc_u32 s13, s15, 0
	s_mov_b32 s39, -2
	s_add_i32 s40, 0, 0x10000
	v_add_u32_e32 v142, s40, v145
	ds_read_b128 v[148:151], v142
	ds_read_b128 v[152:155], v142 offset:1024
	ds_read_b128 v[156:159], v142 offset:2048
	ds_read_b128 v[160:163], v142 offset:3072
	v_lshl_add_u64 v[142:143], s[12:13], 0, v[140:141]
	s_add_i32 m0, s24, 0xc000
	ds_read_b128 v[168:171], v146
	ds_read_b128 v[172:175], v146 offset:1024
	ds_read_b128 v[176:179], v146 offset:2048
	ds_read_b128 v[180:183], v146 offset:3072
	ds_read_b128 v[184:187], v146 offset:4096
	ds_read_b128 v[188:191], v146 offset:5120
	ds_read_b128 v[192:195], v146 offset:6144
	ds_read_b128 v[212:215], v146 offset:7168
	global_load_lds_dwordx4 v[142:143], off
	v_lshl_add_u64 v[142:143], s[12:13], 0, v[138:139]
	s_add_i32 m0, s24, 0xe000
	s_nop 0
	global_load_lds_dwordx4 v[142:143], off
	s_waitcnt lgkmcnt(6)
	s_setprio 1
	s_barrier
	v_mfma_f32_16x16x32_bf16 v[128:131], v[148:151], v[168:171], 0
	v_mfma_f32_16x16x32_bf16 v[128:131], v[152:155], v[172:175], v[128:131]
	s_waitcnt lgkmcnt(0)
	v_mfma_f32_16x16x32_bf16 v[120:123], v[148:151], v[176:179], 0
	v_mfma_f32_16x16x32_bf16 v[120:123], v[152:155], v[180:183], v[120:123]
	v_mfma_f32_16x16x32_bf16 v[104:107], v[148:151], v[184:187], 0
	v_mfma_f32_16x16x32_bf16 v[104:107], v[152:155], v[188:191], v[104:107]
	v_mfma_f32_16x16x32_bf16 v[88:91], v[148:151], v[192:195], 0
	v_mfma_f32_16x16x32_bf16 v[88:91], v[152:155], v[212:215], v[88:91]
	v_mfma_f32_16x16x32_bf16 v[124:127], v[156:159], v[168:171], 0
	v_mfma_f32_16x16x32_bf16 v[124:127], v[160:163], v[172:175], v[124:127]
	v_mfma_f32_16x16x32_bf16 v[112:115], v[156:159], v[176:179], 0
	v_mfma_f32_16x16x32_bf16 v[112:115], v[160:163], v[180:183], v[112:115]
	v_mfma_f32_16x16x32_bf16 v[96:99], v[156:159], v[184:187], 0
	v_mfma_f32_16x16x32_bf16 v[96:99], v[160:163], v[188:191], v[96:99]
	v_mfma_f32_16x16x32_bf16 v[80:83], v[156:159], v[192:195], 0
	v_mfma_f32_16x16x32_bf16 v[80:83], v[160:163], v[212:215], v[80:83]
	s_barrier
	s_setprio 0
	s_add_u32 s14, s12, 0xfff80080
	s_addc_u32 s15, s13, -1
	s_cmp_eq_u32 s39, 28
	s_cselect_b32 s17, s1, s15
	s_cselect_b32 s16, s11, s14
	s_cselect_b32 s15, s3, s38
	s_cselect_b32 s14, s36, s37
	s_add_i32 s42, 0, 0x14000
	v_add_u32_e32 v142, s42, v145
	s_add_i32 s40, s40, s19
	ds_read_b128 v[216:219], v142
	ds_read_b128 v[220:223], v142 offset:1024
	ds_read_b128 v[224:227], v142 offset:2048
	ds_read_b128 v[228:231], v142 offset:3072
	v_lshl_add_u64 v[142:143], s[14:15], 0, v[134:135]
	s_mov_b32 m0, s40
	v_lshl_add_u64 v[196:197], s[14:15], 0, v[0:1]
	global_load_lds_dwordx4 v[142:143], off
	s_add_i32 m0, s40, 0x2000
	s_nop 0
	global_load_lds_dwordx4 v[196:197], off
	s_mov_b32 m0, s24
	v_lshl_add_u64 v[232:233], s[16:17], 0, v[136:137]
	s_waitcnt lgkmcnt(2)
	s_setprio 1
	s_barrier
	v_mfma_f32_16x16x32_bf16 v[116:119], v[216:219], v[168:171], 0
	v_mfma_f32_16x16x32_bf16 v[116:119], v[220:223], v[172:175], v[116:119]
	s_waitcnt lgkmcnt(0)
	v_mfma_f32_16x16x32_bf16 v[100:103], v[216:219], v[176:179], 0
	v_mfma_f32_16x16x32_bf16 v[100:103], v[220:223], v[180:183], v[100:103]
	v_mfma_f32_16x16x32_bf16 v[84:87], v[216:219], v[184:187], 0
	v_mfma_f32_16x16x32_bf16 v[84:87], v[220:223], v[188:191], v[84:87]
	v_mfma_f32_16x16x32_bf16 v[72:75], v[216:219], v[192:195], 0
	v_mfma_f32_16x16x32_bf16 v[72:75], v[220:223], v[212:215], v[72:75]
	v_mfma_f32_16x16x32_bf16 v[108:111], v[224:227], v[168:171], 0
	v_mfma_f32_16x16x32_bf16 v[108:111], v[228:231], v[172:175], v[108:111]
	v_mfma_f32_16x16x32_bf16 v[92:95], v[224:227], v[176:179], 0
	v_mfma_f32_16x16x32_bf16 v[92:95], v[228:231], v[180:183], v[92:95]
	v_mfma_f32_16x16x32_bf16 v[76:79], v[224:227], v[184:187], 0
	v_mfma_f32_16x16x32_bf16 v[76:79], v[228:231], v[188:191], v[76:79]
	v_mfma_f32_16x16x32_bf16 v[68:71], v[224:227], v[192:195], 0
	v_mfma_f32_16x16x32_bf16 v[68:71], v[228:231], v[212:215], v[68:71]
	s_barrier
	s_setprio 0
	ds_read_b128 v[168:171], v146 offset:16384
	ds_read_b128 v[172:175], v146 offset:17408
	ds_read_b128 v[176:179], v146 offset:18432
	ds_read_b128 v[180:183], v146 offset:19456
	ds_read_b128 v[184:187], v146 offset:20480
	ds_read_b128 v[188:191], v146 offset:21504
	ds_read_b128 v[192:195], v146 offset:22528
	ds_read_b128 v[212:215], v146 offset:23552
	global_load_lds_dwordx4 v[232:233], off
	v_lshl_add_u64 v[234:235], s[16:17], 0, v[132:133]
	s_mov_b32 m0, s25
	s_nop 0
	global_load_lds_dwordx4 v[234:235], off
	s_waitcnt lgkmcnt(6)
	s_setprio 1
	s_barrier
	v_mfma_f32_16x16x32_bf16 v[64:67], v[148:151], v[168:171], 0
	v_mfma_f32_16x16x32_bf16 v[64:67], v[152:155], v[172:175], v[64:67]
	s_waitcnt lgkmcnt(0)
	v_mfma_f32_16x16x32_bf16 v[56:59], v[148:151], v[176:179], 0
	v_mfma_f32_16x16x32_bf16 v[56:59], v[152:155], v[180:183], v[56:59]
	v_mfma_f32_16x16x32_bf16 v[40:43], v[148:151], v[184:187], 0
	v_mfma_f32_16x16x32_bf16 v[40:43], v[152:155], v[188:191], v[40:43]
	v_mfma_f32_16x16x32_bf16 v[24:27], v[148:151], v[192:195], 0
	v_mfma_f32_16x16x32_bf16 v[24:27], v[152:155], v[212:215], v[24:27]
	v_mfma_f32_16x16x32_bf16 v[60:63], v[156:159], v[168:171], 0
	v_mfma_f32_16x16x32_bf16 v[60:63], v[160:163], v[172:175], v[60:63]
	v_mfma_f32_16x16x32_bf16 v[48:51], v[156:159], v[176:179], 0
	v_mfma_f32_16x16x32_bf16 v[48:51], v[160:163], v[180:183], v[48:51]
	v_mfma_f32_16x16x32_bf16 v[32:35], v[156:159], v[184:187], 0
	v_mfma_f32_16x16x32_bf16 v[32:35], v[160:163], v[188:191], v[32:35]
	v_mfma_f32_16x16x32_bf16 v[16:19], v[156:159], v[192:195], 0
	v_mfma_f32_16x16x32_bf16 v[16:19], v[160:163], v[212:215], v[16:19]
	s_barrier
; #define PG8_WAIT_V(n) asm volatile("s_waitcnt vmcnt(" #n ")" ::: "memory")
; #define PG8_WAIT_L(n) asm volatile("s_waitcnt lgkmcnt(" #n ")" ::: "memory")
; #define PG8_BAR __builtin_amdgcn_s_barrier()
; #define PG8_SCHED __builtin_amdgcn_sched_barrier(0)
; template <class Epi, class AddrA, class AddrB>
; __device__ __forceinline__ void gemm_phase(const Sched S, const int lda, const int ldb, const int K, const AddrA addrA,
;                                            const AddrB addrB, const Epi E) {
;     ...
;       PG8_BAR; PG8_WAIT_L(0); PG8_MMA(1, 0, At, B0); PG8_BAR; PG8_SCHED;
;       PG8_STAGE(PG8_SB(0, 1), b2 + hstepB, voffB);
;       PG8_WAIT_V(6); PG8_BAR; PG8_MMA(1, 1, At, B1); PG8_BAR;
;       PG8_LDB(B0, 1, 0); PG8_SCHED; PG8_LDA(At, 1, 0); PG8_STAGE(PG8_SA(0, 1), a2 + hstepA, voffA);
;       PG8_WAIT_L(8); PG8_BAR; PG8_WAIT_L(0); PG8_MMA(0, 0, At, B0); PG8_BAR; PG8_SCHED;
;       PG8_LDB(B1, 1, 1); PG8_STAGE(PG8_SB(1, 0), b3, voffB);
;       PG8_BAR; PG8_WAIT_L(0); PG8_MMA(0, 1, At, B1); PG8_BAR;
;       PG8_LDA(At, 1, 1); PG8_STAGE(PG8_SA(1, 0), a3, voffA);
;       PG8_BAR; PG8_WAIT_L(0); PG8_MMA(1, 0, At, B0); PG8_BAR; PG8_SCHED;
	s_setprio 0
	s_add_u32 s40, s14, 0x80000
	s_addc_u32 s41, s15, 0
	s_add_i32 s42, s42, s19
	v_lshl_add_u64 v[148:149], s[40:41], 0, v[134:135]
	s_mov_b32 m0, s42
	s_nop 0
	global_load_lds_dwordx4 v[148:149], off
	v_lshl_add_u64 v[148:149], s[40:41], 0, v[0:1]
	s_add_i32 m0, s42, 0x2000
	s_nop 0
	global_load_lds_dwordx4 v[148:149], off
	s_add_i32 s40, 0, 0x18000
	v_add_u32_e32 v147, s40, v145
	s_waitcnt vmcnt(6)
	s_setprio 1
	s_barrier
	v_mfma_f32_16x16x32_bf16 v[52:55], v[216:219], v[168:171], 0
	v_mfma_f32_16x16x32_bf16 v[52:55], v[220:223], v[172:175], v[52:55]
	v_mfma_f32_16x16x32_bf16 v[36:39], v[216:219], v[176:179], 0
	v_mfma_f32_16x16x32_bf16 v[36:39], v[220:223], v[180:183], v[36:39]
	v_mfma_f32_16x16x32_bf16 v[20:23], v[216:219], v[184:187], 0
	v_mfma_f32_16x16x32_bf16 v[20:23], v[220:223], v[188:191], v[20:23]
	v_mfma_f32_16x16x32_bf16 v[8:11], v[216:219], v[192:195], 0
	v_mfma_f32_16x16x32_bf16 v[8:11], v[220:223], v[212:215], v[8:11]
	v_mfma_f32_16x16x32_bf16 v[44:47], v[224:227], v[168:171], 0
	v_mfma_f32_16x16x32_bf16 v[44:47], v[228:231], v[172:175], v[44:47]
	v_mfma_f32_16x16x32_bf16 v[28:31], v[224:227], v[176:179], 0
	v_mfma_f32_16x16x32_bf16 v[28:31], v[228:231], v[180:183], v[28:31]
	v_mfma_f32_16x16x32_bf16 v[12:15], v[224:227], v[184:187], 0
	v_mfma_f32_16x16x32_bf16 v[12:15], v[228:231], v[188:191], v[12:15]
	v_mfma_f32_16x16x32_bf16 v[4:7], v[224:227], v[192:195], 0
	v_mfma_f32_16x16x32_bf16 v[4:7], v[228:231], v[212:215], v[4:7]
	s_barrier
	s_setprio 0
	ds_read_b128 v[148:151], v147
	ds_read_b128 v[152:155], v147 offset:1024
	ds_read_b128 v[156:159], v147 offset:2048
	ds_read_b128 v[160:163], v147 offset:3072
	s_add_u32 s16, s16, 0x80000
	s_addc_u32 s17, s17, 0
	s_mov_b32 m0, s26
	v_lshl_add_u64 v[216:217], s[16:17], 0, v[136:137]
	ds_read_b128 v[168:171], v146 offset:32768
	ds_read_b128 v[172:175], v146 offset:33792
	ds_read_b128 v[176:179], v146 offset:34816
	ds_read_b128 v[180:183], v146 offset:35840
	ds_read_b128 v[184:187], v146 offset:36864
	ds_read_b128 v[188:191], v146 offset:37888
	ds_read_b128 v[192:195], v146 offset:38912
	ds_read_b128 v[212:215], v146 offset:39936
	global_load_lds_dwordx4 v[216:217], off
	v_lshl_add_u64 v[216:217], s[16:17], 0, v[132:133]
	s_mov_b32 m0, s27
	s_nop 0
	global_load_lds_dwordx4 v[216:217], off
	s_waitcnt lgkmcnt(6)
	s_setprio 1
	s_barrier
	v_mfma_f32_16x16x32_bf16 v[128:131], v[148:151], v[168:171], v[128:131]
	v_mfma_f32_16x16x32_bf16 v[128:131], v[152:155], v[172:175], v[128:131]
	s_waitcnt lgkmcnt(0)
	v_mfma_f32_16x16x32_bf16 v[120:123], v[148:151], v[176:179], v[120:123]
	v_mfma_f32_16x16x32_bf16 v[120:123], v[152:155], v[180:183], v[120:123]
	v_mfma_f32_16x16x32_bf16 v[104:107], v[148:151], v[184:187], v[104:107]
	v_mfma_f32_16x16x32_bf16 v[104:107], v[152:155], v[188:191], v[104:107]
	v_mfma_f32_16x16x32_bf16 v[88:91], v[148:151], v[192:195], v[88:91]
	v_mfma_f32_16x16x32_bf16 v[88:91], v[152:155], v[212:215], v[88:91]
	v_mfma_f32_16x16x32_bf16 v[124:127], v[156:159], v[168:171], v[124:127]
	v_mfma_f32_16x16x32_bf16 v[124:127], v[160:163], v[172:175], v[124:127]
	v_mfma_f32_16x16x32_bf16 v[112:115], v[156:159], v[176:179], v[112:115]
	v_mfma_f32_16x16x32_bf16 v[112:115], v[160:163], v[180:183], v[112:115]
	v_mfma_f32_16x16x32_bf16 v[96:99], v[156:159], v[184:187], v[96:99]
	v_mfma_f32_16x16x32_bf16 v[96:99], v[160:163], v[188:191], v[96:99]
	v_mfma_f32_16x16x32_bf16 v[80:83], v[156:159], v[192:195], v[80:83]
	v_mfma_f32_16x16x32_bf16 v[80:83], v[160:163], v[212:215], v[80:83]
	s_barrier
	s_setprio 0
	s_add_i32 s16, 0, 0x1c000
	s_add_i32 s17, s40, s19
	v_add_u32_e32 v147, s16, v145
	v_lshl_add_u64 v[142:143], v[142:143], 0, s[52:53]
	s_mov_b32 m0, s17
	ds_read_b128 v[216:219], v147
	ds_read_b128 v[220:223], v147 offset:1024
	ds_read_b128 v[224:227], v147 offset:2048
	ds_read_b128 v[228:231], v147 offset:3072
	global_load_lds_dwordx4 v[142:143], off
	v_lshl_add_u64 v[142:143], v[196:197], 0, s[52:53]
	s_add_i32 m0, s17, 0x2000
	s_nop 0
	global_load_lds_dwordx4 v[142:143], off
	s_mov_b32 m0, s30
	v_lshl_add_u64 v[142:143], v[232:233], 0, s[52:53]
	s_waitcnt lgkmcnt(2)
	s_setprio 1
	s_barrier
	v_mfma_f32_16x16x32_bf16 v[116:119], v[216:219], v[168:171], v[116:119]
	v_mfma_f32_16x16x32_bf16 v[116:119], v[220:223], v[172:175], v[116:119]
	s_waitcnt lgkmcnt(0)
	v_mfma_f32_16x16x32_bf16 v[100:103], v[216:219], v[176:179], v[100:103]
	v_mfma_f32_16x16x32_bf16 v[100:103], v[220:223], v[180:183], v[100:103]
	v_mfma_f32_16x16x32_bf16 v[84:87], v[216:219], v[184:187], v[84:87]
	v_mfma_f32_16x16x32_bf16 v[84:87], v[220:223], v[188:191], v[84:87]
	v_mfma_f32_16x16x32_bf16 v[72:75], v[216:219], v[192:195], v[72:75]
	v_mfma_f32_16x16x32_bf16 v[72:75], v[220:223], v[212:215], v[72:75]
	v_mfma_f32_16x16x32_bf16 v[108:111], v[224:227], v[168:171], v[108:111]
	v_mfma_f32_16x16x32_bf16 v[108:111], v[228:231], v[172:175], v[108:111]
	v_mfma_f32_16x16x32_bf16 v[92:95], v[224:227], v[176:179], v[92:95]
	v_mfma_f32_16x16x32_bf16 v[92:95], v[228:231], v[180:183], v[92:95]
	v_mfma_f32_16x16x32_bf16 v[76:79], v[224:227], v[184:187], v[76:79]
	v_mfma_f32_16x16x32_bf16 v[76:79], v[228:231], v[188:191], v[76:79]
	v_mfma_f32_16x16x32_bf16 v[68:71], v[224:227], v[192:195], v[68:71]
	v_mfma_f32_16x16x32_bf16 v[68:71], v[228:231], v[212:215], v[68:71]
	s_barrier
	s_setprio 0
	ds_read_b128 v[168:171], v146 offset:49152
	ds_read_b128 v[172:175], v146 offset:50176
	ds_read_b128 v[176:179], v146 offset:51200
	ds_read_b128 v[180:183], v146 offset:52224
	ds_read_b128 v[184:187], v146 offset:53248
	ds_read_b128 v[188:191], v146 offset:54272
	ds_read_b128 v[192:195], v146 offset:55296
	ds_read_b128 v[212:215], v146 offset:56320
	global_load_lds_dwordx4 v[142:143], off
	v_lshl_add_u64 v[142:143], v[234:235], 0, s[52:53]
	s_mov_b32 m0, s31
	s_nop 0
	global_load_lds_dwordx4 v[142:143], off
	s_waitcnt lgkmcnt(6)
	s_setprio 1
	s_barrier
; #define PG8_WAIT_V(n) asm volatile("s_waitcnt vmcnt(" #n ")" ::: "memory")
; #define PG8_WAIT_L(n) asm volatile("s_waitcnt lgkmcnt(" #n ")" ::: "memory")
; #define PG8_BAR __builtin_amdgcn_s_barrier()
; #define PG8_SCHED __builtin_amdgcn_sched_barrier(0)
; template <class Epi, class AddrA, class AddrB>
; __device__ __forceinline__ void gemm_phase(const Sched S, const int lda, const int ldb, const int K, const AddrA addrA,
;                                            const AddrB addrB, const Epi E) {
;     ...
;       PG8_LDB(B0, 0, 0); PG8_SCHED; PG8_LDA(At, 0, 0); PG8_STAGE(PG8_SA(1, 1), a1 + hstepA, voffA);
;       PG8_WAIT_L(8); PG8_BAR; PG8_WAIT_L(0); PG8_MMA(0, 0, At, B0); PG8_BAR; PG8_SCHED;
;       PG8_LDB(B1, 0, 1); PG8_STAGE(PG8_SB(0, 0), b2, voffB);
;       PG8_BAR; PG8_WAIT_L(0); PG8_MMA(0, 1, At, B1); PG8_BAR;
;     ...
;       PG8_WAIT_V(6); PG8_BAR; PG8_MMA(1, 1, At, B1); PG8_BAR;
;       PG8_LDB(B0, 1, 0); PG8_SCHED; PG8_LDA(At, 1, 0); PG8_STAGE(PG8_SA(0, 1), a2 + hstepA, voffA);
;       PG8_WAIT_L(8); PG8_BAR; PG8_WAIT_L(0); PG8_MMA(0, 0, At, B0); PG8_BAR; PG8_SCHED;
;       PG8_LDB(B1, 1, 1); PG8_STAGE(PG8_SB(1, 0), b3, voffB);
;       PG8_BAR; PG8_WAIT_L(0); PG8_MMA(0, 1, At, B1); PG8_BAR;
;       PG8_LDA(At, 1, 1); PG8_STAGE(PG8_SA(1, 0), a3, voffA);
;       PG8_BAR; PG8_WAIT_L(0); PG8_MMA(1, 0, At, B0); PG8_BAR; PG8_SCHED;
;       PG8_STAGE(PG8_SB(1, 1), b3 + hstepB, voffB);
;       PG8_WAIT_V(6); PG8_BAR; PG8_MMA(1, 1, At, B1); PG8_BAR;
	v_mfma_f32_16x16x32_bf16 v[64:67], v[148:151], v[168:171], v[64:67]
	v_mfma_f32_16x16x32_bf16 v[64:67], v[152:155], v[172:175], v[64:67]
	s_waitcnt lgkmcnt(0)
	v_mfma_f32_16x16x32_bf16 v[56:59], v[148:151], v[176:179], v[56:59]
	v_mfma_f32_16x16x32_bf16 v[56:59], v[152:155], v[180:183], v[56:59]
	v_mfma_f32_16x16x32_bf16 v[40:43], v[148:151], v[184:187], v[40:43]
	v_mfma_f32_16x16x32_bf16 v[40:43], v[152:155], v[188:191], v[40:43]
	v_mfma_f32_16x16x32_bf16 v[24:27], v[148:151], v[192:195], v[24:27]
	v_mfma_f32_16x16x32_bf16 v[24:27], v[152:155], v[212:215], v[24:27]
	v_mfma_f32_16x16x32_bf16 v[60:63], v[156:159], v[168:171], v[60:63]
	v_mfma_f32_16x16x32_bf16 v[60:63], v[160:163], v[172:175], v[60:63]
	v_mfma_f32_16x16x32_bf16 v[48:51], v[156:159], v[176:179], v[48:51]
	v_mfma_f32_16x16x32_bf16 v[48:51], v[160:163], v[180:183], v[48:51]
	v_mfma_f32_16x16x32_bf16 v[32:35], v[156:159], v[184:187], v[32:35]
	v_mfma_f32_16x16x32_bf16 v[32:35], v[160:163], v[188:191], v[32:35]
	v_mfma_f32_16x16x32_bf16 v[16:19], v[156:159], v[192:195], v[16:19]
	v_mfma_f32_16x16x32_bf16 v[16:19], v[160:163], v[212:215], v[16:19]
	s_barrier
	s_setprio 0
	s_add_u32 s14, s14, 0x80080
	s_addc_u32 s15, s15, 0
	s_add_i32 s16, s16, s19
	v_lshl_add_u64 v[142:143], s[14:15], 0, v[134:135]
	s_mov_b32 m0, s16
	s_nop 0
	global_load_lds_dwordx4 v[142:143], off
	v_lshl_add_u64 v[142:143], s[14:15], 0, v[0:1]
	s_add_i32 m0, s16, 0x2000
	s_nop 0
	global_load_lds_dwordx4 v[142:143], off
	s_add_i32 s39, s39, 2
	s_add_u32 s37, s37, 0x100
	s_addc_u32 s38, s38, 0
	s_add_u32 s12, s12, 0x100
	s_addc_u32 s13, s13, 0
	s_waitcnt vmcnt(6)
	s_setprio 1
	s_barrier
	v_mfma_f32_16x16x32_bf16 v[52:55], v[216:219], v[168:171], v[52:55]
	v_mfma_f32_16x16x32_bf16 v[52:55], v[220:223], v[172:175], v[52:55]
	v_mfma_f32_16x16x32_bf16 v[36:39], v[216:219], v[176:179], v[36:39]
	v_mfma_f32_16x16x32_bf16 v[36:39], v[220:223], v[180:183], v[36:39]
	v_mfma_f32_16x16x32_bf16 v[20:23], v[216:219], v[184:187], v[20:23]
	v_mfma_f32_16x16x32_bf16 v[20:23], v[220:223], v[188:191], v[20:23]
	v_mfma_f32_16x16x32_bf16 v[8:11], v[216:219], v[192:195], v[8:11]
	v_mfma_f32_16x16x32_bf16 v[8:11], v[220:223], v[212:215], v[8:11]
	v_mfma_f32_16x16x32_bf16 v[44:47], v[224:227], v[168:171], v[44:47]
	v_mfma_f32_16x16x32_bf16 v[44:47], v[228:231], v[172:175], v[44:47]
	v_mfma_f32_16x16x32_bf16 v[28:31], v[224:227], v[176:179], v[28:31]
	v_mfma_f32_16x16x32_bf16 v[28:31], v[228:231], v[180:183], v[28:31]
	v_mfma_f32_16x16x32_bf16 v[12:15], v[224:227], v[184:187], v[12:15]
	v_mfma_f32_16x16x32_bf16 v[12:15], v[228:231], v[188:191], v[12:15]
	v_mfma_f32_16x16x32_bf16 v[4:7], v[224:227], v[192:195], v[4:7]
	v_mfma_f32_16x16x32_bf16 v[4:7], v[228:231], v[212:215], v[4:7]
	s_barrier
	s_setprio 0
	s_cmp_gt_u32 s39, 29
.LBB0_109:
	s_add_i32 s40, 0, 0x10000
	v_add_u32_e32 v142, s40, v145
	ds_read_b128 v[148:151], v142
	ds_read_b128 v[152:155], v142 offset:1024
	ds_read_b128 v[156:159], v142 offset:2048
	ds_read_b128 v[160:163], v142 offset:3072
	v_lshl_add_u64 v[142:143], s[12:13], 0, v[140:141]
	s_add_i32 m0, s24, 0xc000
	ds_read_b128 v[168:171], v146
	ds_read_b128 v[172:175], v146 offset:1024
	ds_read_b128 v[176:179], v146 offset:2048
	ds_read_b128 v[180:183], v146 offset:3072
	ds_read_b128 v[184:187], v146 offset:4096
	ds_read_b128 v[188:191], v146 offset:5120
	ds_read_b128 v[192:195], v146 offset:6144
	ds_read_b128 v[212:215], v146 offset:7168
	global_load_lds_dwordx4 v[142:143], off
	v_lshl_add_u64 v[142:143], s[12:13], 0, v[138:139]
	s_add_i32 m0, s24, 0xe000
	s_nop 0
	global_load_lds_dwordx4 v[142:143], off
	s_waitcnt lgkmcnt(6)
	s_setprio 1
	s_barrier
	v_mfma_f32_16x16x32_bf16 v[128:131], v[148:151], v[168:171], v[128:131]
	v_mfma_f32_16x16x32_bf16 v[128:131], v[152:155], v[172:175], v[128:131]
	s_waitcnt lgkmcnt(0)
	v_mfma_f32_16x16x32_bf16 v[120:123], v[148:151], v[176:179], v[120:123]
	v_mfma_f32_16x16x32_bf16 v[120:123], v[152:155], v[180:183], v[120:123]
	v_mfma_f32_16x16x32_bf16 v[104:107], v[148:151], v[184:187], v[104:107]
	v_mfma_f32_16x16x32_bf16 v[104:107], v[152:155], v[188:191], v[104:107]
	v_mfma_f32_16x16x32_bf16 v[88:91], v[148:151], v[192:195], v[88:91]
	v_mfma_f32_16x16x32_bf16 v[88:91], v[152:155], v[212:215], v[88:91]
	v_mfma_f32_16x16x32_bf16 v[124:127], v[156:159], v[168:171], v[124:127]
	v_mfma_f32_16x16x32_bf16 v[124:127], v[160:163], v[172:175], v[124:127]
	v_mfma_f32_16x16x32_bf16 v[112:115], v[156:159], v[176:179], v[112:115]
	v_mfma_f32_16x16x32_bf16 v[112:115], v[160:163], v[180:183], v[112:115]
	v_mfma_f32_16x16x32_bf16 v[96:99], v[156:159], v[184:187], v[96:99]
	v_mfma_f32_16x16x32_bf16 v[96:99], v[160:163], v[188:191], v[96:99]
	v_mfma_f32_16x16x32_bf16 v[80:83], v[156:159], v[192:195], v[80:83]
	v_mfma_f32_16x16x32_bf16 v[80:83], v[160:163], v[212:215], v[80:83]
	s_barrier
	s_setprio 0
	s_add_u32 s14, s12, 0xfff80080
	s_addc_u32 s15, s13, -1
	s_cmp_eq_u32 s39, 28
	s_cselect_b32 s17, s1, s15
	s_cselect_b32 s16, s11, s14
	s_cselect_b32 s15, s3, s38
	s_cselect_b32 s14, s36, s37
	s_add_i32 s42, 0, 0x14000
	v_add_u32_e32 v142, s42, v145
	s_add_i32 s40, s40, s19
	ds_read_b128 v[216:219], v142
	ds_read_b128 v[220:223], v142 offset:1024
	ds_read_b128 v[224:227], v142 offset:2048
	ds_read_b128 v[228:231], v142 offset:3072
	v_lshl_add_u64 v[142:143], s[14:15], 0, v[134:135]
	s_mov_b32 m0, s40
	v_lshl_add_u64 v[196:197], s[14:15], 0, v[0:1]
	global_load_lds_dwordx4 v[142:143], off
	s_add_i32 m0, s40, 0x2000
	s_nop 0
	global_load_lds_dwordx4 v[196:197], off
	s_mov_b32 m0, s24
	v_lshl_add_u64 v[232:233], s[16:17], 0, v[136:137]
	s_waitcnt lgkmcnt(2)
	s_setprio 1
	s_barrier
; #define PG8_WAIT_V(n) asm volatile("s_waitcnt vmcnt(" #n ")" ::: "memory")
; #define PG8_WAIT_L(n) asm volatile("s_waitcnt lgkmcnt(" #n ")" ::: "memory")
; #define PG8_BAR __builtin_amdgcn_s_barrier()
; #define PG8_SCHED __builtin_amdgcn_sched_barrier(0)
; template <class Epi, class AddrA, class AddrB>
; __device__ __forceinline__ void gemm_phase(const Sched S, const int lda, const int ldb, const int K, const AddrA addrA,
;                                            const AddrB addrB, const Epi E) {
;     ...
;       PG8_BAR; PG8_WAIT_L(0); PG8_MMA(0, 1, At, B1); PG8_BAR;
;       PG8_LDA(At, 0, 1); PG8_STAGE(PG8_SA(0, 0), a2, voffA);
;       PG8_BAR; PG8_WAIT_L(0); PG8_MMA(1, 0, At, B0); PG8_BAR; PG8_SCHED;
;       PG8_STAGE(PG8_SB(0, 1), b2 + hstepB, voffB);
;       PG8_WAIT_V(6); PG8_BAR; PG8_MMA(1, 1, At, B1); PG8_BAR;
;       PG8_LDB(B0, 1, 0); PG8_SCHED; PG8_LDA(At, 1, 0); PG8_STAGE(PG8_SA(0, 1), a2 + hstepA, voffA);
;       PG8_WAIT_L(8); PG8_BAR; PG8_WAIT_L(0); PG8_MMA(0, 0, At, B0); PG8_BAR; PG8_SCHED;
;       PG8_LDB(B1, 1, 1); PG8_STAGE(PG8_SB(1, 0), b3, voffB);
;       PG8_BAR; PG8_WAIT_L(0); PG8_MMA(0, 1, At, B1); PG8_BAR;
;       PG8_LDA(At, 1, 1); PG8_STAGE(PG8_SA(1, 0), a3, voffA);
;       PG8_BAR; PG8_WAIT_L(0); PG8_MMA(1, 0, At, B0); PG8_BAR; PG8_SCHED;
	v_mfma_f32_16x16x32_bf16 v[116:119], v[216:219], v[168:171], v[116:119]
	v_mfma_f32_16x16x32_bf16 v[116:119], v[220:223], v[172:175], v[116:119]
	s_waitcnt lgkmcnt(0)
	v_mfma_f32_16x16x32_bf16 v[100:103], v[216:219], v[176:179], v[100:103]
	v_mfma_f32_16x16x32_bf16 v[100:103], v[220:223], v[180:183], v[100:103]
	v_mfma_f32_16x16x32_bf16 v[84:87], v[216:219], v[184:187], v[84:87]
	v_mfma_f32_16x16x32_bf16 v[84:87], v[220:223], v[188:191], v[84:87]
	v_mfma_f32_16x16x32_bf16 v[72:75], v[216:219], v[192:195], v[72:75]
	v_mfma_f32_16x16x32_bf16 v[72:75], v[220:223], v[212:215], v[72:75]
	v_mfma_f32_16x16x32_bf16 v[108:111], v[224:227], v[168:171], v[108:111]
	v_mfma_f32_16x16x32_bf16 v[108:111], v[228:231], v[172:175], v[108:111]
	v_mfma_f32_16x16x32_bf16 v[92:95], v[224:227], v[176:179], v[92:95]
	v_mfma_f32_16x16x32_bf16 v[92:95], v[228:231], v[180:183], v[92:95]
	v_mfma_f32_16x16x32_bf16 v[76:79], v[224:227], v[184:187], v[76:79]
	v_mfma_f32_16x16x32_bf16 v[76:79], v[228:231], v[188:191], v[76:79]
	v_mfma_f32_16x16x32_bf16 v[68:71], v[224:227], v[192:195], v[68:71]
	v_mfma_f32_16x16x32_bf16 v[68:71], v[228:231], v[212:215], v[68:71]
	s_barrier
	s_setprio 0
	ds_read_b128 v[168:171], v146 offset:16384
	ds_read_b128 v[172:175], v146 offset:17408
	ds_read_b128 v[176:179], v146 offset:18432
	ds_read_b128 v[180:183], v146 offset:19456
	ds_read_b128 v[184:187], v146 offset:20480
	ds_read_b128 v[188:191], v146 offset:21504
	ds_read_b128 v[192:195], v146 offset:22528
	ds_read_b128 v[212:215], v146 offset:23552
	global_load_lds_dwordx4 v[232:233], off
	v_lshl_add_u64 v[234:235], s[16:17], 0, v[132:133]
	s_mov_b32 m0, s25
	s_nop 0
	global_load_lds_dwordx4 v[234:235], off
	s_waitcnt lgkmcnt(6)
	s_setprio 1
	s_barrier
	v_mfma_f32_16x16x32_bf16 v[64:67], v[148:151], v[168:171], v[64:67]
	v_mfma_f32_16x16x32_bf16 v[64:67], v[152:155], v[172:175], v[64:67]
	s_waitcnt lgkmcnt(0)
	v_mfma_f32_16x16x32_bf16 v[56:59], v[148:151], v[176:179], v[56:59]
	v_mfma_f32_16x16x32_bf16 v[56:59], v[152:155], v[180:183], v[56:59]
	v_mfma_f32_16x16x32_bf16 v[40:43], v[148:151], v[184:187], v[40:43]
	v_mfma_f32_16x16x32_bf16 v[40:43], v[152:155], v[188:191], v[40:43]
	v_mfma_f32_16x16x32_bf16 v[24:27], v[148:151], v[192:195], v[24:27]
	v_mfma_f32_16x16x32_bf16 v[24:27], v[152:155], v[212:215], v[24:27]
	v_mfma_f32_16x16x32_bf16 v[60:63], v[156:159], v[168:171], v[60:63]
	v_mfma_f32_16x16x32_bf16 v[60:63], v[160:163], v[172:175], v[60:63]
	v_mfma_f32_16x16x32_bf16 v[48:51], v[156:159], v[176:179], v[48:51]
	v_mfma_f32_16x16x32_bf16 v[48:51], v[160:163], v[180:183], v[48:51]
	v_mfma_f32_16x16x32_bf16 v[32:35], v[156:159], v[184:187], v[32:35]
	v_mfma_f32_16x16x32_bf16 v[32:35], v[160:163], v[188:191], v[32:35]
	v_mfma_f32_16x16x32_bf16 v[16:19], v[156:159], v[192:195], v[16:19]
	v_mfma_f32_16x16x32_bf16 v[16:19], v[160:163], v[212:215], v[16:19]
	s_barrier
	s_setprio 0
	s_add_u32 s40, s14, 0x80000
	s_addc_u32 s41, s15, 0
	s_add_i32 s42, s42, s19
	v_lshl_add_u64 v[148:149], s[40:41], 0, v[134:135]
	s_mov_b32 m0, s42
	s_nop 0
	global_load_lds_dwordx4 v[148:149], off
	v_lshl_add_u64 v[148:149], s[40:41], 0, v[0:1]
	s_add_i32 m0, s42, 0x2000
	s_nop 0
	global_load_lds_dwordx4 v[148:149], off
	s_add_i32 s40, 0, 0x18000
	v_add_u32_e32 v147, s40, v145
	s_waitcnt vmcnt(6)
	s_setprio 1
	s_barrier
	v_mfma_f32_16x16x32_bf16 v[52:55], v[216:219], v[168:171], v[52:55]
	v_mfma_f32_16x16x32_bf16 v[52:55], v[220:223], v[172:175], v[52:55]
	v_mfma_f32_16x16x32_bf16 v[36:39], v[216:219], v[176:179], v[36:39]
	v_mfma_f32_16x16x32_bf16 v[36:39], v[220:223], v[180:183], v[36:39]
	v_mfma_f32_16x16x32_bf16 v[20:23], v[216:219], v[184:187], v[20:23]
	v_mfma_f32_16x16x32_bf16 v[20:23], v[220:223], v[188:191], v[20:23]
	v_mfma_f32_16x16x32_bf16 v[8:11], v[216:219], v[192:195], v[8:11]
	v_mfma_f32_16x16x32_bf16 v[8:11], v[220:223], v[212:215], v[8:11]
	v_mfma_f32_16x16x32_bf16 v[44:47], v[224:227], v[168:171], v[44:47]
	v_mfma_f32_16x16x32_bf16 v[44:47], v[228:231], v[172:175], v[44:47]
	v_mfma_f32_16x16x32_bf16 v[28:31], v[224:227], v[176:179], v[28:31]
	v_mfma_f32_16x16x32_bf16 v[28:31], v[228:231], v[180:183], v[28:31]
	v_mfma_f32_16x16x32_bf16 v[12:15], v[224:227], v[184:187], v[12:15]
	v_mfma_f32_16x16x32_bf16 v[12:15], v[228:231], v[188:191], v[12:15]
	v_mfma_f32_16x16x32_bf16 v[4:7], v[224:227], v[192:195], v[4:7]
	v_mfma_f32_16x16x32_bf16 v[4:7], v[228:231], v[212:215], v[4:7]
	s_barrier
	s_setprio 0
	ds_read_b128 v[148:151], v147
	ds_read_b128 v[152:155], v147 offset:1024
	ds_read_b128 v[156:159], v147 offset:2048
	ds_read_b128 v[160:163], v147 offset:3072
	s_add_u32 s16, s16, 0x80000
	s_addc_u32 s17, s17, 0
	s_mov_b32 m0, s26
	v_lshl_add_u64 v[216:217], s[16:17], 0, v[136:137]
	ds_read_b128 v[168:171], v146 offset:32768
	ds_read_b128 v[172:175], v146 offset:33792
	ds_read_b128 v[176:179], v146 offset:34816
	ds_read_b128 v[180:183], v146 offset:35840
	ds_read_b128 v[184:187], v146 offset:36864
	ds_read_b128 v[188:191], v146 offset:37888
	ds_read_b128 v[192:195], v146 offset:38912
	ds_read_b128 v[212:215], v146 offset:39936
	global_load_lds_dwordx4 v[216:217], off
	v_lshl_add_u64 v[216:217], s[16:17], 0, v[132:133]
	s_mov_b32 m0, s27
	s_nop 0
	global_load_lds_dwordx4 v[216:217], off
	s_waitcnt lgkmcnt(6)
	s_setprio 1
	s_barrier
; #define PG8_WAIT_V(n) asm volatile("s_waitcnt vmcnt(" #n ")" ::: "memory")
; #define PG8_WAIT_L(n) asm volatile("s_waitcnt lgkmcnt(" #n ")" ::: "memory")
; #define PG8_BAR __builtin_amdgcn_s_barrier()
; #define PG8_SCHED __builtin_amdgcn_sched_barrier(0)
; template <class Epi, class AddrA, class AddrB>
; __device__ __forceinline__ void gemm_phase(const Sched S, const int lda, const int ldb, const int K, const AddrA addrA,
;                                            const AddrB addrB, const Epi E) {
;     ...
;       PG8_WAIT_L(8); PG8_BAR; PG8_WAIT_L(0); PG8_MMA(0, 0, At, B0); PG8_BAR; PG8_SCHED;
;       PG8_LDB(B1, 1, 1); PG8_STAGE(PG8_SB(1, 0), b3, voffB);
;       PG8_BAR; PG8_WAIT_L(0); PG8_MMA(0, 1, At, B1); PG8_BAR;
;       PG8_LDA(At, 1, 1); PG8_STAGE(PG8_SA(1, 0), a3, voffA);
;       PG8_BAR; PG8_WAIT_L(0); PG8_MMA(1, 0, At, B0); PG8_BAR; PG8_SCHED;
;       PG8_STAGE(PG8_SB(1, 1), b3 + hstepB, voffB);
;       PG8_WAIT_V(6); PG8_BAR; PG8_MMA(1, 1, At, B1); PG8_BAR;
	v_mfma_f32_16x16x32_bf16 v[128:131], v[148:151], v[168:171], v[128:131]
	v_mfma_f32_16x16x32_bf16 v[128:131], v[152:155], v[172:175], v[128:131]
	s_waitcnt lgkmcnt(0)
	v_mfma_f32_16x16x32_bf16 v[120:123], v[148:151], v[176:179], v[120:123]
	v_mfma_f32_16x16x32_bf16 v[120:123], v[152:155], v[180:183], v[120:123]
	v_mfma_f32_16x16x32_bf16 v[104:107], v[148:151], v[184:187], v[104:107]
	v_mfma_f32_16x16x32_bf16 v[104:107], v[152:155], v[188:191], v[104:107]
	v_mfma_f32_16x16x32_bf16 v[88:91], v[148:151], v[192:195], v[88:91]
	v_mfma_f32_16x16x32_bf16 v[88:91], v[152:155], v[212:215], v[88:91]
	v_mfma_f32_16x16x32_bf16 v[124:127], v[156:159], v[168:171], v[124:127]
	v_mfma_f32_16x16x32_bf16 v[124:127], v[160:163], v[172:175], v[124:127]
	v_mfma_f32_16x16x32_bf16 v[112:115], v[156:159], v[176:179], v[112:115]
	v_mfma_f32_16x16x32_bf16 v[112:115], v[160:163], v[180:183], v[112:115]
	v_mfma_f32_16x16x32_bf16 v[96:99], v[156:159], v[184:187], v[96:99]
	v_mfma_f32_16x16x32_bf16 v[96:99], v[160:163], v[188:191], v[96:99]
	v_mfma_f32_16x16x32_bf16 v[80:83], v[156:159], v[192:195], v[80:83]
	v_mfma_f32_16x16x32_bf16 v[80:83], v[160:163], v[212:215], v[80:83]
	s_barrier
	s_setprio 0
	s_add_i32 s16, 0, 0x1c000
	s_add_i32 s17, s40, s19
	v_add_u32_e32 v147, s16, v145
	v_lshl_add_u64 v[142:143], v[142:143], 0, s[52:53]
	s_mov_b32 m0, s17
	ds_read_b128 v[216:219], v147
	ds_read_b128 v[220:223], v147 offset:1024
	ds_read_b128 v[224:227], v147 offset:2048
	ds_read_b128 v[228:231], v147 offset:3072
	global_load_lds_dwordx4 v[142:143], off
	v_lshl_add_u64 v[142:143], v[196:197], 0, s[52:53]
	s_add_i32 m0, s17, 0x2000
	s_nop 0
	global_load_lds_dwordx4 v[142:143], off
	s_mov_b32 m0, s30
	v_lshl_add_u64 v[142:143], v[232:233], 0, s[52:53]
	s_waitcnt lgkmcnt(2)
	s_setprio 1
	s_barrier
	v_mfma_f32_16x16x32_bf16 v[116:119], v[216:219], v[168:171], v[116:119]
	v_mfma_f32_16x16x32_bf16 v[116:119], v[220:223], v[172:175], v[116:119]
	s_waitcnt lgkmcnt(0)
	v_mfma_f32_16x16x32_bf16 v[100:103], v[216:219], v[176:179], v[100:103]
	v_mfma_f32_16x16x32_bf16 v[100:103], v[220:223], v[180:183], v[100:103]
	v_mfma_f32_16x16x32_bf16 v[84:87], v[216:219], v[184:187], v[84:87]
	v_mfma_f32_16x16x32_bf16 v[84:87], v[220:223], v[188:191], v[84:87]
	v_mfma_f32_16x16x32_bf16 v[72:75], v[216:219], v[192:195], v[72:75]
	v_mfma_f32_16x16x32_bf16 v[72:75], v[220:223], v[212:215], v[72:75]
	v_mfma_f32_16x16x32_bf16 v[108:111], v[224:227], v[168:171], v[108:111]
	v_mfma_f32_16x16x32_bf16 v[108:111], v[228:231], v[172:175], v[108:111]
	v_mfma_f32_16x16x32_bf16 v[92:95], v[224:227], v[176:179], v[92:95]
	v_mfma_f32_16x16x32_bf16 v[92:95], v[228:231], v[180:183], v[92:95]
	v_mfma_f32_16x16x32_bf16 v[76:79], v[224:227], v[184:187], v[76:79]
	v_mfma_f32_16x16x32_bf16 v[76:79], v[228:231], v[188:191], v[76:79]
	v_mfma_f32_16x16x32_bf16 v[68:71], v[224:227], v[192:195], v[68:71]
	v_mfma_f32_16x16x32_bf16 v[68:71], v[228:231], v[212:215], v[68:71]
	s_barrier
	s_setprio 0
	ds_read_b128 v[168:171], v146 offset:49152
	ds_read_b128 v[172:175], v146 offset:50176
	ds_read_b128 v[176:179], v146 offset:51200
	ds_read_b128 v[180:183], v146 offset:52224
	ds_read_b128 v[184:187], v146 offset:53248
	ds_read_b128 v[188:191], v146 offset:54272
	ds_read_b128 v[192:195], v146 offset:55296
	ds_read_b128 v[212:215], v146 offset:56320
	global_load_lds_dwordx4 v[142:143], off
	v_lshl_add_u64 v[142:143], v[234:235], 0, s[52:53]
	s_mov_b32 m0, s31
	s_nop 0
	global_load_lds_dwordx4 v[142:143], off
	s_waitcnt lgkmcnt(6)
	s_setprio 1
	s_barrier
	v_mfma_f32_16x16x32_bf16 v[64:67], v[148:151], v[168:171], v[64:67]
	v_mfma_f32_16x16x32_bf16 v[64:67], v[152:155], v[172:175], v[64:67]
	s_waitcnt lgkmcnt(0)
	v_mfma_f32_16x16x32_bf16 v[56:59], v[148:151], v[176:179], v[56:59]
	v_mfma_f32_16x16x32_bf16 v[56:59], v[152:155], v[180:183], v[56:59]
	v_mfma_f32_16x16x32_bf16 v[40:43], v[148:151], v[184:187], v[40:43]
	v_mfma_f32_16x16x32_bf16 v[40:43], v[152:155], v[188:191], v[40:43]
	v_mfma_f32_16x16x32_bf16 v[24:27], v[148:151], v[192:195], v[24:27]
	v_mfma_f32_16x16x32_bf16 v[24:27], v[152:155], v[212:215], v[24:27]
	v_mfma_f32_16x16x32_bf16 v[60:63], v[156:159], v[168:171], v[60:63]
	v_mfma_f32_16x16x32_bf16 v[60:63], v[160:163], v[172:175], v[60:63]
	v_mfma_f32_16x16x32_bf16 v[48:51], v[156:159], v[176:179], v[48:51]
	v_mfma_f32_16x16x32_bf16 v[48:51], v[160:163], v[180:183], v[48:51]
	v_mfma_f32_16x16x32_bf16 v[32:35], v[156:159], v[184:187], v[32:35]
	v_mfma_f32_16x16x32_bf16 v[32:35], v[160:163], v[188:191], v[32:35]
	v_mfma_f32_16x16x32_bf16 v[16:19], v[156:159], v[192:195], v[16:19]
	v_mfma_f32_16x16x32_bf16 v[16:19], v[160:163], v[212:215], v[16:19]
	s_barrier
	s_setprio 0
	s_add_u32 s14, s14, 0x80080
	s_addc_u32 s15, s15, 0
	s_add_i32 s16, s16, s19
	v_lshl_add_u64 v[142:143], s[14:15], 0, v[134:135]
	s_mov_b32 m0, s16
	s_nop 0
	global_load_lds_dwordx4 v[142:143], off
	v_lshl_add_u64 v[142:143], s[14:15], 0, v[0:1]
	s_add_i32 m0, s16, 0x2000
	s_nop 0
	global_load_lds_dwordx4 v[142:143], off
	s_add_i32 s39, s39, 2
	s_add_u32 s37, s37, 0x100
	s_addc_u32 s38, s38, 0
	s_add_u32 s12, s12, 0x100
	s_addc_u32 s13, s13, 0
	s_waitcnt vmcnt(6)
	s_setprio 1
	s_barrier
;   __device__ __forceinline__ void operator()(EPI_ARGS) const {
;     bf16_t* base = proj + ((size_t)u.pn * MTOK + (size_t)(u.pm * 256 + wr * 64 + fr)) * PLD + wc * 32 + 8 * fq;
; #pragma unroll
;     for (int ai = 0; ai < 2; ++ai)
; #pragma unroll
;       for (int m = 0; m < 4; ++m) {
;         bf16_t* rowp = base + (size_t)(ai * HALF + m * 16) * PLD;
; #pragma unroll
;         for (int bj = 0; bj < 2; ++bj) {
;           const f32x4 v0 = acc[ai][bj][m][0], v1 = acc[ai][bj][m][1];
;           u32x4 o;
;           o.x = pack2(v0[0], v0[1]); o.y = pack2(v0[2], v0[3]); o.z = pack2(v1[0], v1[1]); o.w = pack2(v1[2], v1[3]);
;           *(u32x4*)(rowp + bj * HALF) = o;
;         }
;       }
	v_mfma_f32_16x16x32_bf16 v[52:55], v[216:219], v[168:171], v[52:55]
	v_mfma_f32_16x16x32_bf16 v[52:55], v[220:223], v[172:175], v[52:55]
	v_mfma_f32_16x16x32_bf16 v[36:39], v[216:219], v[176:179], v[36:39]
	v_mfma_f32_16x16x32_bf16 v[36:39], v[220:223], v[180:183], v[36:39]
	v_mfma_f32_16x16x32_bf16 v[20:23], v[216:219], v[184:187], v[20:23]
	v_mfma_f32_16x16x32_bf16 v[20:23], v[220:223], v[188:191], v[20:23]
	v_mfma_f32_16x16x32_bf16 v[8:11], v[216:219], v[192:195], v[8:11]
	v_mfma_f32_16x16x32_bf16 v[8:11], v[220:223], v[212:215], v[8:11]
	v_mfma_f32_16x16x32_bf16 v[44:47], v[224:227], v[168:171], v[44:47]
	v_mfma_f32_16x16x32_bf16 v[44:47], v[228:231], v[172:175], v[44:47]
	v_mfma_f32_16x16x32_bf16 v[28:31], v[224:227], v[176:179], v[28:31]
	v_mfma_f32_16x16x32_bf16 v[28:31], v[228:231], v[180:183], v[28:31]
	v_mfma_f32_16x16x32_bf16 v[12:15], v[224:227], v[184:187], v[12:15]
	v_mfma_f32_16x16x32_bf16 v[12:15], v[228:231], v[188:191], v[12:15]
	v_mfma_f32_16x16x32_bf16 v[4:7], v[224:227], v[192:195], v[4:7]
	v_mfma_f32_16x16x32_bf16 v[4:7], v[228:231], v[212:215], v[4:7]
	s_barrier
	s_setprio 0
	s_cmp_gt_u32 s39, 29
	s_cbranch_scc0 .LBB0_109
	s_ashr_i32 s11, s10, 31
	v_lshl_add_u32 v142, s35, 8, v144
	s_lshl_b64 s[10:11], s[10:11], 23
	v_ashrrev_i32_e32 v143, 31, v142
	s_add_u32 s10, s28, s10
	s_addc_u32 s11, s29, s11
	v_lshlrev_b64 v[142:143], 9, v[142:143]
	v_lshl_add_u64 v[142:143], s[10:11], 0, v[142:143]
	v_lshl_add_u64 v[142:143], v[142:143], 0, s[72:73]
	v_lshl_add_u64 v[142:143], v[142:143], 0, v[2:3]
	v_cvt_pk_bf16_f32 v116, v116, v117
	v_cvt_pk_bf16_f32 v117, v118, v119
	v_cvt_pk_bf16_f32 v119, v110, v111
	v_cvt_pk_bf16_f32 v110, v112, v113
	v_add_co_u32_e32 v112, vcc, s96, v142
	s_movk_i32 s1, 0x4000
	s_nop 0
	v_addc_co_u32_e32 v113, vcc, 0, v143, vcc
	v_cvt_pk_bf16_f32 v100, v100, v101
	v_cvt_pk_bf16_f32 v101, v102, v103
	v_cvt_pk_bf16_f32 v103, v94, v95
	v_cvt_pk_bf16_f32 v94, v96, v97
	v_add_co_u32_e32 v96, vcc, s1, v142
	s_movk_i32 s1, 0x6000
	s_nop 0
	v_addc_co_u32_e32 v97, vcc, 0, v143, vcc
	v_cvt_pk_bf16_f32 v84, v84, v85
	v_cvt_pk_bf16_f32 v85, v86, v87
	v_cvt_pk_bf16_f32 v87, v78, v79
	v_cvt_pk_bf16_f32 v78, v80, v81
	v_add_co_u32_e32 v80, vcc, s1, v142
	v_cvt_pk_bf16_f32 v64, v64, v65
	v_cvt_pk_bf16_f32 v65, v66, v67
	v_cvt_pk_bf16_f32 v66, v60, v61
	s_mov_b32 s1, 0x12000
	s_nop 0
	v_addc_co_u32_e32 v81, vcc, 0, v143, vcc
	v_add_co_u32_e32 v60, vcc, s67, v142
	v_cvt_pk_bf16_f32 v52, v52, v53
	v_cvt_pk_bf16_f32 v53, v54, v55
	v_cvt_pk_bf16_f32 v55, v46, v47
	v_cvt_pk_bf16_f32 v46, v48, v49
	s_nop 1
	v_addc_co_u32_e32 v61, vcc, 0, v143, vcc
	v_add_co_u32_e32 v48, vcc, s1, v142
	s_mov_b32 s1, 0x14000
	s_nop 0
	v_addc_co_u32_e32 v49, vcc, 0, v143, vcc
	v_cvt_pk_bf16_f32 v36, v36, v37
	v_cvt_pk_bf16_f32 v37, v38, v39
	v_cvt_pk_bf16_f32 v39, v30, v31
	v_cvt_pk_bf16_f32 v30, v32, v33
	v_add_co_u32_e32 v32, vcc, s1, v142
	s_mov_b32 s1, 0x16000
	s_nop 0
	v_addc_co_u32_e32 v33, vcc, 0, v143, vcc
	v_cvt_pk_bf16_f32 v20, v20, v21
	v_cvt_pk_bf16_f32 v21, v22, v23
	v_cvt_pk_bf16_f32 v23, v14, v15
	v_cvt_pk_bf16_f32 v14, v16, v17
	v_add_co_u32_e32 v16, vcc, s1, v142
	s_mov_b32 s10, s2
	s_nop 0
	v_addc_co_u32_e32 v17, vcc, 0, v143, vcc
	s_and_b64 vcc, exec, s[4:5]
	s_mov_b32 s35, s0
	s_mov_b64 s[12:13], s[8:9]
	s_mov_b64 s[14:15], s[6:7]
	v_cvt_pk_bf16_f32 v128, v128, v129
	v_cvt_pk_bf16_f32 v129, v130, v131
	v_cvt_pk_bf16_f32 v130, v124, v125
	v_cvt_pk_bf16_f32 v131, v126, v127
	flat_store_dwordx4 v[142:143], v[128:131]
	v_cvt_pk_bf16_f32 v118, v108, v109
	flat_store_dwordx4 v[142:143], v[116:119] offset:256
	v_cvt_pk_bf16_f32 v108, v120, v121
	v_cvt_pk_bf16_f32 v109, v122, v123
	v_cvt_pk_bf16_f32 v111, v114, v115
	flat_store_dwordx4 v[112:113], v[108:111]
	v_cvt_pk_bf16_f32 v102, v92, v93
	flat_store_dwordx4 v[112:113], v[100:103] offset:256
	v_cvt_pk_bf16_f32 v92, v104, v105
	v_cvt_pk_bf16_f32 v93, v106, v107
	v_cvt_pk_bf16_f32 v95, v98, v99
	flat_store_dwordx4 v[96:97], v[92:95]
	v_cvt_pk_bf16_f32 v86, v76, v77
	flat_store_dwordx4 v[96:97], v[84:87] offset:256
	v_cvt_pk_bf16_f32 v76, v88, v89
	v_cvt_pk_bf16_f32 v77, v90, v91
	v_cvt_pk_bf16_f32 v79, v82, v83
	flat_store_dwordx4 v[80:81], v[76:79]
	v_cvt_pk_bf16_f32 v72, v72, v73
	v_cvt_pk_bf16_f32 v73, v74, v75
	v_cvt_pk_bf16_f32 v74, v68, v69
	v_cvt_pk_bf16_f32 v75, v70, v71
	flat_store_dwordx4 v[80:81], v[72:75] offset:256
	v_cvt_pk_bf16_f32 v67, v62, v63
	flat_store_dwordx4 v[60:61], v[64:67]
	v_cvt_pk_bf16_f32 v54, v44, v45
	flat_store_dwordx4 v[60:61], v[52:55] offset:256
	v_cvt_pk_bf16_f32 v44, v56, v57
	v_cvt_pk_bf16_f32 v45, v58, v59
	v_cvt_pk_bf16_f32 v47, v50, v51
	flat_store_dwordx4 v[48:49], v[44:47]
	v_cvt_pk_bf16_f32 v38, v28, v29
	flat_store_dwordx4 v[48:49], v[36:39] offset:256
	v_cvt_pk_bf16_f32 v28, v40, v41
	v_cvt_pk_bf16_f32 v29, v42, v43
	v_cvt_pk_bf16_f32 v31, v34, v35
	flat_store_dwordx4 v[32:33], v[28:31]
	v_cvt_pk_bf16_f32 v22, v12, v13
	flat_store_dwordx4 v[32:33], v[20:23] offset:256
	v_cvt_pk_bf16_f32 v12, v24, v25
	v_cvt_pk_bf16_f32 v13, v26, v27
	v_cvt_pk_bf16_f32 v15, v18, v19
	flat_store_dwordx4 v[16:17], v[12:15]
	v_cvt_pk_bf16_f32 v8, v8, v9
	v_cvt_pk_bf16_f32 v9, v10, v11
	v_cvt_pk_bf16_f32 v10, v4, v5
	v_cvt_pk_bf16_f32 v11, v6, v7
	flat_store_dwordx4 v[16:17], v[8:11] offset:256
	s_cbranch_vccz .LBB0_106
	s_waitcnt vmcnt(0)
	s_cmpk_gt_u32 s18, 0xff
	s_cbranch_scc1 .LBB0_113
	s_barrier

; #define PG8_WAIT_V(n) asm volatile("s_waitcnt vmcnt(" #n ")" ::: "memory")
; #define PG8_WAIT_L(n) asm volatile("s_waitcnt lgkmcnt(" #n ")" ::: "memory")
; #define PG8_BAR __builtin_amdgcn_s_barrier()
; #define PG8_SCHED __builtin_amdgcn_sched_barrier(0)
; template <class Epi, class AddrA, class AddrB>
; __device__ __forceinline__ void gemm_phase(const Sched S, const int lda, const int ldb, const int K, const AddrA addrA,
;                                            const AddrB addrB, const Epi E) {
;     ...
;     const bool has_next = S.next(ui + 1, nxt);
;     const char* nA = has_next ? addrA(nxt) : cA;
;     const char* nB = has_next ? addrB(nxt) : cB;
;     for (int t = 0; t < nt; t += 2) {
;       const bool last = (t == nt - 2);
;       const char* a1 = cA + (size_t)(t + 1) * kstep;
;       const char* a2 = last ? nA : cA + (size_t)(t + 2) * kstep;
;       const char* b2 = last ? nB : cB + (size_t)(t + 2) * kstep;
;       const char* a3 = a2 + kstep;
;       const char* b3 = b2 + kstep;
;       PG8_LDB(B0, 0, 0); PG8_SCHED; PG8_LDA(At, 0, 0); PG8_STAGE(PG8_SA(1, 1), a1 + hstepA, voffA);
;       PG8_WAIT_L(8); PG8_BAR; PG8_WAIT_L(0); PG8_MMA(0, 0, At, B0); PG8_BAR; PG8_SCHED;
;       PG8_LDB(B1, 0, 1); PG8_STAGE(PG8_SB(0, 0), b2, voffB);
;       PG8_BAR; PG8_WAIT_L(0); PG8_MMA(0, 1, At, B1); PG8_BAR;
;       PG8_LDA(At, 0, 1); PG8_STAGE(PG8_SA(0, 0), a2, voffA);
;       PG8_BAR; PG8_WAIT_L(0); PG8_MMA(1, 0, At, B0); PG8_BAR; PG8_SCHED;
;       PG8_STAGE(PG8_SB(0, 1), b2 + hstepB, voffB);
;       PG8_WAIT_V(6); PG8_BAR; PG8_MMA(1, 1, At, B1); PG8_BAR;
.LBB0_484:
	s_ashr_i32 s15, s14, 31
	s_lshl_b64 s[20:21], s[14:15], 20
	s_add_u32 s3, s25, s20
	s_addc_u32 s15, s26, s21
	s_lshl_b32 s17, s16, 8
	s_and_b32 s20, s17, 0xfffffe00
	s_ashr_i32 s21, s20, 31
	s_lshl_b64 s[20:21], s[20:21], 1
	s_add_u32 s20, s3, s20
	s_addc_u32 s21, s15, s21
	s_and_b64 s[22:23], s[10:11], exec
	s_cselect_b32 s3, s21, s7
	s_cselect_b32 s15, s20, s6
	s_ashr_i32 s17, s16, 31
	s_lshl_b64 s[22:23], s[16:17], 18
	s_add_u32 s22, s27, s22
	s_addc_u32 s23, s28, s23
	s_and_b64 s[10:11], s[10:11], exec
	s_cselect_b32 s17, s23, s5
	s_cselect_b32 s40, s22, s4
	s_add_u32 s41, s4, 0x100
	s_addc_u32 s42, s5, 0
	s_add_u32 s4, s6, 0x80080
	s_addc_u32 s5, s7, 0
	s_mov_b32 s43, -2
	s_add_i32 s44, 0, 0x10000
	v_add_u32_e32 v2, s44, v167
	ds_read_b128 v[92:95], v2
	ds_read_b128 v[100:103], v2 offset:1024
	ds_read_b128 v[132:135], v2 offset:2048
	ds_read_b128 v[144:147], v2 offset:3072
	v_lshl_add_u64 v[196:197], s[4:5], 0, v[172:173]
	s_add_i32 m0, s30, 0xc000
	ds_read_b128 v[148:151], v169
	ds_read_b128 v[152:155], v169 offset:1024
	ds_read_b128 v[176:179], v169 offset:2048
	ds_read_b128 v[180:183], v169 offset:3072
	ds_read_b128 v[184:187], v169 offset:4096
	ds_read_b128 v[188:191], v169 offset:5120
	ds_read_b128 v[192:195], v169 offset:6144
	ds_read_b128 v[212:215], v169 offset:7168
	global_load_lds_dwordx4 v[196:197], off
	v_lshl_add_u64 v[196:197], s[4:5], 0, v[170:171]
	s_add_i32 m0, s30, 0xe000
	s_nop 0
	global_load_lds_dwordx4 v[196:197], off
	s_waitcnt lgkmcnt(6)
	s_setprio 1
	s_barrier
	v_mfma_f32_16x16x32_bf16 v[140:143], v[92:95], v[148:151], 0
	v_mfma_f32_16x16x32_bf16 v[140:143], v[100:103], v[152:155], v[140:143]
	s_waitcnt lgkmcnt(0)
	v_mfma_f32_16x16x32_bf16 v[128:131], v[92:95], v[176:179], 0
	v_mfma_f32_16x16x32_bf16 v[128:131], v[100:103], v[180:183], v[128:131]
	v_mfma_f32_16x16x32_bf16 v[120:123], v[92:95], v[184:187], 0
	v_mfma_f32_16x16x32_bf16 v[120:123], v[100:103], v[188:191], v[120:123]
	v_mfma_f32_16x16x32_bf16 v[112:115], v[92:95], v[192:195], 0
	v_mfma_f32_16x16x32_bf16 v[112:115], v[100:103], v[212:215], v[112:115]
	v_mfma_f32_16x16x32_bf16 v[136:139], v[132:135], v[148:151], 0
	v_mfma_f32_16x16x32_bf16 v[136:139], v[144:147], v[152:155], v[136:139]
	v_mfma_f32_16x16x32_bf16 v[124:127], v[132:135], v[176:179], 0
	v_mfma_f32_16x16x32_bf16 v[124:127], v[144:147], v[180:183], v[124:127]
	v_mfma_f32_16x16x32_bf16 v[116:119], v[132:135], v[184:187], 0
	v_mfma_f32_16x16x32_bf16 v[116:119], v[144:147], v[188:191], v[116:119]
	v_mfma_f32_16x16x32_bf16 v[108:111], v[132:135], v[192:195], 0
	v_mfma_f32_16x16x32_bf16 v[108:111], v[144:147], v[212:215], v[108:111]
	s_barrier
	s_setprio 0
	s_add_u32 s6, s4, 0xfff80080
	s_addc_u32 s7, s5, -1
	s_cmp_eq_u32 s43, 4
	s_cselect_b32 s11, s3, s7
	s_cselect_b32 s10, s15, s6
	s_cselect_b32 s7, s17, s42
	s_cselect_b32 s6, s40, s41
	s_add_i32 s46, 0, 0x14000
	s_add_i32 s44, s44, s29
	v_add_u32_e32 v2, s46, v167
	v_lshl_add_u64 v[196:197], s[6:7], 0, v[158:159]
	s_mov_b32 m0, s44
	ds_read_b128 v[216:219], v2
	ds_read_b128 v[220:223], v2 offset:1024
	ds_read_b128 v[224:227], v2 offset:2048
	ds_read_b128 v[228:231], v2 offset:3072
	global_load_lds_dwordx4 v[196:197], off
	v_lshl_add_u64 v[232:233], s[6:7], 0, v[0:1]
	s_add_i32 m0, s44, 0x2000
	s_nop 0
	global_load_lds_dwordx4 v[232:233], off
	s_mov_b32 m0, s30
	v_lshl_add_u64 v[234:235], s[10:11], 0, v[160:161]
	s_waitcnt lgkmcnt(2)
	s_setprio 1
	s_barrier
	v_mfma_f32_16x16x32_bf16 v[64:67], v[216:219], v[148:151], 0
	v_mfma_f32_16x16x32_bf16 v[64:67], v[220:223], v[152:155], v[64:67]
	s_waitcnt lgkmcnt(0)
	v_mfma_f32_16x16x32_bf16 v[56:59], v[216:219], v[176:179], 0
	v_mfma_f32_16x16x32_bf16 v[56:59], v[220:223], v[180:183], v[56:59]
	v_mfma_f32_16x16x32_bf16 v[48:51], v[216:219], v[184:187], 0
	v_mfma_f32_16x16x32_bf16 v[48:51], v[220:223], v[188:191], v[48:51]
	v_mfma_f32_16x16x32_bf16 v[40:43], v[216:219], v[192:195], 0
	v_mfma_f32_16x16x32_bf16 v[40:43], v[220:223], v[212:215], v[40:43]
	v_mfma_f32_16x16x32_bf16 v[60:63], v[224:227], v[148:151], 0
	v_mfma_f32_16x16x32_bf16 v[60:63], v[228:231], v[152:155], v[60:63]
	v_mfma_f32_16x16x32_bf16 v[52:55], v[224:227], v[176:179], 0
	v_mfma_f32_16x16x32_bf16 v[52:55], v[228:231], v[180:183], v[52:55]
	v_mfma_f32_16x16x32_bf16 v[44:47], v[224:227], v[184:187], 0
	v_mfma_f32_16x16x32_bf16 v[44:47], v[228:231], v[188:191], v[44:47]
	v_mfma_f32_16x16x32_bf16 v[36:39], v[224:227], v[192:195], 0
	v_mfma_f32_16x16x32_bf16 v[36:39], v[228:231], v[212:215], v[36:39]
	s_barrier
	s_setprio 0
	ds_read_b128 v[148:151], v169 offset:16384
	ds_read_b128 v[152:155], v169 offset:17408
	ds_read_b128 v[176:179], v169 offset:18432
	ds_read_b128 v[180:183], v169 offset:19456
	ds_read_b128 v[184:187], v169 offset:20480
	ds_read_b128 v[188:191], v169 offset:21504
	ds_read_b128 v[192:195], v169 offset:22528
	ds_read_b128 v[212:215], v169 offset:23552
	global_load_lds_dwordx4 v[234:235], off
	v_lshl_add_u64 v[236:237], s[10:11], 0, v[156:157]
	s_mov_b32 m0, s31
	s_nop 0
	global_load_lds_dwordx4 v[236:237], off
	s_waitcnt lgkmcnt(6)
	s_setprio 1
	s_barrier
	v_mfma_f32_16x16x32_bf16 v[104:107], v[92:95], v[148:151], 0
	v_mfma_f32_16x16x32_bf16 v[104:107], v[100:103], v[152:155], v[104:107]
	s_waitcnt lgkmcnt(0)
	v_mfma_f32_16x16x32_bf16 v[88:91], v[92:95], v[176:179], 0
	v_mfma_f32_16x16x32_bf16 v[88:91], v[100:103], v[180:183], v[88:91]
	v_mfma_f32_16x16x32_bf16 v[80:83], v[92:95], v[184:187], 0
	v_mfma_f32_16x16x32_bf16 v[80:83], v[100:103], v[188:191], v[80:83]
	v_mfma_f32_16x16x32_bf16 v[72:75], v[92:95], v[192:195], 0
	v_mfma_f32_16x16x32_bf16 v[72:75], v[100:103], v[212:215], v[72:75]
	v_mfma_f32_16x16x32_bf16 v[96:99], v[132:135], v[148:151], 0
	v_mfma_f32_16x16x32_bf16 v[96:99], v[144:147], v[152:155], v[96:99]
	v_mfma_f32_16x16x32_bf16 v[84:87], v[132:135], v[176:179], 0
	v_mfma_f32_16x16x32_bf16 v[84:87], v[144:147], v[180:183], v[84:87]
	v_mfma_f32_16x16x32_bf16 v[76:79], v[132:135], v[184:187], 0
	v_mfma_f32_16x16x32_bf16 v[76:79], v[144:147], v[188:191], v[76:79]
	v_mfma_f32_16x16x32_bf16 v[68:71], v[132:135], v[192:195], 0
	v_mfma_f32_16x16x32_bf16 v[68:71], v[144:147], v[212:215], v[68:71]
	s_barrier
; #define PG8_WAIT_V(n) asm volatile("s_waitcnt vmcnt(" #n ")" ::: "memory")
; #define PG8_WAIT_L(n) asm volatile("s_waitcnt lgkmcnt(" #n ")" ::: "memory")
; #define PG8_BAR __builtin_amdgcn_s_barrier()
; #define PG8_SCHED __builtin_amdgcn_sched_barrier(0)
; template <class Epi, class AddrA, class AddrB>
; __device__ __forceinline__ void gemm_phase(const Sched S, const int lda, const int ldb, const int K, const AddrA addrA,
;                                            const AddrB addrB, const Epi E) {
;     ...
;       PG8_BAR; PG8_WAIT_L(0); PG8_MMA(1, 0, At, B0); PG8_BAR; PG8_SCHED;
;       PG8_STAGE(PG8_SB(0, 1), b2 + hstepB, voffB);
;       PG8_WAIT_V(6); PG8_BAR; PG8_MMA(1, 1, At, B1); PG8_BAR;
;       PG8_LDB(B0, 1, 0); PG8_SCHED; PG8_LDA(At, 1, 0); PG8_STAGE(PG8_SA(0, 1), a2 + hstepA, voffA);
;       PG8_WAIT_L(8); PG8_BAR; PG8_WAIT_L(0); PG8_MMA(0, 0, At, B0); PG8_BAR; PG8_SCHED;
;       PG8_LDB(B1, 1, 1); PG8_STAGE(PG8_SB(1, 0), b3, voffB);
;       PG8_BAR; PG8_WAIT_L(0); PG8_MMA(0, 1, At, B1); PG8_BAR;
;       PG8_LDA(At, 1, 1); PG8_STAGE(PG8_SA(1, 0), a3, voffA);
;       PG8_BAR; PG8_WAIT_L(0); PG8_MMA(1, 0, At, B0); PG8_BAR; PG8_SCHED;
	s_setprio 0
	s_add_u32 s44, s6, 0x20000
	s_addc_u32 s45, s7, 0
	s_add_i32 s46, s46, s29
	v_lshl_add_u64 v[92:93], s[44:45], 0, v[158:159]
	s_mov_b32 m0, s46
	s_nop 0
	global_load_lds_dwordx4 v[92:93], off
	v_lshl_add_u64 v[92:93], s[44:45], 0, v[0:1]
	s_add_i32 m0, s46, 0x2000
	s_nop 0
	global_load_lds_dwordx4 v[92:93], off
	s_add_i32 s44, 0, 0x18000
	v_add_u32_e32 v2, s44, v167
	s_waitcnt vmcnt(6)
	s_setprio 1
	s_barrier
	v_mfma_f32_16x16x32_bf16 v[32:35], v[216:219], v[148:151], 0
	v_mfma_f32_16x16x32_bf16 v[32:35], v[220:223], v[152:155], v[32:35]
	v_mfma_f32_16x16x32_bf16 v[24:27], v[216:219], v[176:179], 0
	v_mfma_f32_16x16x32_bf16 v[24:27], v[220:223], v[180:183], v[24:27]
	v_mfma_f32_16x16x32_bf16 v[16:19], v[216:219], v[184:187], 0
	v_mfma_f32_16x16x32_bf16 v[16:19], v[220:223], v[188:191], v[16:19]
	v_mfma_f32_16x16x32_bf16 v[8:11], v[216:219], v[192:195], 0
	v_mfma_f32_16x16x32_bf16 v[8:11], v[220:223], v[212:215], v[8:11]
	v_mfma_f32_16x16x32_bf16 v[28:31], v[224:227], v[148:151], 0
	v_mfma_f32_16x16x32_bf16 v[28:31], v[228:231], v[152:155], v[28:31]
	v_mfma_f32_16x16x32_bf16 v[20:23], v[224:227], v[176:179], 0
	v_mfma_f32_16x16x32_bf16 v[20:23], v[228:231], v[180:183], v[20:23]
	v_mfma_f32_16x16x32_bf16 v[12:15], v[224:227], v[184:187], 0
	v_mfma_f32_16x16x32_bf16 v[12:15], v[228:231], v[188:191], v[12:15]
	v_mfma_f32_16x16x32_bf16 v[4:7], v[224:227], v[192:195], 0
	v_mfma_f32_16x16x32_bf16 v[4:7], v[228:231], v[212:215], v[4:7]
	s_barrier
	s_setprio 0
	ds_read_b128 v[92:95], v2
	ds_read_b128 v[100:103], v2 offset:1024
	ds_read_b128 v[132:135], v2 offset:2048
	ds_read_b128 v[144:147], v2 offset:3072
	s_add_u32 s10, s10, 0x80000
	s_addc_u32 s11, s11, 0
	s_mov_b32 m0, s34
	v_lshl_add_u64 v[216:217], s[10:11], 0, v[160:161]
	ds_read_b128 v[148:151], v169 offset:32768
	ds_read_b128 v[152:155], v169 offset:33792
	ds_read_b128 v[176:179], v169 offset:34816
	ds_read_b128 v[180:183], v169 offset:35840
	ds_read_b128 v[184:187], v169 offset:36864
	ds_read_b128 v[188:191], v169 offset:37888
	ds_read_b128 v[192:195], v169 offset:38912
	ds_read_b128 v[212:215], v169 offset:39936
	global_load_lds_dwordx4 v[216:217], off
	v_lshl_add_u64 v[216:217], s[10:11], 0, v[156:157]
	s_mov_b32 m0, s35
	s_nop 0
	global_load_lds_dwordx4 v[216:217], off
	s_waitcnt lgkmcnt(6)
	s_setprio 1
	s_barrier
	v_mfma_f32_16x16x32_bf16 v[140:143], v[92:95], v[148:151], v[140:143]
	v_mfma_f32_16x16x32_bf16 v[140:143], v[100:103], v[152:155], v[140:143]
	s_waitcnt lgkmcnt(0)
	v_mfma_f32_16x16x32_bf16 v[128:131], v[92:95], v[176:179], v[128:131]
	v_mfma_f32_16x16x32_bf16 v[128:131], v[100:103], v[180:183], v[128:131]
	v_mfma_f32_16x16x32_bf16 v[120:123], v[92:95], v[184:187], v[120:123]
	v_mfma_f32_16x16x32_bf16 v[120:123], v[100:103], v[188:191], v[120:123]
	v_mfma_f32_16x16x32_bf16 v[112:115], v[92:95], v[192:195], v[112:115]
	v_mfma_f32_16x16x32_bf16 v[112:115], v[100:103], v[212:215], v[112:115]
	v_mfma_f32_16x16x32_bf16 v[136:139], v[132:135], v[148:151], v[136:139]
	v_mfma_f32_16x16x32_bf16 v[136:139], v[144:147], v[152:155], v[136:139]
	v_mfma_f32_16x16x32_bf16 v[124:127], v[132:135], v[176:179], v[124:127]
	v_mfma_f32_16x16x32_bf16 v[124:127], v[144:147], v[180:183], v[124:127]
	v_mfma_f32_16x16x32_bf16 v[116:119], v[132:135], v[184:187], v[116:119]
	v_mfma_f32_16x16x32_bf16 v[116:119], v[144:147], v[188:191], v[116:119]
	v_mfma_f32_16x16x32_bf16 v[108:111], v[132:135], v[192:195], v[108:111]
	v_mfma_f32_16x16x32_bf16 v[108:111], v[144:147], v[212:215], v[108:111]
	s_barrier
	s_setprio 0
	s_add_i32 s10, 0, 0x1c000
	s_add_i32 s11, s44, s29
	v_add_u32_e32 v2, s10, v167
	v_lshl_add_u64 v[196:197], v[196:197], 0, s[52:53]
	s_mov_b32 m0, s11
	ds_read_b128 v[216:219], v2
	ds_read_b128 v[220:223], v2 offset:1024
	ds_read_b128 v[224:227], v2 offset:2048
	ds_read_b128 v[228:231], v2 offset:3072
	global_load_lds_dwordx4 v[196:197], off
	v_lshl_add_u64 v[196:197], v[232:233], 0, s[52:53]
	s_add_i32 m0, s11, 0x2000
	s_nop 0
	global_load_lds_dwordx4 v[196:197], off
	s_mov_b32 m0, s37
	v_lshl_add_u64 v[196:197], v[234:235], 0, s[52:53]
	s_waitcnt lgkmcnt(2)
	s_setprio 1
	s_barrier
	v_mfma_f32_16x16x32_bf16 v[64:67], v[216:219], v[148:151], v[64:67]
	v_mfma_f32_16x16x32_bf16 v[64:67], v[220:223], v[152:155], v[64:67]
	s_waitcnt lgkmcnt(0)
	v_mfma_f32_16x16x32_bf16 v[56:59], v[216:219], v[176:179], v[56:59]
	v_mfma_f32_16x16x32_bf16 v[56:59], v[220:223], v[180:183], v[56:59]
	v_mfma_f32_16x16x32_bf16 v[48:51], v[216:219], v[184:187], v[48:51]
	v_mfma_f32_16x16x32_bf16 v[48:51], v[220:223], v[188:191], v[48:51]
	v_mfma_f32_16x16x32_bf16 v[40:43], v[216:219], v[192:195], v[40:43]
	v_mfma_f32_16x16x32_bf16 v[40:43], v[220:223], v[212:215], v[40:43]
	v_mfma_f32_16x16x32_bf16 v[60:63], v[224:227], v[148:151], v[60:63]
	v_mfma_f32_16x16x32_bf16 v[60:63], v[228:231], v[152:155], v[60:63]
	v_mfma_f32_16x16x32_bf16 v[52:55], v[224:227], v[176:179], v[52:55]
	v_mfma_f32_16x16x32_bf16 v[52:55], v[228:231], v[180:183], v[52:55]
	v_mfma_f32_16x16x32_bf16 v[44:47], v[224:227], v[184:187], v[44:47]
	v_mfma_f32_16x16x32_bf16 v[44:47], v[228:231], v[188:191], v[44:47]
	v_mfma_f32_16x16x32_bf16 v[36:39], v[224:227], v[192:195], v[36:39]
	v_mfma_f32_16x16x32_bf16 v[36:39], v[228:231], v[212:215], v[36:39]
	s_barrier
	s_setprio 0
	ds_read_b128 v[148:151], v169 offset:49152
	ds_read_b128 v[152:155], v169 offset:50176
	ds_read_b128 v[176:179], v169 offset:51200
	ds_read_b128 v[180:183], v169 offset:52224
	ds_read_b128 v[184:187], v169 offset:53248
	ds_read_b128 v[188:191], v169 offset:54272
	ds_read_b128 v[192:195], v169 offset:55296
	ds_read_b128 v[212:215], v169 offset:56320
	global_load_lds_dwordx4 v[196:197], off
	v_lshl_add_u64 v[196:197], v[236:237], 0, s[52:53]
	s_mov_b32 m0, s38
	s_nop 0
	global_load_lds_dwordx4 v[196:197], off
	s_waitcnt lgkmcnt(6)
	s_setprio 1
	s_barrier
; #define PG8_WAIT_V(n) asm volatile("s_waitcnt vmcnt(" #n ")" ::: "memory")
; #define PG8_WAIT_L(n) asm volatile("s_waitcnt lgkmcnt(" #n ")" ::: "memory")
; #define PG8_BAR __builtin_amdgcn_s_barrier()
; #define PG8_SCHED __builtin_amdgcn_sched_barrier(0)
; template <class Epi, class AddrA, class AddrB>
; __device__ __forceinline__ void gemm_phase(const Sched S, const int lda, const int ldb, const int K, const AddrA addrA,
;                                            const AddrB addrB, const Epi E) {
;     ...
;       PG8_LDB(B0, 0, 0); PG8_SCHED; PG8_LDA(At, 0, 0); PG8_STAGE(PG8_SA(1, 1), a1 + hstepA, voffA);
;       PG8_WAIT_L(8); PG8_BAR; PG8_WAIT_L(0); PG8_MMA(0, 0, At, B0); PG8_BAR; PG8_SCHED;
;       PG8_LDB(B1, 0, 1); PG8_STAGE(PG8_SB(0, 0), b2, voffB);
;       PG8_BAR; PG8_WAIT_L(0); PG8_MMA(0, 1, At, B1); PG8_BAR;
;     ...
;       PG8_WAIT_V(6); PG8_BAR; PG8_MMA(1, 1, At, B1); PG8_BAR;
;       PG8_LDB(B0, 1, 0); PG8_SCHED; PG8_LDA(At, 1, 0); PG8_STAGE(PG8_SA(0, 1), a2 + hstepA, voffA);
;       PG8_WAIT_L(8); PG8_BAR; PG8_WAIT_L(0); PG8_MMA(0, 0, At, B0); PG8_BAR; PG8_SCHED;
;       PG8_LDB(B1, 1, 1); PG8_STAGE(PG8_SB(1, 0), b3, voffB);
;       PG8_BAR; PG8_WAIT_L(0); PG8_MMA(0, 1, At, B1); PG8_BAR;
;       PG8_LDA(At, 1, 1); PG8_STAGE(PG8_SA(1, 0), a3, voffA);
;       PG8_BAR; PG8_WAIT_L(0); PG8_MMA(1, 0, At, B0); PG8_BAR; PG8_SCHED;
;       PG8_STAGE(PG8_SB(1, 1), b3 + hstepB, voffB);
;       PG8_WAIT_V(6); PG8_BAR; PG8_MMA(1, 1, At, B1); PG8_BAR;
	v_mfma_f32_16x16x32_bf16 v[104:107], v[92:95], v[148:151], v[104:107]
	v_mfma_f32_16x16x32_bf16 v[104:107], v[100:103], v[152:155], v[104:107]
	s_waitcnt lgkmcnt(0)
	v_mfma_f32_16x16x32_bf16 v[88:91], v[92:95], v[176:179], v[88:91]
	v_mfma_f32_16x16x32_bf16 v[88:91], v[100:103], v[180:183], v[88:91]
	v_mfma_f32_16x16x32_bf16 v[80:83], v[92:95], v[184:187], v[80:83]
	v_mfma_f32_16x16x32_bf16 v[80:83], v[100:103], v[188:191], v[80:83]
	v_mfma_f32_16x16x32_bf16 v[72:75], v[92:95], v[192:195], v[72:75]
	v_mfma_f32_16x16x32_bf16 v[72:75], v[100:103], v[212:215], v[72:75]
	v_mfma_f32_16x16x32_bf16 v[96:99], v[132:135], v[148:151], v[96:99]
	v_mfma_f32_16x16x32_bf16 v[96:99], v[144:147], v[152:155], v[96:99]
	v_mfma_f32_16x16x32_bf16 v[84:87], v[132:135], v[176:179], v[84:87]
	v_mfma_f32_16x16x32_bf16 v[84:87], v[144:147], v[180:183], v[84:87]
	v_mfma_f32_16x16x32_bf16 v[76:79], v[132:135], v[184:187], v[76:79]
	v_mfma_f32_16x16x32_bf16 v[76:79], v[144:147], v[188:191], v[76:79]
	v_mfma_f32_16x16x32_bf16 v[68:71], v[132:135], v[192:195], v[68:71]
	v_mfma_f32_16x16x32_bf16 v[68:71], v[144:147], v[212:215], v[68:71]
	s_barrier
	s_setprio 0
	s_add_u32 s6, s6, 0x20080
	s_addc_u32 s7, s7, 0
	s_add_i32 s10, s10, s29
	v_lshl_add_u64 v[92:93], s[6:7], 0, v[158:159]
	s_mov_b32 m0, s10
	s_nop 0
	global_load_lds_dwordx4 v[92:93], off
	v_lshl_add_u64 v[92:93], s[6:7], 0, v[0:1]
	s_add_i32 m0, s10, 0x2000
	s_nop 0
	global_load_lds_dwordx4 v[92:93], off
	s_add_i32 s43, s43, 2
	s_add_u32 s41, s41, 0x100
	s_addc_u32 s42, s42, 0
	s_add_u32 s4, s4, 0x100
	s_addc_u32 s5, s5, 0
	s_waitcnt vmcnt(6)
	s_setprio 1
	s_barrier
	v_mfma_f32_16x16x32_bf16 v[32:35], v[216:219], v[148:151], v[32:35]
	v_mfma_f32_16x16x32_bf16 v[32:35], v[220:223], v[152:155], v[32:35]
	v_mfma_f32_16x16x32_bf16 v[24:27], v[216:219], v[176:179], v[24:27]
	v_mfma_f32_16x16x32_bf16 v[24:27], v[220:223], v[180:183], v[24:27]
	v_mfma_f32_16x16x32_bf16 v[16:19], v[216:219], v[184:187], v[16:19]
	v_mfma_f32_16x16x32_bf16 v[16:19], v[220:223], v[188:191], v[16:19]
	v_mfma_f32_16x16x32_bf16 v[8:11], v[216:219], v[192:195], v[8:11]
	v_mfma_f32_16x16x32_bf16 v[8:11], v[220:223], v[212:215], v[8:11]
	v_mfma_f32_16x16x32_bf16 v[28:31], v[224:227], v[148:151], v[28:31]
	v_mfma_f32_16x16x32_bf16 v[28:31], v[228:231], v[152:155], v[28:31]
	v_mfma_f32_16x16x32_bf16 v[20:23], v[224:227], v[176:179], v[20:23]
	v_mfma_f32_16x16x32_bf16 v[20:23], v[228:231], v[180:183], v[20:23]
	v_mfma_f32_16x16x32_bf16 v[12:15], v[224:227], v[184:187], v[12:15]
	v_mfma_f32_16x16x32_bf16 v[12:15], v[228:231], v[188:191], v[12:15]
	v_mfma_f32_16x16x32_bf16 v[4:7], v[224:227], v[192:195], v[4:7]
	v_mfma_f32_16x16x32_bf16 v[4:7], v[228:231], v[212:215], v[4:7]
	s_barrier
	s_setprio 0
	s_cmp_gt_u32 s43, 5
.LBB0_485:
	s_add_i32 s44, 0, 0x10000
	v_add_u32_e32 v2, s44, v167
	ds_read_b128 v[92:95], v2
	ds_read_b128 v[100:103], v2 offset:1024
	ds_read_b128 v[132:135], v2 offset:2048
	ds_read_b128 v[144:147], v2 offset:3072
	v_lshl_add_u64 v[196:197], s[4:5], 0, v[172:173]
	s_add_i32 m0, s30, 0xc000
	ds_read_b128 v[148:151], v169
	ds_read_b128 v[152:155], v169 offset:1024
	ds_read_b128 v[176:179], v169 offset:2048
	ds_read_b128 v[180:183], v169 offset:3072
	ds_read_b128 v[184:187], v169 offset:4096
	ds_read_b128 v[188:191], v169 offset:5120
	ds_read_b128 v[192:195], v169 offset:6144
	ds_read_b128 v[212:215], v169 offset:7168
	global_load_lds_dwordx4 v[196:197], off
	v_lshl_add_u64 v[196:197], s[4:5], 0, v[170:171]
	s_add_i32 m0, s30, 0xe000
	s_nop 0
	global_load_lds_dwordx4 v[196:197], off
	s_waitcnt lgkmcnt(6)
	s_setprio 1
	s_barrier
	v_mfma_f32_16x16x32_bf16 v[140:143], v[92:95], v[148:151], v[140:143]
	v_mfma_f32_16x16x32_bf16 v[140:143], v[100:103], v[152:155], v[140:143]
	s_waitcnt lgkmcnt(0)
	v_mfma_f32_16x16x32_bf16 v[128:131], v[92:95], v[176:179], v[128:131]
	v_mfma_f32_16x16x32_bf16 v[128:131], v[100:103], v[180:183], v[128:131]
	v_mfma_f32_16x16x32_bf16 v[120:123], v[92:95], v[184:187], v[120:123]
	v_mfma_f32_16x16x32_bf16 v[120:123], v[100:103], v[188:191], v[120:123]
	v_mfma_f32_16x16x32_bf16 v[112:115], v[92:95], v[192:195], v[112:115]
	v_mfma_f32_16x16x32_bf16 v[112:115], v[100:103], v[212:215], v[112:115]
	v_mfma_f32_16x16x32_bf16 v[136:139], v[132:135], v[148:151], v[136:139]
	v_mfma_f32_16x16x32_bf16 v[136:139], v[144:147], v[152:155], v[136:139]
	v_mfma_f32_16x16x32_bf16 v[124:127], v[132:135], v[176:179], v[124:127]
	v_mfma_f32_16x16x32_bf16 v[124:127], v[144:147], v[180:183], v[124:127]
	v_mfma_f32_16x16x32_bf16 v[116:119], v[132:135], v[184:187], v[116:119]
	v_mfma_f32_16x16x32_bf16 v[116:119], v[144:147], v[188:191], v[116:119]
	v_mfma_f32_16x16x32_bf16 v[108:111], v[132:135], v[192:195], v[108:111]
	v_mfma_f32_16x16x32_bf16 v[108:111], v[144:147], v[212:215], v[108:111]
	s_barrier
	s_setprio 0
	s_add_u32 s6, s4, 0xfff80080
	s_addc_u32 s7, s5, -1
	s_cmp_eq_u32 s43, 4
	s_cselect_b32 s11, s3, s7
	s_cselect_b32 s10, s15, s6
	s_cselect_b32 s7, s17, s42
	s_cselect_b32 s6, s40, s41
	s_add_i32 s46, 0, 0x14000
	s_add_i32 s44, s44, s29
	v_add_u32_e32 v2, s46, v167
	v_lshl_add_u64 v[196:197], s[6:7], 0, v[158:159]
	s_mov_b32 m0, s44
	ds_read_b128 v[216:219], v2
	ds_read_b128 v[220:223], v2 offset:1024
	ds_read_b128 v[224:227], v2 offset:2048
	ds_read_b128 v[228:231], v2 offset:3072
	global_load_lds_dwordx4 v[196:197], off
	v_lshl_add_u64 v[232:233], s[6:7], 0, v[0:1]
	s_add_i32 m0, s44, 0x2000
	s_nop 0
	global_load_lds_dwordx4 v[232:233], off
	s_mov_b32 m0, s30
	v_lshl_add_u64 v[234:235], s[10:11], 0, v[160:161]
	s_waitcnt lgkmcnt(2)
	s_setprio 1
	s_barrier
; #define PG8_WAIT_V(n) asm volatile("s_waitcnt vmcnt(" #n ")" ::: "memory")
; #define PG8_WAIT_L(n) asm volatile("s_waitcnt lgkmcnt(" #n ")" ::: "memory")
; #define PG8_BAR __builtin_amdgcn_s_barrier()
; #define PG8_SCHED __builtin_amdgcn_sched_barrier(0)
; template <class Epi, class AddrA, class AddrB>
; __device__ __forceinline__ void gemm_phase(const Sched S, const int lda, const int ldb, const int K, const AddrA addrA,
;                                            const AddrB addrB, const Epi E) {
;     ...
;       PG8_BAR; PG8_WAIT_L(0); PG8_MMA(0, 1, At, B1); PG8_BAR;
;       PG8_LDA(At, 0, 1); PG8_STAGE(PG8_SA(0, 0), a2, voffA);
;       PG8_BAR; PG8_WAIT_L(0); PG8_MMA(1, 0, At, B0); PG8_BAR; PG8_SCHED;
;       PG8_STAGE(PG8_SB(0, 1), b2 + hstepB, voffB);
;       PG8_WAIT_V(6); PG8_BAR; PG8_MMA(1, 1, At, B1); PG8_BAR;
;       PG8_LDB(B0, 1, 0); PG8_SCHED; PG8_LDA(At, 1, 0); PG8_STAGE(PG8_SA(0, 1), a2 + hstepA, voffA);
;       PG8_WAIT_L(8); PG8_BAR; PG8_WAIT_L(0); PG8_MMA(0, 0, At, B0); PG8_BAR; PG8_SCHED;
;       PG8_LDB(B1, 1, 1); PG8_STAGE(PG8_SB(1, 0), b3, voffB);
;       PG8_BAR; PG8_WAIT_L(0); PG8_MMA(0, 1, At, B1); PG8_BAR;
;       PG8_LDA(At, 1, 1); PG8_STAGE(PG8_SA(1, 0), a3, voffA);
;       PG8_BAR; PG8_WAIT_L(0); PG8_MMA(1, 0, At, B0); PG8_BAR; PG8_SCHED;
	v_mfma_f32_16x16x32_bf16 v[64:67], v[216:219], v[148:151], v[64:67]
	v_mfma_f32_16x16x32_bf16 v[64:67], v[220:223], v[152:155], v[64:67]
	s_waitcnt lgkmcnt(0)
	v_mfma_f32_16x16x32_bf16 v[56:59], v[216:219], v[176:179], v[56:59]
	v_mfma_f32_16x16x32_bf16 v[56:59], v[220:223], v[180:183], v[56:59]
	v_mfma_f32_16x16x32_bf16 v[48:51], v[216:219], v[184:187], v[48:51]
	v_mfma_f32_16x16x32_bf16 v[48:51], v[220:223], v[188:191], v[48:51]
	v_mfma_f32_16x16x32_bf16 v[40:43], v[216:219], v[192:195], v[40:43]
	v_mfma_f32_16x16x32_bf16 v[40:43], v[220:223], v[212:215], v[40:43]
	v_mfma_f32_16x16x32_bf16 v[60:63], v[224:227], v[148:151], v[60:63]
	v_mfma_f32_16x16x32_bf16 v[60:63], v[228:231], v[152:155], v[60:63]
	v_mfma_f32_16x16x32_bf16 v[52:55], v[224:227], v[176:179], v[52:55]
	v_mfma_f32_16x16x32_bf16 v[52:55], v[228:231], v[180:183], v[52:55]
	v_mfma_f32_16x16x32_bf16 v[44:47], v[224:227], v[184:187], v[44:47]
	v_mfma_f32_16x16x32_bf16 v[44:47], v[228:231], v[188:191], v[44:47]
	v_mfma_f32_16x16x32_bf16 v[36:39], v[224:227], v[192:195], v[36:39]
	v_mfma_f32_16x16x32_bf16 v[36:39], v[228:231], v[212:215], v[36:39]
	s_barrier
	s_setprio 0
	ds_read_b128 v[148:151], v169 offset:16384
	ds_read_b128 v[152:155], v169 offset:17408
	ds_read_b128 v[176:179], v169 offset:18432
	ds_read_b128 v[180:183], v169 offset:19456
	ds_read_b128 v[184:187], v169 offset:20480
	ds_read_b128 v[188:191], v169 offset:21504
	ds_read_b128 v[192:195], v169 offset:22528
	ds_read_b128 v[212:215], v169 offset:23552
	global_load_lds_dwordx4 v[234:235], off
	v_lshl_add_u64 v[236:237], s[10:11], 0, v[156:157]
	s_mov_b32 m0, s31
	s_nop 0
	global_load_lds_dwordx4 v[236:237], off
	s_waitcnt lgkmcnt(6)
	s_setprio 1
	s_barrier
	v_mfma_f32_16x16x32_bf16 v[104:107], v[92:95], v[148:151], v[104:107]
	v_mfma_f32_16x16x32_bf16 v[104:107], v[100:103], v[152:155], v[104:107]
	s_waitcnt lgkmcnt(0)
	v_mfma_f32_16x16x32_bf16 v[88:91], v[92:95], v[176:179], v[88:91]
	v_mfma_f32_16x16x32_bf16 v[88:91], v[100:103], v[180:183], v[88:91]
	v_mfma_f32_16x16x32_bf16 v[80:83], v[92:95], v[184:187], v[80:83]
	v_mfma_f32_16x16x32_bf16 v[80:83], v[100:103], v[188:191], v[80:83]
	v_mfma_f32_16x16x32_bf16 v[72:75], v[92:95], v[192:195], v[72:75]
	v_mfma_f32_16x16x32_bf16 v[72:75], v[100:103], v[212:215], v[72:75]
	v_mfma_f32_16x16x32_bf16 v[96:99], v[132:135], v[148:151], v[96:99]
	v_mfma_f32_16x16x32_bf16 v[96:99], v[144:147], v[152:155], v[96:99]
	v_mfma_f32_16x16x32_bf16 v[84:87], v[132:135], v[176:179], v[84:87]
	v_mfma_f32_16x16x32_bf16 v[84:87], v[144:147], v[180:183], v[84:87]
	v_mfma_f32_16x16x32_bf16 v[76:79], v[132:135], v[184:187], v[76:79]
	v_mfma_f32_16x16x32_bf16 v[76:79], v[144:147], v[188:191], v[76:79]
	v_mfma_f32_16x16x32_bf16 v[68:71], v[132:135], v[192:195], v[68:71]
	v_mfma_f32_16x16x32_bf16 v[68:71], v[144:147], v[212:215], v[68:71]
	s_barrier
	s_setprio 0
	s_add_u32 s44, s6, 0x20000
	s_addc_u32 s45, s7, 0
	s_add_i32 s46, s46, s29
	v_lshl_add_u64 v[92:93], s[44:45], 0, v[158:159]
	s_mov_b32 m0, s46
	s_nop 0
	global_load_lds_dwordx4 v[92:93], off
	v_lshl_add_u64 v[92:93], s[44:45], 0, v[0:1]
	s_add_i32 m0, s46, 0x2000
	s_nop 0
	global_load_lds_dwordx4 v[92:93], off
	s_add_i32 s44, 0, 0x18000
	v_add_u32_e32 v2, s44, v167
	s_waitcnt vmcnt(6)
	s_setprio 1
	s_barrier
	v_mfma_f32_16x16x32_bf16 v[32:35], v[216:219], v[148:151], v[32:35]
	v_mfma_f32_16x16x32_bf16 v[32:35], v[220:223], v[152:155], v[32:35]
	v_mfma_f32_16x16x32_bf16 v[24:27], v[216:219], v[176:179], v[24:27]
	v_mfma_f32_16x16x32_bf16 v[24:27], v[220:223], v[180:183], v[24:27]
	v_mfma_f32_16x16x32_bf16 v[16:19], v[216:219], v[184:187], v[16:19]
	v_mfma_f32_16x16x32_bf16 v[16:19], v[220:223], v[188:191], v[16:19]
	v_mfma_f32_16x16x32_bf16 v[8:11], v[216:219], v[192:195], v[8:11]
	v_mfma_f32_16x16x32_bf16 v[8:11], v[220:223], v[212:215], v[8:11]
	v_mfma_f32_16x16x32_bf16 v[28:31], v[224:227], v[148:151], v[28:31]
	v_mfma_f32_16x16x32_bf16 v[28:31], v[228:231], v[152:155], v[28:31]
	v_mfma_f32_16x16x32_bf16 v[20:23], v[224:227], v[176:179], v[20:23]
	v_mfma_f32_16x16x32_bf16 v[20:23], v[228:231], v[180:183], v[20:23]
	v_mfma_f32_16x16x32_bf16 v[12:15], v[224:227], v[184:187], v[12:15]
	v_mfma_f32_16x16x32_bf16 v[12:15], v[228:231], v[188:191], v[12:15]
	v_mfma_f32_16x16x32_bf16 v[4:7], v[224:227], v[192:195], v[4:7]
	v_mfma_f32_16x16x32_bf16 v[4:7], v[228:231], v[212:215], v[4:7]
	s_barrier
	s_setprio 0
	ds_read_b128 v[92:95], v2
	ds_read_b128 v[100:103], v2 offset:1024
	ds_read_b128 v[132:135], v2 offset:2048
	ds_read_b128 v[144:147], v2 offset:3072
	s_add_u32 s10, s10, 0x80000
	s_addc_u32 s11, s11, 0
	s_mov_b32 m0, s34
	v_lshl_add_u64 v[216:217], s[10:11], 0, v[160:161]
	ds_read_b128 v[148:151], v169 offset:32768
	ds_read_b128 v[152:155], v169 offset:33792
	ds_read_b128 v[176:179], v169 offset:34816
	ds_read_b128 v[180:183], v169 offset:35840
	ds_read_b128 v[184:187], v169 offset:36864
	ds_read_b128 v[188:191], v169 offset:37888
	ds_read_b128 v[192:195], v169 offset:38912
	ds_read_b128 v[212:215], v169 offset:39936
	global_load_lds_dwordx4 v[216:217], off
	v_lshl_add_u64 v[216:217], s[10:11], 0, v[156:157]
	s_mov_b32 m0, s35
	s_nop 0
	global_load_lds_dwordx4 v[216:217], off
	s_waitcnt lgkmcnt(6)
	s_setprio 1
	s_barrier
; #define PG8_WAIT_V(n) asm volatile("s_waitcnt vmcnt(" #n ")" ::: "memory")
; #define PG8_WAIT_L(n) asm volatile("s_waitcnt lgkmcnt(" #n ")" ::: "memory")
; #define PG8_BAR __builtin_amdgcn_s_barrier()
; #define PG8_SCHED __builtin_amdgcn_sched_barrier(0)
; template <class Epi, class AddrA, class AddrB>
; __device__ __forceinline__ void gemm_phase(const Sched S, const int lda, const int ldb, const int K, const AddrA addrA,
;                                            const AddrB addrB, const Epi E) {
;     ...
;       PG8_WAIT_L(8); PG8_BAR; PG8_WAIT_L(0); PG8_MMA(0, 0, At, B0); PG8_BAR; PG8_SCHED;
;       PG8_LDB(B1, 1, 1); PG8_STAGE(PG8_SB(1, 0), b3, voffB);
;       PG8_BAR; PG8_WAIT_L(0); PG8_MMA(0, 1, At, B1); PG8_BAR;
;       PG8_LDA(At, 1, 1); PG8_STAGE(PG8_SA(1, 0), a3, voffA);
;       PG8_BAR; PG8_WAIT_L(0); PG8_MMA(1, 0, At, B0); PG8_BAR; PG8_SCHED;
;       PG8_STAGE(PG8_SB(1, 1), b3 + hstepB, voffB);
;       PG8_WAIT_V(6); PG8_BAR; PG8_MMA(1, 1, At, B1); PG8_BAR;
	v_mfma_f32_16x16x32_bf16 v[140:143], v[92:95], v[148:151], v[140:143]
	v_mfma_f32_16x16x32_bf16 v[140:143], v[100:103], v[152:155], v[140:143]
	s_waitcnt lgkmcnt(0)
	v_mfma_f32_16x16x32_bf16 v[128:131], v[92:95], v[176:179], v[128:131]
	v_mfma_f32_16x16x32_bf16 v[128:131], v[100:103], v[180:183], v[128:131]
	v_mfma_f32_16x16x32_bf16 v[120:123], v[92:95], v[184:187], v[120:123]
	v_mfma_f32_16x16x32_bf16 v[120:123], v[100:103], v[188:191], v[120:123]
	v_mfma_f32_16x16x32_bf16 v[112:115], v[92:95], v[192:195], v[112:115]
	v_mfma_f32_16x16x32_bf16 v[112:115], v[100:103], v[212:215], v[112:115]
	v_mfma_f32_16x16x32_bf16 v[136:139], v[132:135], v[148:151], v[136:139]
	v_mfma_f32_16x16x32_bf16 v[136:139], v[144:147], v[152:155], v[136:139]
	v_mfma_f32_16x16x32_bf16 v[124:127], v[132:135], v[176:179], v[124:127]
	v_mfma_f32_16x16x32_bf16 v[124:127], v[144:147], v[180:183], v[124:127]
	v_mfma_f32_16x16x32_bf16 v[116:119], v[132:135], v[184:187], v[116:119]
	v_mfma_f32_16x16x32_bf16 v[116:119], v[144:147], v[188:191], v[116:119]
	v_mfma_f32_16x16x32_bf16 v[108:111], v[132:135], v[192:195], v[108:111]
	v_mfma_f32_16x16x32_bf16 v[108:111], v[144:147], v[212:215], v[108:111]
	s_barrier
	s_setprio 0
	s_add_i32 s10, 0, 0x1c000
	s_add_i32 s11, s44, s29
	v_add_u32_e32 v2, s10, v167
	v_lshl_add_u64 v[196:197], v[196:197], 0, s[52:53]
	s_mov_b32 m0, s11
	ds_read_b128 v[216:219], v2
	ds_read_b128 v[220:223], v2 offset:1024
	ds_read_b128 v[224:227], v2 offset:2048
	ds_read_b128 v[228:231], v2 offset:3072
	global_load_lds_dwordx4 v[196:197], off
	v_lshl_add_u64 v[196:197], v[232:233], 0, s[52:53]
	s_add_i32 m0, s11, 0x2000
	s_nop 0
	global_load_lds_dwordx4 v[196:197], off
	s_mov_b32 m0, s37
	v_lshl_add_u64 v[196:197], v[234:235], 0, s[52:53]
	s_waitcnt lgkmcnt(2)
	s_setprio 1
	s_barrier
	v_mfma_f32_16x16x32_bf16 v[64:67], v[216:219], v[148:151], v[64:67]
	v_mfma_f32_16x16x32_bf16 v[64:67], v[220:223], v[152:155], v[64:67]
	s_waitcnt lgkmcnt(0)
	v_mfma_f32_16x16x32_bf16 v[56:59], v[216:219], v[176:179], v[56:59]
	v_mfma_f32_16x16x32_bf16 v[56:59], v[220:223], v[180:183], v[56:59]
	v_mfma_f32_16x16x32_bf16 v[48:51], v[216:219], v[184:187], v[48:51]
	v_mfma_f32_16x16x32_bf16 v[48:51], v[220:223], v[188:191], v[48:51]
	v_mfma_f32_16x16x32_bf16 v[40:43], v[216:219], v[192:195], v[40:43]
	v_mfma_f32_16x16x32_bf16 v[40:43], v[220:223], v[212:215], v[40:43]
	v_mfma_f32_16x16x32_bf16 v[60:63], v[224:227], v[148:151], v[60:63]
	v_mfma_f32_16x16x32_bf16 v[60:63], v[228:231], v[152:155], v[60:63]
	v_mfma_f32_16x16x32_bf16 v[52:55], v[224:227], v[176:179], v[52:55]
	v_mfma_f32_16x16x32_bf16 v[52:55], v[228:231], v[180:183], v[52:55]
	v_mfma_f32_16x16x32_bf16 v[44:47], v[224:227], v[184:187], v[44:47]
	v_mfma_f32_16x16x32_bf16 v[44:47], v[228:231], v[188:191], v[44:47]
	v_mfma_f32_16x16x32_bf16 v[36:39], v[224:227], v[192:195], v[36:39]
	v_mfma_f32_16x16x32_bf16 v[36:39], v[228:231], v[212:215], v[36:39]
	s_barrier
	s_setprio 0
	ds_read_b128 v[148:151], v169 offset:49152
	ds_read_b128 v[152:155], v169 offset:50176
	ds_read_b128 v[176:179], v169 offset:51200
	ds_read_b128 v[180:183], v169 offset:52224
	ds_read_b128 v[184:187], v169 offset:53248
	ds_read_b128 v[188:191], v169 offset:54272
	ds_read_b128 v[192:195], v169 offset:55296
	ds_read_b128 v[212:215], v169 offset:56320
	global_load_lds_dwordx4 v[196:197], off
	v_lshl_add_u64 v[196:197], v[236:237], 0, s[52:53]
	s_mov_b32 m0, s38
	s_nop 0
	global_load_lds_dwordx4 v[196:197], off
	s_waitcnt lgkmcnt(6)
	s_setprio 1
	s_barrier
	v_mfma_f32_16x16x32_bf16 v[104:107], v[92:95], v[148:151], v[104:107]
	v_mfma_f32_16x16x32_bf16 v[104:107], v[100:103], v[152:155], v[104:107]
	s_waitcnt lgkmcnt(0)
	v_mfma_f32_16x16x32_bf16 v[88:91], v[92:95], v[176:179], v[88:91]
	v_mfma_f32_16x16x32_bf16 v[88:91], v[100:103], v[180:183], v[88:91]
	v_mfma_f32_16x16x32_bf16 v[80:83], v[92:95], v[184:187], v[80:83]
	v_mfma_f32_16x16x32_bf16 v[80:83], v[100:103], v[188:191], v[80:83]
	v_mfma_f32_16x16x32_bf16 v[72:75], v[92:95], v[192:195], v[72:75]
	v_mfma_f32_16x16x32_bf16 v[72:75], v[100:103], v[212:215], v[72:75]
	v_mfma_f32_16x16x32_bf16 v[96:99], v[132:135], v[148:151], v[96:99]
	v_mfma_f32_16x16x32_bf16 v[96:99], v[144:147], v[152:155], v[96:99]
	v_mfma_f32_16x16x32_bf16 v[84:87], v[132:135], v[176:179], v[84:87]
	v_mfma_f32_16x16x32_bf16 v[84:87], v[144:147], v[180:183], v[84:87]
	v_mfma_f32_16x16x32_bf16 v[76:79], v[132:135], v[184:187], v[76:79]
	v_mfma_f32_16x16x32_bf16 v[76:79], v[144:147], v[188:191], v[76:79]
	v_mfma_f32_16x16x32_bf16 v[68:71], v[132:135], v[192:195], v[68:71]
	v_mfma_f32_16x16x32_bf16 v[68:71], v[144:147], v[212:215], v[68:71]
	s_barrier
	s_setprio 0
	s_add_u32 s6, s6, 0x20080
	s_addc_u32 s7, s7, 0
	s_add_i32 s10, s10, s29
	v_lshl_add_u64 v[92:93], s[6:7], 0, v[158:159]
	s_mov_b32 m0, s10
	s_nop 0
	global_load_lds_dwordx4 v[92:93], off
	v_lshl_add_u64 v[92:93], s[6:7], 0, v[0:1]
	s_add_i32 m0, s10, 0x2000
	s_nop 0
	global_load_lds_dwordx4 v[92:93], off
	s_add_i32 s43, s43, 2
	s_add_u32 s41, s41, 0x100
	s_addc_u32 s42, s42, 0
	s_add_u32 s4, s4, 0x100
	s_addc_u32 s5, s5, 0
	s_waitcnt vmcnt(6)
	s_setprio 1
	s_barrier
; __device__ __forceinline__ size_t pidx(size_t row, int col) { return ((size_t)(col >> 8) * MTOK + row) * PLD + (col & 255); }
; __device__ __forceinline__ float bflo(unsigned v) { return __uint_as_float(v << 16); }
; __device__ __forceinline__ float bfhi(unsigned v) { return __uint_as_float(v & 0xffff0000u); }
; __device__ __forceinline__ float siluf_(float x) { return x * __builtin_amdgcn_rcpf(1.0f + __expf(-x)); }
;   __device__ __forceinline__ void operator()(EPI_ARGS) const {
;     const size_t row0 = (size_t)u.pm * 256 + wr * 64 + fr;
;     const int col0 = u.pn * 256 + wc * 32 + 8 * fq;
; #pragma unroll
;     for (int bj = 0; bj < 2; ++bj) {
;       const int c = col0 + bj * HALF;
;       const f32x4 s0 = *(const f32x4*)(psc + c), s1 = *(const f32x4*)(psc + c + 4);
; #pragma unroll
;       for (int ai = 0; ai < 2; ++ai) {
;         u32x4 z[4];
; #pragma unroll
;         for (int m = 0; m < 4; ++m) z[m] = *(const u32x4*)(proj + pidx(row0 + ai * HALF + m * 16, PZ + c));
;         __builtin_amdgcn_sched_barrier(0);
; #pragma unroll
;         for (int m = 0; m < 4; ++m) {
;           const size_t row = row0 + ai * HALF + m * 16;
;           const f32x4 v0 = acc[ai][bj][m][0], v1 = acc[ai][bj][m][1];
;           u32x4 o;
;           o.x = pack2(v0[0] * s0[0] * siluf_(bflo(z[m].x)), v0[1] * s0[1] * siluf_(bfhi(z[m].x)));
;           o.y = pack2(v0[2] * s0[2] * siluf_(bflo(z[m].y)), v0[3] * s0[3] * siluf_(bfhi(z[m].y)));
;           o.z = pack2(v1[0] * s1[0] * siluf_(bflo(z[m].z)), v1[1] * s1[1] * siluf_(bfhi(z[m].z)));
;           o.w = pack2(v1[2] * s1[2] * siluf_(bflo(z[m].w)), v1[3] * s1[3] * siluf_(bfhi(z[m].w)));
;           *(u32x4*)(y0 + row * DM + c) = o;
	v_mfma_f32_16x16x32_bf16 v[32:35], v[216:219], v[148:151], v[32:35]
	v_mfma_f32_16x16x32_bf16 v[32:35], v[220:223], v[152:155], v[32:35]
	v_mfma_f32_16x16x32_bf16 v[24:27], v[216:219], v[176:179], v[24:27]
	v_mfma_f32_16x16x32_bf16 v[24:27], v[220:223], v[180:183], v[24:27]
	v_mfma_f32_16x16x32_bf16 v[16:19], v[216:219], v[184:187], v[16:19]
	v_mfma_f32_16x16x32_bf16 v[16:19], v[220:223], v[188:191], v[16:19]
	v_mfma_f32_16x16x32_bf16 v[8:11], v[216:219], v[192:195], v[8:11]
	v_mfma_f32_16x16x32_bf16 v[8:11], v[220:223], v[212:215], v[8:11]
	v_mfma_f32_16x16x32_bf16 v[28:31], v[224:227], v[148:151], v[28:31]
	v_mfma_f32_16x16x32_bf16 v[28:31], v[228:231], v[152:155], v[28:31]
	v_mfma_f32_16x16x32_bf16 v[20:23], v[224:227], v[176:179], v[20:23]
	v_mfma_f32_16x16x32_bf16 v[20:23], v[228:231], v[180:183], v[20:23]
	v_mfma_f32_16x16x32_bf16 v[12:15], v[224:227], v[184:187], v[12:15]
	v_mfma_f32_16x16x32_bf16 v[12:15], v[228:231], v[188:191], v[12:15]
	v_mfma_f32_16x16x32_bf16 v[4:7], v[224:227], v[192:195], v[4:7]
	v_mfma_f32_16x16x32_bf16 v[4:7], v[228:231], v[212:215], v[4:7]
	s_barrier
	s_setprio 0
	s_cmp_gt_u32 s43, 5
	s_cbranch_scc0 .LBB0_485
	s_ashr_i32 s3, s2, 31
	s_lshl_b64 s[2:3], s[2:3], 8
	v_lshl_add_u64 v[186:187], s[2:3], 0, v[162:163]
	s_lshl_b32 s2, s33, 8
	v_or_b32_e32 v196, s2, v168
	s_addk_i32 s2, 0x800
	s_ashr_i32 s2, s2, 8
	s_ashr_i32 s3, s2, 31
	s_lshl_b64 s[2:3], s[2:3], 23
	s_add_u32 s2, s0, s2
	s_addc_u32 s3, s1, s3
	v_lshlrev_b32_e32 v2, 1, v168
	v_or_b32_e32 v194, 16, v186
	v_mov_b32_e32 v195, v187
	v_ashrrev_i32_e32 v197, 31, v196
	v_lshl_add_u64 v[188:189], s[2:3], 0, v[2:3]
	v_lshlrev_b64 v[178:179], 9, v[186:187]
	v_lshlrev_b64 v[180:181], 9, v[194:195]
	v_or_b32_e32 v192, 32, v186
	v_mov_b32_e32 v193, v187
	v_or_b32_e32 v190, 48, v186
	v_mov_b32_e32 v191, v187
	v_lshl_add_u64 v[176:177], v[196:197], 2, s[12:13]
	v_lshl_add_u64 v[132:133], v[188:189], 0, v[178:179]
	v_lshl_add_u64 v[134:135], v[188:189], 0, v[180:181]
	v_lshlrev_b64 v[182:183], 9, v[192:193]
	v_lshlrev_b64 v[184:185], 9, v[190:191]
	global_load_dwordx4 v[92:95], v[176:177], off offset:16
	global_load_dwordx4 v[100:103], v[176:177], off
	flat_load_dwordx4 v[152:155], v[132:133]
	flat_load_dwordx4 v[148:151], v[134:135]
	v_lshl_add_u64 v[132:133], v[188:189], 0, v[182:183]
	v_lshl_add_u64 v[134:135], v[188:189], 0, v[184:185]
	flat_load_dwordx4 v[144:147], v[132:133]
	s_nop 0
	flat_load_dwordx4 v[132:135], v[134:135]
	s_waitcnt vmcnt(0) lgkmcnt(0)
	v_lshlrev_b32_e32 v213, 16, v152
	v_mul_f32_e32 v2, 0xbfb8aa3b, v213
	v_exp_f32_e32 v2, v2
	v_mov_b32_e32 v214, v140
	v_mov_b32_e32 v212, v100
	s_mov_b64 s[4:5], 0x90
	v_add_f32_e32 v2, 1.0, v2
	v_rcp_f32_e32 v215, v2
	s_nop 0
	v_pk_mul_f32 v[212:213], v[214:215], v[212:213]
	s_nop 0
	v_mul_f32_e32 v2, v212, v213
	v_and_b32_e32 v213, 0xffff0000, v152
	v_mul_f32_e32 v140, 0xbfb8aa3b, v213
	v_exp_f32_e32 v140, v140
	v_mov_b32_e32 v214, v141
	v_mov_b32_e32 v212, v101
	v_add_f32_e32 v140, 1.0, v140
	v_rcp_f32_e32 v215, v140
	s_nop 0
	v_pk_mul_f32 v[140:141], v[214:215], v[212:213]
	s_nop 0
	v_mul_f32_e32 v140, v140, v141
	v_lshlrev_b32_e32 v141, 16, v153
	v_cvt_pk_bf16_f32 v152, v2, v140
	v_mul_f32_e32 v2, 0xbfb8aa3b, v141
	v_exp_f32_e32 v2, v2
	v_mov_b32_e32 v212, v142
	v_mov_b32_e32 v140, v102
	v_mov_b32_e32 v142, v136
	v_add_f32_e32 v2, 1.0, v2
	v_rcp_f32_e32 v213, v2
	s_nop 0
	v_pk_mul_f32 v[140:141], v[212:213], v[140:141]
	s_nop 0
	v_mul_f32_e32 v2, v140, v141
	v_and_b32_e32 v141, 0xffff0000, v153
	v_mul_f32_e32 v140, 0xbfb8aa3b, v141
	v_exp_f32_e32 v140, v140
	v_mov_b32_e32 v212, v143
	v_add_f32_e32 v140, 1.0, v140
	v_rcp_f32_e32 v213, v140
	v_mov_b32_e32 v140, v103
	v_pk_mul_f32 v[140:141], v[212:213], v[140:141]
	s_nop 0
	v_mul_f32_e32 v140, v140, v141
	v_lshlrev_b32_e32 v141, 16, v154
	v_cvt_pk_bf16_f32 v153, v2, v140
	v_mul_f32_e32 v2, 0xbfb8aa3b, v141
	v_exp_f32_e32 v2, v2
	v_mov_b32_e32 v140, v92
	v_add_f32_e32 v2, 1.0, v2
	v_rcp_f32_e32 v143, v2
	s_nop 0
	v_pk_mul_f32 v[140:141], v[142:143], v[140:141]
	s_nop 0
	v_mul_f32_e32 v2, v140, v141
	v_and_b32_e32 v141, 0xffff0000, v154
	v_mul_f32_e32 v136, 0xbfb8aa3b, v141
	v_exp_f32_e32 v136, v136
	v_mov_b32_e32 v142, v137
	v_mov_b32_e32 v140, v93
	v_add_f32_e32 v136, 1.0, v136
	v_rcp_f32_e32 v143, v136
	s_nop 0
	v_pk_mul_f32 v[136:137], v[142:143], v[140:141]
	s_nop 0
	v_mul_f32_e32 v136, v136, v137
	v_lshlrev_b32_e32 v137, 16, v155
	v_cvt_pk_bf16_f32 v154, v2, v136
	v_mul_f32_e32 v2, 0xbfb8aa3b, v137
	v_exp_f32_e32 v2, v2
	v_mov_b32_e32 v140, v138
	v_mov_b32_e32 v136, v94
	v_mov_b32_e32 v142, v128
	v_add_f32_e32 v2, 1.0, v2
	v_rcp_f32_e32 v141, v2
	v_mov_b32_e32 v138, v100
	v_pk_mul_f32 v[136:137], v[140:141], v[136:137]
	s_nop 0
	v_mul_f32_e32 v2, v136, v137
	v_and_b32_e32 v137, 0xffff0000, v155
	v_mul_f32_e32 v136, 0xbfb8aa3b, v137
	v_exp_f32_e32 v136, v136
	v_mov_b32_e32 v140, v139
	v_lshlrev_b32_e32 v139, 16, v148
	v_add_f32_e32 v136, 1.0, v136
	v_rcp_f32_e32 v141, v136
	v_mov_b32_e32 v136, v95
	v_pk_mul_f32 v[136:137], v[140:141], v[136:137]
	s_nop 0
	v_mul_f32_e32 v136, v136, v137
	v_cvt_pk_bf16_f32 v155, v2, v136
	v_mul_f32_e32 v2, 0xbfb8aa3b, v139
	v_exp_f32_e32 v2, v2
	v_lshlrev_b64 v[140:141], 1, v[196:197]
	v_lshlrev_b64 v[136:137], 12, v[186:187]
	v_lshl_add_u64 v[136:137], s[8:9], 0, v[136:137]
	v_add_f32_e32 v2, 1.0, v2
	v_rcp_f32_e32 v143, v2
	v_lshl_add_u64 v[136:137], v[136:137], 0, v[140:141]
	flat_store_dwordx4 v[136:137], v[152:155]
	v_pk_mul_f32 v[138:139], v[142:143], v[138:139]
	s_nop 0
	v_mul_f32_e32 v2, v138, v139
	v_and_b32_e32 v139, 0xffff0000, v148
	v_mul_f32_e32 v128, 0xbfb8aa3b, v139
	v_exp_f32_e32 v128, v128
; __device__ __forceinline__ size_t pidx(size_t row, int col) { return ((size_t)(col >> 8) * MTOK + row) * PLD + (col & 255); }
; __device__ __forceinline__ float bflo(unsigned v) { return __uint_as_float(v << 16); }
; __device__ __forceinline__ float bfhi(unsigned v) { return __uint_as_float(v & 0xffff0000u); }
; __device__ __forceinline__ float siluf_(float x) { return x * __builtin_amdgcn_rcpf(1.0f + __expf(-x)); }
;   __device__ __forceinline__ void operator()(EPI_ARGS) const {
;     ...
;         for (int m = 0; m < 4; ++m) z[m] = *(const u32x4*)(proj + pidx(row0 + ai * HALF + m * 16, PZ + c));
;         __builtin_amdgcn_sched_barrier(0);
; #pragma unroll
;         for (int m = 0; m < 4; ++m) {
;           const size_t row = row0 + ai * HALF + m * 16;
;           const f32x4 v0 = acc[ai][bj][m][0], v1 = acc[ai][bj][m][1];
;           u32x4 o;
;           o.x = pack2(v0[0] * s0[0] * siluf_(bflo(z[m].x)), v0[1] * s0[1] * siluf_(bfhi(z[m].x)));
;           o.y = pack2(v0[2] * s0[2] * siluf_(bflo(z[m].y)), v0[3] * s0[3] * siluf_(bfhi(z[m].y)));
;           o.z = pack2(v1[0] * s1[0] * siluf_(bflo(z[m].z)), v1[1] * s1[1] * siluf_(bfhi(z[m].z)));
;           o.w = pack2(v1[2] * s1[2] * siluf_(bflo(z[m].w)), v1[3] * s1[3] * siluf_(bfhi(z[m].w)));
;           *(u32x4*)(y0 + row * DM + c) = o;
	v_mov_b32_e32 v142, v129
	v_mov_b32_e32 v138, v101
	v_add_f32_e32 v128, 1.0, v128
	v_rcp_f32_e32 v143, v128
	s_nop 0
	v_pk_mul_f32 v[128:129], v[142:143], v[138:139]
	s_nop 0
	v_mul_f32_e32 v128, v128, v129
	v_lshlrev_b32_e32 v139, 16, v149
	v_cvt_pk_bf16_f32 v128, v2, v128
	v_mul_f32_e32 v2, 0xbfb8aa3b, v139
	v_exp_f32_e32 v2, v2
	v_mov_b32_e32 v142, v130
	v_mov_b32_e32 v138, v102
	v_add_f32_e32 v2, 1.0, v2
	v_rcp_f32_e32 v143, v2
	s_nop 0
	v_pk_mul_f32 v[138:139], v[142:143], v[138:139]
	s_nop 0
	v_mul_f32_e32 v2, v138, v139
	v_and_b32_e32 v139, 0xffff0000, v149
	v_mul_f32_e32 v129, 0xbfb8aa3b, v139
	v_exp_f32_e32 v129, v129
	v_mov_b32_e32 v142, v131
	v_mov_b32_e32 v138, v103
	v_lshl_add_u64 v[148:149], v[186:187], 0, s[52:53]
	v_add_f32_e32 v129, 1.0, v129
	v_rcp_f32_e32 v143, v129
	s_nop 0
	v_pk_mul_f32 v[130:131], v[142:143], v[138:139]
	s_nop 0
	v_mul_f32_e32 v129, v130, v131
	v_lshlrev_b32_e32 v131, 16, v150
	v_cvt_pk_bf16_f32 v129, v2, v129
	v_mul_f32_e32 v2, 0xbfb8aa3b, v131
	v_exp_f32_e32 v2, v2
	v_mov_b32_e32 v138, v124
	v_mov_b32_e32 v130, v92
	v_add_f32_e32 v2, 1.0, v2
	v_rcp_f32_e32 v139, v2
	s_nop 0
	v_pk_mul_f32 v[130:131], v[138:139], v[130:131]
	s_nop 0
	v_mul_f32_e32 v2, v130, v131
	v_and_b32_e32 v131, 0xffff0000, v150
	v_mul_f32_e32 v124, 0xbfb8aa3b, v131
	v_exp_f32_e32 v124, v124
	v_mov_b32_e32 v138, v125
	v_mov_b32_e32 v130, v93
	v_add_f32_e32 v124, 1.0, v124
	v_rcp_f32_e32 v139, v124
	s_nop 0
	v_pk_mul_f32 v[124:125], v[138:139], v[130:131]
	s_nop 0
	v_mul_f32_e32 v124, v124, v125
	v_lshlrev_b32_e32 v125, 16, v151
	v_cvt_pk_bf16_f32 v130, v2, v124
	v_mul_f32_e32 v2, 0xbfb8aa3b, v125
	v_exp_f32_e32 v2, v2
	v_mov_b32_e32 v138, v126
	v_mov_b32_e32 v124, v94
	v_mov_b32_e32 v126, v100
	v_add_f32_e32 v2, 1.0, v2
	v_rcp_f32_e32 v139, v2
	s_nop 0
	v_pk_mul_f32 v[124:125], v[138:139], v[124:125]
	s_nop 0
	v_mul_f32_e32 v2, v124, v125
	v_and_b32_e32 v125, 0xffff0000, v151
	v_mul_f32_e32 v124, 0xbfb8aa3b, v125
	v_exp_f32_e32 v124, v124
	v_mov_b32_e32 v138, v127
	v_lshlrev_b32_e32 v127, 16, v144
	v_add_f32_e32 v124, 1.0, v124
	v_rcp_f32_e32 v139, v124
	v_mov_b32_e32 v124, v95
	v_pk_mul_f32 v[124:125], v[138:139], v[124:125]
	s_nop 0
	v_mul_f32_e32 v124, v124, v125
	v_cvt_pk_bf16_f32 v131, v2, v124
	v_mul_f32_e32 v2, 0xbfb8aa3b, v127
	v_exp_f32_e32 v2, v2
	v_lshlrev_b64 v[124:125], 12, v[194:195]
	v_lshl_add_u64 v[124:125], s[8:9], 0, v[124:125]
	v_lshl_add_u64 v[124:125], v[124:125], 0, v[140:141]
	v_add_f32_e32 v2, 1.0, v2
	flat_store_dwordx4 v[124:125], v[128:131]
	s_nop 1
	v_rcp_f32_e32 v129, v2
	v_mov_b32_e32 v128, v120
	v_lshlrev_b64 v[130:131], 9, v[148:149]
	v_pk_mul_f32 v[126:127], v[128:129], v[126:127]
	s_nop 0
	v_mul_f32_e32 v2, v126, v127
	v_and_b32_e32 v127, 0xffff0000, v144
	v_mul_f32_e32 v120, 0xbfb8aa3b, v127
	v_exp_f32_e32 v120, v120
	v_mov_b32_e32 v128, v121
	v_mov_b32_e32 v126, v101
	v_add_f32_e32 v120, 1.0, v120
	v_rcp_f32_e32 v129, v120
	s_nop 0
	v_pk_mul_f32 v[120:121], v[128:129], v[126:127]
	s_nop 0
	v_mul_f32_e32 v120, v120, v121
	v_lshlrev_b32_e32 v127, 16, v145
	v_cvt_pk_bf16_f32 v120, v2, v120
	v_mul_f32_e32 v2, 0xbfb8aa3b, v127
	v_exp_f32_e32 v2, v2
	v_mov_b32_e32 v128, v122
	v_mov_b32_e32 v126, v102
	v_add_f32_e32 v2, 1.0, v2
	v_rcp_f32_e32 v129, v2
	s_nop 0
	v_pk_mul_f32 v[126:127], v[128:129], v[126:127]
	s_nop 0
	v_mul_f32_e32 v2, v126, v127
	v_and_b32_e32 v127, 0xffff0000, v145
	v_mul_f32_e32 v121, 0xbfb8aa3b, v127
	v_exp_f32_e32 v121, v121
	v_mov_b32_e32 v128, v123
	v_mov_b32_e32 v126, v103
	v_add_f32_e32 v121, 1.0, v121
	v_rcp_f32_e32 v129, v121
	s_nop 0
	v_pk_mul_f32 v[122:123], v[128:129], v[126:127]
	s_nop 0
	v_mul_f32_e32 v121, v122, v123
	v_lshlrev_b32_e32 v123, 16, v146
	v_cvt_pk_bf16_f32 v121, v2, v121
	v_mul_f32_e32 v2, 0xbfb8aa3b, v123
	v_exp_f32_e32 v2, v2
	v_mov_b32_e32 v126, v116
	v_mov_b32_e32 v122, v92
	v_add_f32_e32 v2, 1.0, v2
	v_rcp_f32_e32 v127, v2
	s_nop 0
	v_pk_mul_f32 v[122:123], v[126:127], v[122:123]
	s_nop 0
	v_mul_f32_e32 v2, v122, v123
	v_and_b32_e32 v123, 0xffff0000, v146
	v_mul_f32_e32 v116, 0xbfb8aa3b, v123
	v_exp_f32_e32 v116, v116
	v_mov_b32_e32 v126, v117
	v_mov_b32_e32 v122, v93
	v_add_f32_e32 v116, 1.0, v116
	v_rcp_f32_e32 v127, v116
	s_nop 0
	v_pk_mul_f32 v[116:117], v[126:127], v[122:123]
	s_nop 0
	v_mul_f32_e32 v116, v116, v117
	v_lshlrev_b32_e32 v117, 16, v147
	v_cvt_pk_bf16_f32 v122, v2, v116
	v_mul_f32_e32 v2, 0xbfb8aa3b, v117
	v_exp_f32_e32 v2, v2
	v_mov_b32_e32 v126, v118
	v_mov_b32_e32 v116, v94
	v_mov_b32_e32 v118, v112
	v_add_f32_e32 v2, 1.0, v2
	v_rcp_f32_e32 v127, v2
	s_nop 0
	v_pk_mul_f32 v[116:117], v[126:127], v[116:117]
	s_nop 0
	v_mul_f32_e32 v2, v116, v117
	v_and_b32_e32 v117, 0xffff0000, v147
	v_mul_f32_e32 v116, 0xbfb8aa3b, v117
	v_exp_f32_e32 v116, v116
	v_mov_b32_e32 v126, v119
	v_lshl_add_u64 v[146:147], v[186:187], 0, s[4:5]
	s_mov_b64 s[4:5], 0xa0
	v_add_f32_e32 v116, 1.0, v116
	v_rcp_f32_e32 v127, v116
	v_mov_b32_e32 v116, v95
	v_lshl_add_u64 v[144:145], v[186:187], 0, s[4:5]
	s_mov_b64 s[4:5], 0xb0
	v_pk_mul_f32 v[116:117], v[126:127], v[116:117]
	v_lshl_add_u64 v[142:143], v[186:187], 0, s[4:5]
	v_mul_f32_e32 v116, v116, v117
	v_cvt_pk_bf16_f32 v123, v2, v116
	v_lshlrev_b64 v[116:117], 12, v[192:193]
	v_lshl_add_u64 v[116:117], s[8:9], 0, v[116:117]
	v_lshl_add_u64 v[128:129], v[116:117], 0, v[140:141]
	v_lshlrev_b32_e32 v117, 16, v132
	v_mul_f32_e32 v2, 0xbfb8aa3b, v117
	v_exp_f32_e32 v2, v2
	v_mov_b32_e32 v116, v100
	flat_store_dwordx4 v[128:129], v[120:123]
	v_lshlrev_b64 v[138:139], 9, v[142:143]
	v_add_f32_e32 v2, 1.0, v2
	v_rcp_f32_e32 v119, v2
	s_nop 0
	v_pk_mul_f32 v[116:117], v[118:119], v[116:117]
	s_nop 0
; __device__ __forceinline__ size_t pidx(size_t row, int col) { return ((size_t)(col >> 8) * MTOK + row) * PLD + (col & 255); }
; __device__ __forceinline__ float bflo(unsigned v) { return __uint_as_float(v << 16); }
; __device__ __forceinline__ float bfhi(unsigned v) { return __uint_as_float(v & 0xffff0000u); }
; __device__ __forceinline__ float siluf_(float x) { return x * __builtin_amdgcn_rcpf(1.0f + __expf(-x)); }
;   __device__ __forceinline__ void operator()(EPI_ARGS) const {
;     ...
;         for (int m = 0; m < 4; ++m) z[m] = *(const u32x4*)(proj + pidx(row0 + ai * HALF + m * 16, PZ + c));
;         __builtin_amdgcn_sched_barrier(0);
; #pragma unroll
;         for (int m = 0; m < 4; ++m) {
;           const size_t row = row0 + ai * HALF + m * 16;
;           const f32x4 v0 = acc[ai][bj][m][0], v1 = acc[ai][bj][m][1];
;           u32x4 o;
;           o.x = pack2(v0[0] * s0[0] * siluf_(bflo(z[m].x)), v0[1] * s0[1] * siluf_(bfhi(z[m].x)));
;           o.y = pack2(v0[2] * s0[2] * siluf_(bflo(z[m].y)), v0[3] * s0[3] * siluf_(bfhi(z[m].y)));
;           o.z = pack2(v1[0] * s1[0] * siluf_(bflo(z[m].z)), v1[1] * s1[1] * siluf_(bfhi(z[m].z)));
;           o.w = pack2(v1[2] * s1[2] * siluf_(bflo(z[m].w)), v1[3] * s1[3] * siluf_(bfhi(z[m].w)));
;           *(u32x4*)(y0 + row * DM + c) = o;
	v_mul_f32_e32 v2, v116, v117
	v_and_b32_e32 v117, 0xffff0000, v132
	v_mul_f32_e32 v112, 0xbfb8aa3b, v117
	v_exp_f32_e32 v112, v112
	v_mov_b32_e32 v118, v113
	v_mov_b32_e32 v116, v101
	v_add_f32_e32 v112, 1.0, v112
	v_rcp_f32_e32 v119, v112
	s_nop 0
	v_pk_mul_f32 v[112:113], v[118:119], v[116:117]
	s_nop 0
	v_mul_f32_e32 v112, v112, v113
	v_lshlrev_b32_e32 v117, 16, v133
	v_cvt_pk_bf16_f32 v112, v2, v112
	v_mul_f32_e32 v2, 0xbfb8aa3b, v117
	v_exp_f32_e32 v2, v2
	v_mov_b32_e32 v118, v114
	v_mov_b32_e32 v116, v102
	v_add_f32_e32 v2, 1.0, v2
	v_rcp_f32_e32 v119, v2
	s_nop 0
	v_pk_mul_f32 v[116:117], v[118:119], v[116:117]
	s_nop 0
	v_mul_f32_e32 v2, v116, v117
	v_and_b32_e32 v117, 0xffff0000, v133
	v_mul_f32_e32 v113, 0xbfb8aa3b, v117
	v_exp_f32_e32 v113, v113
	v_mov_b32_e32 v118, v115
	v_mov_b32_e32 v116, v103
	v_lshlrev_b64 v[132:133], 9, v[146:147]
	v_add_f32_e32 v113, 1.0, v113
	v_rcp_f32_e32 v119, v113
	s_nop 0
	v_pk_mul_f32 v[114:115], v[118:119], v[116:117]
	s_nop 0
	v_mul_f32_e32 v113, v114, v115
	v_lshlrev_b32_e32 v115, 16, v134
	v_cvt_pk_bf16_f32 v113, v2, v113
	v_mul_f32_e32 v2, 0xbfb8aa3b, v115
	v_exp_f32_e32 v2, v2
	v_mov_b32_e32 v116, v108
	v_mov_b32_e32 v114, v92
	v_add_f32_e32 v2, 1.0, v2
	v_rcp_f32_e32 v117, v2
	s_nop 0
	v_pk_mul_f32 v[114:115], v[116:117], v[114:115]
	s_nop 0
	v_mul_f32_e32 v2, v114, v115
	v_and_b32_e32 v115, 0xffff0000, v134
	v_mul_f32_e32 v108, 0xbfb8aa3b, v115
	v_exp_f32_e32 v108, v108
	v_mov_b32_e32 v116, v109
	v_mov_b32_e32 v114, v93
	v_add_f32_e32 v108, 1.0, v108
	v_rcp_f32_e32 v117, v108
	s_nop 0
	v_pk_mul_f32 v[108:109], v[116:117], v[114:115]
	s_nop 0
	v_mul_f32_e32 v108, v108, v109
	v_lshlrev_b32_e32 v109, 16, v135
	v_cvt_pk_bf16_f32 v114, v2, v108
	v_mul_f32_e32 v2, 0xbfb8aa3b, v109
	v_exp_f32_e32 v2, v2
	v_mov_b32_e32 v116, v110
	v_mov_b32_e32 v108, v94
	v_add_f32_e32 v2, 1.0, v2
	v_rcp_f32_e32 v117, v2
	s_nop 0
	v_pk_mul_f32 v[108:109], v[116:117], v[108:109]
	s_nop 0
	v_mul_f32_e32 v2, v108, v109
	v_and_b32_e32 v109, 0xffff0000, v135
	v_mul_f32_e32 v108, 0xbfb8aa3b, v109
	v_exp_f32_e32 v108, v108
	v_mov_b32_e32 v116, v111
	v_lshlrev_b64 v[134:135], 9, v[144:145]
	v_add_f32_e32 v108, 1.0, v108
	v_rcp_f32_e32 v117, v108
	v_mov_b32_e32 v108, v95
	v_pk_mul_f32 v[108:109], v[116:117], v[108:109]
	s_nop 0
	v_mul_f32_e32 v108, v108, v109
	v_cvt_pk_bf16_f32 v115, v2, v108
	v_lshlrev_b64 v[108:109], 12, v[190:191]
	v_lshl_add_u64 v[108:109], s[8:9], 0, v[108:109]
	v_lshl_add_u64 v[126:127], v[108:109], 0, v[140:141]
	flat_store_dwordx4 v[126:127], v[112:115]
	v_lshl_add_u64 v[108:109], v[188:189], 0, v[130:131]
	flat_load_dwordx4 v[120:123], v[108:109]
	v_lshl_add_u64 v[108:109], v[188:189], 0, v[132:133]
	flat_load_dwordx4 v[116:119], v[108:109]
	v_lshl_add_u64 v[108:109], v[188:189], 0, v[134:135]
	flat_load_dwordx4 v[112:115], v[108:109]
	v_lshl_add_u64 v[108:109], v[188:189], 0, v[138:139]
	flat_load_dwordx4 v[108:111], v[108:109]
	s_waitcnt vmcnt(0) lgkmcnt(0)
	v_lshlrev_b32_e32 v151, 16, v120
	v_mul_f32_e32 v2, 0xbfb8aa3b, v151
	v_exp_f32_e32 v2, v2
	v_mov_b32_e32 v152, v104
	v_mov_b32_e32 v150, v100
	v_mov_b32_e32 v175, v3
	v_add_f32_e32 v2, 1.0, v2
	v_rcp_f32_e32 v153, v2
	s_nop 0
	v_pk_mul_f32 v[150:151], v[152:153], v[150:151]
	s_nop 0
	v_mul_f32_e32 v2, v150, v151
	v_and_b32_e32 v151, 0xffff0000, v120
	v_mul_f32_e32 v104, 0xbfb8aa3b, v151
	v_exp_f32_e32 v104, v104
	v_mov_b32_e32 v152, v105
	v_mov_b32_e32 v150, v101
	v_mov_b32_e32 v120, v103
	v_add_f32_e32 v104, 1.0, v104
	v_rcp_f32_e32 v153, v104
	s_nop 0
	v_pk_mul_f32 v[104:105], v[152:153], v[150:151]
	s_nop 0
	v_mul_f32_e32 v104, v104, v105
	v_lshlrev_b32_e32 v151, 16, v121
	v_cvt_pk_bf16_f32 v104, v2, v104
	v_mul_f32_e32 v2, 0xbfb8aa3b, v151
	v_exp_f32_e32 v2, v2
	v_and_b32_e32 v121, 0xffff0000, v121
	v_mul_f32_e32 v105, 0xbfb8aa3b, v121
	v_exp_f32_e32 v105, v105
	v_add_f32_e32 v2, 1.0, v2
	v_rcp_f32_e32 v153, v2
	v_mov_b32_e32 v152, v106
	v_mov_b32_e32 v150, v102
	v_add_f32_e32 v105, 1.0, v105
	v_pk_mul_f32 v[150:151], v[152:153], v[150:151]
	s_nop 0
	v_mul_f32_e32 v2, v150, v151
	v_rcp_f32_e32 v151, v105
	v_mov_b32_e32 v150, v107
	v_pk_mul_f32 v[106:107], v[150:151], v[120:121]
	s_nop 0
	v_mul_f32_e32 v105, v106, v107
	v_lshlrev_b32_e32 v107, 16, v122
	v_cvt_pk_bf16_f32 v105, v2, v105
	v_mul_f32_e32 v2, 0xbfb8aa3b, v107
	v_exp_f32_e32 v2, v2
	v_mov_b32_e32 v120, v96
	v_mov_b32_e32 v106, v92
	v_add_f32_e32 v2, 1.0, v2
	v_rcp_f32_e32 v121, v2
	s_nop 0
	v_pk_mul_f32 v[106:107], v[120:121], v[106:107]
	s_nop 0
	v_mul_f32_e32 v2, v106, v107
	v_and_b32_e32 v107, 0xffff0000, v122
	v_mul_f32_e32 v96, 0xbfb8aa3b, v107
	v_exp_f32_e32 v96, v96
	v_mov_b32_e32 v120, v97
	v_mov_b32_e32 v106, v93
	v_add_f32_e32 v96, 1.0, v96
	v_rcp_f32_e32 v121, v96
	s_nop 0
	v_pk_mul_f32 v[96:97], v[120:121], v[106:107]
	s_nop 0
	v_mul_f32_e32 v96, v96, v97
	v_lshlrev_b32_e32 v97, 16, v123
	v_cvt_pk_bf16_f32 v106, v2, v96
	v_mul_f32_e32 v2, 0xbfb8aa3b, v97
	v_exp_f32_e32 v2, v2
	v_mov_b32_e32 v120, v98
	v_mov_b32_e32 v96, v94
	v_mov_b32_e32 v98, v100
	v_add_f32_e32 v2, 1.0, v2
	v_rcp_f32_e32 v121, v2
	s_nop 0
	v_pk_mul_f32 v[96:97], v[120:121], v[96:97]
	s_nop 0
	v_mul_f32_e32 v2, v96, v97
	v_and_b32_e32 v97, 0xffff0000, v123
	v_mul_f32_e32 v96, 0xbfb8aa3b, v97
	v_exp_f32_e32 v96, v96
	v_mov_b32_e32 v120, v99
	v_lshlrev_b32_e32 v99, 16, v116
	v_add_f32_e32 v96, 1.0, v96
	v_rcp_f32_e32 v121, v96
	v_mov_b32_e32 v96, v95
	v_pk_mul_f32 v[96:97], v[120:121], v[96:97]
	s_nop 0
	v_mul_f32_e32 v96, v96, v97
	v_cvt_pk_bf16_f32 v107, v2, v96
	v_mul_f32_e32 v2, 0xbfb8aa3b, v99
	v_exp_f32_e32 v2, v2
	v_lshlrev_b64 v[96:97], 12, v[148:149]
	v_lshl_add_u64 v[96:97], s[8:9], 0, v[96:97]
; __device__ __forceinline__ size_t pidx(size_t row, int col) { return ((size_t)(col >> 8) * MTOK + row) * PLD + (col & 255); }
; __device__ __forceinline__ float bflo(unsigned v) { return __uint_as_float(v << 16); }
; __device__ __forceinline__ float bfhi(unsigned v) { return __uint_as_float(v & 0xffff0000u); }
; __device__ __forceinline__ float siluf_(float x) { return x * __builtin_amdgcn_rcpf(1.0f + __expf(-x)); }
;   __device__ __forceinline__ void operator()(EPI_ARGS) const {
;     ...
;         for (int m = 0; m < 4; ++m) z[m] = *(const u32x4*)(proj + pidx(row0 + ai * HALF + m * 16, PZ + c));
;         __builtin_amdgcn_sched_barrier(0);
; #pragma unroll
;         for (int m = 0; m < 4; ++m) {
;           const size_t row = row0 + ai * HALF + m * 16;
;           const f32x4 v0 = acc[ai][bj][m][0], v1 = acc[ai][bj][m][1];
;           u32x4 o;
;           o.x = pack2(v0[0] * s0[0] * siluf_(bflo(z[m].x)), v0[1] * s0[1] * siluf_(bfhi(z[m].x)));
;           o.y = pack2(v0[2] * s0[2] * siluf_(bflo(z[m].y)), v0[3] * s0[3] * siluf_(bfhi(z[m].y)));
;           o.z = pack2(v1[0] * s1[0] * siluf_(bflo(z[m].z)), v1[1] * s1[1] * siluf_(bfhi(z[m].z)));
;           o.w = pack2(v1[2] * s1[2] * siluf_(bflo(z[m].w)), v1[3] * s1[3] * siluf_(bfhi(z[m].w)));
;           *(u32x4*)(y0 + row * DM + c) = o;
	v_lshl_add_u64 v[96:97], v[96:97], 0, v[140:141]
	v_add_f32_e32 v2, 1.0, v2
	flat_store_dwordx4 v[96:97], v[104:107]
	s_nop 1
	v_rcp_f32_e32 v105, v2
	v_mov_b32_e32 v104, v88
	v_pk_mul_f32 v[98:99], v[104:105], v[98:99]
	s_nop 0
	v_mul_f32_e32 v2, v98, v99
	v_and_b32_e32 v99, 0xffff0000, v116
	v_mul_f32_e32 v88, 0xbfb8aa3b, v99
	v_exp_f32_e32 v88, v88
	v_mov_b32_e32 v104, v89
	v_mov_b32_e32 v98, v101
	v_add_f32_e32 v88, 1.0, v88
	v_rcp_f32_e32 v105, v88
	s_nop 0
	v_pk_mul_f32 v[88:89], v[104:105], v[98:99]
	s_nop 0
	v_mul_f32_e32 v88, v88, v89
	v_lshlrev_b32_e32 v99, 16, v117
	v_cvt_pk_bf16_f32 v88, v2, v88
	v_mul_f32_e32 v2, 0xbfb8aa3b, v99
	v_exp_f32_e32 v2, v2
	v_mov_b32_e32 v104, v90
	v_mov_b32_e32 v98, v102
	v_add_f32_e32 v2, 1.0, v2
	v_rcp_f32_e32 v105, v2
	s_nop 0
	v_pk_mul_f32 v[98:99], v[104:105], v[98:99]
	s_nop 0
	v_mul_f32_e32 v2, v98, v99
	v_and_b32_e32 v99, 0xffff0000, v117
	v_mul_f32_e32 v89, 0xbfb8aa3b, v99
	v_exp_f32_e32 v89, v89
	v_mov_b32_e32 v104, v91
	v_mov_b32_e32 v98, v103
	v_add_f32_e32 v89, 1.0, v89
	v_rcp_f32_e32 v105, v89
	s_nop 0
	v_pk_mul_f32 v[90:91], v[104:105], v[98:99]
	s_nop 0
	v_mul_f32_e32 v89, v90, v91
	v_lshlrev_b32_e32 v91, 16, v118
	v_cvt_pk_bf16_f32 v89, v2, v89
	v_mul_f32_e32 v2, 0xbfb8aa3b, v91
	v_exp_f32_e32 v2, v2
	v_mov_b32_e32 v98, v84
	v_mov_b32_e32 v90, v92
	v_add_f32_e32 v2, 1.0, v2
	v_rcp_f32_e32 v99, v2
	s_nop 0
	v_pk_mul_f32 v[90:91], v[98:99], v[90:91]
	s_nop 0
	v_mul_f32_e32 v2, v90, v91
	v_and_b32_e32 v91, 0xffff0000, v118
	v_mul_f32_e32 v84, 0xbfb8aa3b, v91
	v_exp_f32_e32 v84, v84
	v_mov_b32_e32 v98, v85
	v_mov_b32_e32 v90, v93
	v_add_f32_e32 v84, 1.0, v84
	v_rcp_f32_e32 v99, v84
	s_nop 0
	v_pk_mul_f32 v[84:85], v[98:99], v[90:91]
	s_nop 0
	v_mul_f32_e32 v84, v84, v85
	v_lshlrev_b32_e32 v85, 16, v119
	v_cvt_pk_bf16_f32 v90, v2, v84
	v_mul_f32_e32 v2, 0xbfb8aa3b, v85
	v_exp_f32_e32 v2, v2
	v_mov_b32_e32 v98, v86
	v_mov_b32_e32 v84, v94
	v_mov_b32_e32 v86, v80
	v_add_f32_e32 v2, 1.0, v2
	v_rcp_f32_e32 v99, v2
	s_nop 0
	v_pk_mul_f32 v[84:85], v[98:99], v[84:85]
	s_nop 0
	v_mul_f32_e32 v2, v84, v85
	v_and_b32_e32 v85, 0xffff0000, v119
	v_mul_f32_e32 v84, 0xbfb8aa3b, v85
	v_exp_f32_e32 v84, v84
	v_mov_b32_e32 v98, v87
	v_add_f32_e32 v84, 1.0, v84
	v_rcp_f32_e32 v99, v84
	v_mov_b32_e32 v84, v95
	v_pk_mul_f32 v[84:85], v[98:99], v[84:85]
	s_nop 0
	v_mul_f32_e32 v84, v84, v85
	v_cvt_pk_bf16_f32 v91, v2, v84
	v_lshlrev_b64 v[84:85], 12, v[146:147]
	v_lshl_add_u64 v[84:85], s[8:9], 0, v[84:85]
	v_lshl_add_u64 v[98:99], v[84:85], 0, v[140:141]
	v_lshlrev_b32_e32 v85, 16, v112
	v_mul_f32_e32 v2, 0xbfb8aa3b, v85
	v_exp_f32_e32 v2, v2
	v_mov_b32_e32 v84, v100
	flat_store_dwordx4 v[98:99], v[88:91]
	v_add_f32_e32 v2, 1.0, v2
	v_rcp_f32_e32 v87, v2
	s_nop 0
	v_pk_mul_f32 v[84:85], v[86:87], v[84:85]
	s_nop 0
	v_mul_f32_e32 v2, v84, v85
	v_and_b32_e32 v85, 0xffff0000, v112
	v_mul_f32_e32 v80, 0xbfb8aa3b, v85
	v_exp_f32_e32 v80, v80
	v_mov_b32_e32 v86, v81
	v_mov_b32_e32 v84, v101
	v_add_f32_e32 v80, 1.0, v80
	v_rcp_f32_e32 v87, v80
	s_nop 0
	v_pk_mul_f32 v[80:81], v[86:87], v[84:85]
	s_nop 0
	v_mul_f32_e32 v80, v80, v81
	v_lshlrev_b32_e32 v85, 16, v113
	v_cvt_pk_bf16_f32 v80, v2, v80
	v_mul_f32_e32 v2, 0xbfb8aa3b, v85
	v_exp_f32_e32 v2, v2
	v_mov_b32_e32 v86, v82
	v_mov_b32_e32 v84, v102
	v_add_f32_e32 v2, 1.0, v2
	v_rcp_f32_e32 v87, v2
	s_nop 0
	v_pk_mul_f32 v[84:85], v[86:87], v[84:85]
	s_nop 0
	v_mul_f32_e32 v2, v84, v85
	v_and_b32_e32 v85, 0xffff0000, v113
	v_mul_f32_e32 v81, 0xbfb8aa3b, v85
	v_exp_f32_e32 v81, v81
	v_mov_b32_e32 v86, v83
	v_mov_b32_e32 v84, v103
	v_add_f32_e32 v81, 1.0, v81
	v_rcp_f32_e32 v87, v81
	s_nop 0
	v_pk_mul_f32 v[82:83], v[86:87], v[84:85]
	s_nop 0
	v_mul_f32_e32 v81, v82, v83
	v_lshlrev_b32_e32 v83, 16, v114
	v_cvt_pk_bf16_f32 v81, v2, v81
	v_mul_f32_e32 v2, 0xbfb8aa3b, v83
	v_exp_f32_e32 v2, v2
	v_mov_b32_e32 v84, v76
	v_mov_b32_e32 v82, v92
	v_add_f32_e32 v2, 1.0, v2
	v_rcp_f32_e32 v85, v2
	s_nop 0
	v_pk_mul_f32 v[82:83], v[84:85], v[82:83]
	s_nop 0
	v_mul_f32_e32 v2, v82, v83
	v_and_b32_e32 v83, 0xffff0000, v114
	v_mul_f32_e32 v76, 0xbfb8aa3b, v83
	v_exp_f32_e32 v76, v76
	v_mov_b32_e32 v84, v77
	v_mov_b32_e32 v82, v93
	v_add_f32_e32 v76, 1.0, v76
	v_rcp_f32_e32 v85, v76
	s_nop 0
	v_pk_mul_f32 v[76:77], v[84:85], v[82:83]
	s_nop 0
	v_mul_f32_e32 v76, v76, v77
	v_lshlrev_b32_e32 v77, 16, v115
	v_cvt_pk_bf16_f32 v82, v2, v76
	v_mul_f32_e32 v2, 0xbfb8aa3b, v77
	v_exp_f32_e32 v2, v2
	v_mov_b32_e32 v84, v78
	v_mov_b32_e32 v76, v94
	v_mov_b32_e32 v78, v72
	v_add_f32_e32 v2, 1.0, v2
	v_rcp_f32_e32 v85, v2
	s_nop 0
	v_pk_mul_f32 v[76:77], v[84:85], v[76:77]
	s_nop 0
	v_mul_f32_e32 v2, v76, v77
	v_and_b32_e32 v77, 0xffff0000, v115
	v_mul_f32_e32 v76, 0xbfb8aa3b, v77
	v_exp_f32_e32 v76, v76
	v_mov_b32_e32 v84, v79
	v_add_f32_e32 v76, 1.0, v76
	v_rcp_f32_e32 v85, v76
	v_mov_b32_e32 v76, v95
	v_pk_mul_f32 v[76:77], v[84:85], v[76:77]
	s_nop 0
	v_mul_f32_e32 v76, v76, v77
	v_cvt_pk_bf16_f32 v83, v2, v76
	v_lshlrev_b64 v[76:77], 12, v[144:145]
	v_lshl_add_u64 v[76:77], s[8:9], 0, v[76:77]
	v_lshl_add_u64 v[104:105], v[76:77], 0, v[140:141]
	v_lshlrev_b32_e32 v77, 16, v108
	v_mul_f32_e32 v2, 0xbfb8aa3b, v77
	v_exp_f32_e32 v2, v2
	v_mov_b32_e32 v76, v100
	flat_store_dwordx4 v[104:105], v[80:83]
	v_add_f32_e32 v2, 1.0, v2
	v_rcp_f32_e32 v79, v2
	s_nop 0
	v_pk_mul_f32 v[76:77], v[78:79], v[76:77]
	s_nop 0
	v_mul_f32_e32 v2, v76, v77
	v_and_b32_e32 v77, 0xffff0000, v108
	v_mul_f32_e32 v72, 0xbfb8aa3b, v77
	v_exp_f32_e32 v72, v72
	v_mov_b32_e32 v78, v73
	v_mov_b32_e32 v76, v101
	v_add_f32_e32 v72, 1.0, v72
	v_rcp_f32_e32 v79, v72
	s_nop 0
	v_pk_mul_f32 v[72:73], v[78:79], v[76:77]
; __device__ __forceinline__ size_t pidx(size_t row, int col) { return ((size_t)(col >> 8) * MTOK + row) * PLD + (col & 255); }
; __device__ __forceinline__ float bflo(unsigned v) { return __uint_as_float(v << 16); }
; __device__ __forceinline__ float bfhi(unsigned v) { return __uint_as_float(v & 0xffff0000u); }
; __device__ __forceinline__ float siluf_(float x) { return x * __builtin_amdgcn_rcpf(1.0f + __expf(-x)); }
;   __device__ __forceinline__ void operator()(EPI_ARGS) const {
;     ...
;     for (int bj = 0; bj < 2; ++bj) {
;       const int c = col0 + bj * HALF;
;       const f32x4 s0 = *(const f32x4*)(psc + c), s1 = *(const f32x4*)(psc + c + 4);
; #pragma unroll
;       for (int ai = 0; ai < 2; ++ai) {
;         u32x4 z[4];
; #pragma unroll
;         for (int m = 0; m < 4; ++m) z[m] = *(const u32x4*)(proj + pidx(row0 + ai * HALF + m * 16, PZ + c));
;         __builtin_amdgcn_sched_barrier(0);
; #pragma unroll
;         for (int m = 0; m < 4; ++m) {
;           const size_t row = row0 + ai * HALF + m * 16;
;           const f32x4 v0 = acc[ai][bj][m][0], v1 = acc[ai][bj][m][1];
;           u32x4 o;
;           o.x = pack2(v0[0] * s0[0] * siluf_(bflo(z[m].x)), v0[1] * s0[1] * siluf_(bfhi(z[m].x)));
;           o.y = pack2(v0[2] * s0[2] * siluf_(bflo(z[m].y)), v0[3] * s0[3] * siluf_(bfhi(z[m].y)));
;           o.z = pack2(v1[0] * s1[0] * siluf_(bflo(z[m].z)), v1[1] * s1[1] * siluf_(bfhi(z[m].z)));
;           o.w = pack2(v1[2] * s1[2] * siluf_(bflo(z[m].w)), v1[3] * s1[3] * siluf_(bfhi(z[m].w)));
;           *(u32x4*)(y0 + row * DM + c) = o;
	s_nop 0
	v_mul_f32_e32 v72, v72, v73
	v_lshlrev_b32_e32 v77, 16, v109
	v_cvt_pk_bf16_f32 v72, v2, v72
	v_mul_f32_e32 v2, 0xbfb8aa3b, v77
	v_exp_f32_e32 v2, v2
	v_mov_b32_e32 v78, v74
	v_mov_b32_e32 v76, v102
	v_add_f32_e32 v2, 1.0, v2
	v_rcp_f32_e32 v79, v2
	s_nop 0
	v_pk_mul_f32 v[76:77], v[78:79], v[76:77]
	s_nop 0
	v_mul_f32_e32 v2, v76, v77
	v_and_b32_e32 v77, 0xffff0000, v109
	v_mul_f32_e32 v73, 0xbfb8aa3b, v77
	v_exp_f32_e32 v73, v73
	v_mov_b32_e32 v78, v75
	v_mov_b32_e32 v76, v103
	v_add_f32_e32 v73, 1.0, v73
	v_rcp_f32_e32 v79, v73
	s_nop 0
	v_pk_mul_f32 v[74:75], v[78:79], v[76:77]
	s_nop 0
	v_mul_f32_e32 v73, v74, v75
	v_lshlrev_b32_e32 v75, 16, v110
	v_cvt_pk_bf16_f32 v73, v2, v73
	v_mul_f32_e32 v2, 0xbfb8aa3b, v75
	v_exp_f32_e32 v2, v2
	v_mov_b32_e32 v76, v68
	v_mov_b32_e32 v74, v92
	v_add_f32_e32 v2, 1.0, v2
	v_rcp_f32_e32 v77, v2
	s_nop 0
	v_pk_mul_f32 v[74:75], v[76:77], v[74:75]
	s_nop 0
	v_mul_f32_e32 v2, v74, v75
	v_and_b32_e32 v75, 0xffff0000, v110
	v_mul_f32_e32 v68, 0xbfb8aa3b, v75
	v_exp_f32_e32 v68, v68
	v_mov_b32_e32 v76, v69
	v_mov_b32_e32 v74, v93
	v_add_f32_e32 v68, 1.0, v68
	v_rcp_f32_e32 v77, v68
	s_nop 0
	v_pk_mul_f32 v[68:69], v[76:77], v[74:75]
	s_nop 0
	v_mul_f32_e32 v68, v68, v69
	v_lshlrev_b32_e32 v69, 16, v111
	v_cvt_pk_bf16_f32 v74, v2, v68
	v_mul_f32_e32 v2, 0xbfb8aa3b, v69
	v_exp_f32_e32 v2, v2
	v_mov_b32_e32 v76, v70
	v_mov_b32_e32 v68, v94
	v_add_f32_e32 v2, 1.0, v2
	v_rcp_f32_e32 v77, v2
	s_nop 0
	v_pk_mul_f32 v[68:69], v[76:77], v[68:69]
	s_nop 0
	v_mul_f32_e32 v2, v68, v69
	v_and_b32_e32 v69, 0xffff0000, v111
	v_mul_f32_e32 v68, 0xbfb8aa3b, v69
	v_exp_f32_e32 v68, v68
	v_mov_b32_e32 v76, v71
	v_add_f32_e32 v68, 1.0, v68
	v_rcp_f32_e32 v77, v68
	v_mov_b32_e32 v68, v95
	v_lshl_add_u64 v[94:95], s[2:3], 0, v[174:175]
	v_pk_mul_f32 v[68:69], v[76:77], v[68:69]
	s_nop 0
	v_mul_f32_e32 v68, v68, v69
	v_cvt_pk_bf16_f32 v75, v2, v68
	v_lshlrev_b64 v[68:69], 12, v[142:143]
	v_lshl_add_u64 v[68:69], s[8:9], 0, v[68:69]
	v_lshl_add_u64 v[92:93], v[68:69], 0, v[140:141]
	flat_store_dwordx4 v[92:93], v[72:75]
	v_lshl_add_u64 v[76:77], v[94:95], 0, v[178:179]
	global_load_dwordx4 v[68:71], v[176:177], off offset:528
	global_load_dwordx4 v[72:75], v[176:177], off offset:512
	flat_load_dwordx4 v[88:91], v[76:77]
	v_lshl_add_u64 v[76:77], v[94:95], 0, v[180:181]
	flat_load_dwordx4 v[84:87], v[76:77]
	v_lshl_add_u64 v[76:77], v[94:95], 0, v[182:183]
	flat_load_dwordx4 v[80:83], v[76:77]
	v_lshl_add_u64 v[76:77], v[94:95], 0, v[184:185]
	flat_load_dwordx4 v[76:79], v[76:77]
	s_waitcnt vmcnt(0) lgkmcnt(0)
	v_lshlrev_b32_e32 v101, 16, v88
	v_mul_f32_e32 v2, 0xbfb8aa3b, v101
	v_exp_f32_e32 v2, v2
	v_mov_b32_e32 v102, v64
	v_mov_b32_e32 v100, v72
	v_add_f32_e32 v2, 1.0, v2
	v_rcp_f32_e32 v103, v2
	s_nop 0
	v_pk_mul_f32 v[100:101], v[102:103], v[100:101]
	s_nop 0
	v_mul_f32_e32 v2, v100, v101
	v_and_b32_e32 v101, 0xffff0000, v88
	v_mul_f32_e32 v64, 0xbfb8aa3b, v101
	v_exp_f32_e32 v64, v64
	v_mov_b32_e32 v102, v65
	v_mov_b32_e32 v100, v73
	v_mov_b32_e32 v88, v75
	v_add_f32_e32 v64, 1.0, v64
	v_rcp_f32_e32 v103, v64
	s_nop 0
	v_pk_mul_f32 v[64:65], v[102:103], v[100:101]
	s_nop 0
	v_mul_f32_e32 v64, v64, v65
	v_lshlrev_b32_e32 v101, 16, v89
	v_cvt_pk_bf16_f32 v64, v2, v64
	v_mul_f32_e32 v2, 0xbfb8aa3b, v101
	v_exp_f32_e32 v2, v2
	v_and_b32_e32 v89, 0xffff0000, v89
	v_mul_f32_e32 v65, 0xbfb8aa3b, v89
	v_exp_f32_e32 v65, v65
	v_add_f32_e32 v2, 1.0, v2
	v_rcp_f32_e32 v103, v2
	v_mov_b32_e32 v102, v66
	v_mov_b32_e32 v100, v74
	v_add_f32_e32 v65, 1.0, v65
	v_pk_mul_f32 v[100:101], v[102:103], v[100:101]
	s_nop 0
	v_mul_f32_e32 v2, v100, v101
	v_rcp_f32_e32 v101, v65
	v_mov_b32_e32 v100, v67
	v_pk_mul_f32 v[66:67], v[100:101], v[88:89]
	s_nop 0
	v_mul_f32_e32 v65, v66, v67
	v_lshlrev_b32_e32 v67, 16, v90
	v_cvt_pk_bf16_f32 v65, v2, v65
	v_mul_f32_e32 v2, 0xbfb8aa3b, v67
	v_exp_f32_e32 v2, v2
	v_mov_b32_e32 v88, v60
	v_mov_b32_e32 v66, v68
	v_add_f32_e32 v2, 1.0, v2
	v_rcp_f32_e32 v89, v2
	s_nop 0
	v_pk_mul_f32 v[66:67], v[88:89], v[66:67]
	s_nop 0
	v_mul_f32_e32 v2, v66, v67
	v_and_b32_e32 v67, 0xffff0000, v90
	v_mul_f32_e32 v60, 0xbfb8aa3b, v67
	v_exp_f32_e32 v60, v60
	v_mov_b32_e32 v88, v61
	v_mov_b32_e32 v66, v69
	v_add_f32_e32 v60, 1.0, v60
	v_rcp_f32_e32 v89, v60
	s_nop 0
	v_pk_mul_f32 v[60:61], v[88:89], v[66:67]
	s_nop 0
	v_mul_f32_e32 v60, v60, v61
	v_lshlrev_b32_e32 v61, 16, v91
	v_cvt_pk_bf16_f32 v66, v2, v60
	v_mul_f32_e32 v2, 0xbfb8aa3b, v61
	v_exp_f32_e32 v2, v2
	v_mov_b32_e32 v88, v62
	v_mov_b32_e32 v60, v70
	v_mov_b32_e32 v62, v56
	v_add_f32_e32 v2, 1.0, v2
	v_rcp_f32_e32 v89, v2
	s_nop 0
	v_pk_mul_f32 v[60:61], v[88:89], v[60:61]
	s_nop 0
	v_mul_f32_e32 v2, v60, v61
	v_and_b32_e32 v61, 0xffff0000, v91
	v_mul_f32_e32 v60, 0xbfb8aa3b, v61
	v_exp_f32_e32 v60, v60
	v_mov_b32_e32 v88, v63
	v_add_f32_e32 v60, 1.0, v60
	v_rcp_f32_e32 v89, v60
	v_mov_b32_e32 v60, v71
	v_pk_mul_f32 v[60:61], v[88:89], v[60:61]
	s_nop 0
	v_mul_f32_e32 v60, v60, v61
	v_lshlrev_b32_e32 v61, 16, v84
	v_cvt_pk_bf16_f32 v67, v2, v60
	v_mul_f32_e32 v2, 0xbfb8aa3b, v61
	v_exp_f32_e32 v2, v2
	v_mov_b32_e32 v60, v72
	flat_store_dwordx4 v[136:137], v[64:67] offset:256
	v_add_f32_e32 v2, 1.0, v2
	v_rcp_f32_e32 v63, v2
	s_nop 0
	v_pk_mul_f32 v[60:61], v[62:63], v[60:61]
	s_nop 0
	v_mul_f32_e32 v2, v60, v61
	v_and_b32_e32 v61, 0xffff0000, v84
	v_mul_f32_e32 v56, 0xbfb8aa3b, v61
	v_exp_f32_e32 v56, v56
	v_mov_b32_e32 v62, v57
	v_mov_b32_e32 v60, v73
	v_add_f32_e32 v56, 1.0, v56
	v_rcp_f32_e32 v63, v56
	s_nop 0
	v_pk_mul_f32 v[56:57], v[62:63], v[60:61]
	s_nop 0
	v_mul_f32_e32 v56, v56, v57
	v_lshlrev_b32_e32 v61, 16, v85
	v_cvt_pk_bf16_f32 v56, v2, v56
; __device__ __forceinline__ size_t pidx(size_t row, int col) { return ((size_t)(col >> 8) * MTOK + row) * PLD + (col & 255); }
; __device__ __forceinline__ float bflo(unsigned v) { return __uint_as_float(v << 16); }
; __device__ __forceinline__ float bfhi(unsigned v) { return __uint_as_float(v & 0xffff0000u); }
; __device__ __forceinline__ float siluf_(float x) { return x * __builtin_amdgcn_rcpf(1.0f + __expf(-x)); }
;   __device__ __forceinline__ void operator()(EPI_ARGS) const {
;     ...
;       for (int ai = 0; ai < 2; ++ai) {
;         u32x4 z[4];
; #pragma unroll
;         for (int m = 0; m < 4; ++m) z[m] = *(const u32x4*)(proj + pidx(row0 + ai * HALF + m * 16, PZ + c));
;         __builtin_amdgcn_sched_barrier(0);
; #pragma unroll
;         for (int m = 0; m < 4; ++m) {
;           const size_t row = row0 + ai * HALF + m * 16;
;           const f32x4 v0 = acc[ai][bj][m][0], v1 = acc[ai][bj][m][1];
;           u32x4 o;
;           o.x = pack2(v0[0] * s0[0] * siluf_(bflo(z[m].x)), v0[1] * s0[1] * siluf_(bfhi(z[m].x)));
;           o.y = pack2(v0[2] * s0[2] * siluf_(bflo(z[m].y)), v0[3] * s0[3] * siluf_(bfhi(z[m].y)));
;           o.z = pack2(v1[0] * s1[0] * siluf_(bflo(z[m].z)), v1[1] * s1[1] * siluf_(bfhi(z[m].z)));
;           o.w = pack2(v1[2] * s1[2] * siluf_(bflo(z[m].w)), v1[3] * s1[3] * siluf_(bfhi(z[m].w)));
;           *(u32x4*)(y0 + row * DM + c) = o;
	v_mul_f32_e32 v2, 0xbfb8aa3b, v61
	v_exp_f32_e32 v2, v2
	v_mov_b32_e32 v62, v58
	v_mov_b32_e32 v60, v74
	v_add_f32_e32 v2, 1.0, v2
	v_rcp_f32_e32 v63, v2
	s_nop 0
	v_pk_mul_f32 v[60:61], v[62:63], v[60:61]
	s_nop 0
	v_mul_f32_e32 v2, v60, v61
	v_and_b32_e32 v61, 0xffff0000, v85
	v_mul_f32_e32 v57, 0xbfb8aa3b, v61
	v_exp_f32_e32 v57, v57
	v_mov_b32_e32 v62, v59
	v_mov_b32_e32 v60, v75
	v_add_f32_e32 v57, 1.0, v57
	v_rcp_f32_e32 v63, v57
	s_nop 0
	v_pk_mul_f32 v[58:59], v[62:63], v[60:61]
	s_nop 0
	v_mul_f32_e32 v57, v58, v59
	v_lshlrev_b32_e32 v59, 16, v86
	v_cvt_pk_bf16_f32 v57, v2, v57
	v_mul_f32_e32 v2, 0xbfb8aa3b, v59
	v_exp_f32_e32 v2, v2
	v_mov_b32_e32 v60, v52
	v_mov_b32_e32 v58, v68
	v_add_f32_e32 v2, 1.0, v2
	v_rcp_f32_e32 v61, v2
	s_nop 0
	v_pk_mul_f32 v[58:59], v[60:61], v[58:59]
	s_nop 0
	v_mul_f32_e32 v2, v58, v59
	v_and_b32_e32 v59, 0xffff0000, v86
	v_mul_f32_e32 v52, 0xbfb8aa3b, v59
	v_exp_f32_e32 v52, v52
	v_mov_b32_e32 v60, v53
	v_mov_b32_e32 v58, v69
	v_add_f32_e32 v52, 1.0, v52
	v_rcp_f32_e32 v61, v52
	s_nop 0
	v_pk_mul_f32 v[52:53], v[60:61], v[58:59]
	s_nop 0
	v_mul_f32_e32 v52, v52, v53
	v_lshlrev_b32_e32 v53, 16, v87
	v_cvt_pk_bf16_f32 v58, v2, v52
	v_mul_f32_e32 v2, 0xbfb8aa3b, v53
	v_exp_f32_e32 v2, v2
	v_mov_b32_e32 v60, v54
	v_mov_b32_e32 v52, v70
	v_mov_b32_e32 v54, v48
	v_add_f32_e32 v2, 1.0, v2
	v_rcp_f32_e32 v61, v2
	s_nop 0
	v_pk_mul_f32 v[52:53], v[60:61], v[52:53]
	s_nop 0
	v_mul_f32_e32 v2, v52, v53
	v_and_b32_e32 v53, 0xffff0000, v87
	v_mul_f32_e32 v52, 0xbfb8aa3b, v53
	v_exp_f32_e32 v52, v52
	v_mov_b32_e32 v60, v55
	v_add_f32_e32 v52, 1.0, v52
	v_rcp_f32_e32 v61, v52
	v_mov_b32_e32 v52, v71
	v_pk_mul_f32 v[52:53], v[60:61], v[52:53]
	s_nop 0
	v_mul_f32_e32 v52, v52, v53
	v_lshlrev_b32_e32 v53, 16, v80
	v_cvt_pk_bf16_f32 v59, v2, v52
	v_mul_f32_e32 v2, 0xbfb8aa3b, v53
	v_exp_f32_e32 v2, v2
	v_mov_b32_e32 v52, v72
	flat_store_dwordx4 v[124:125], v[56:59] offset:256
	v_add_f32_e32 v2, 1.0, v2
	v_rcp_f32_e32 v55, v2
	s_nop 0
	v_pk_mul_f32 v[52:53], v[54:55], v[52:53]
	s_nop 0
	v_mul_f32_e32 v2, v52, v53
	v_and_b32_e32 v53, 0xffff0000, v80
	v_mul_f32_e32 v48, 0xbfb8aa3b, v53
	v_exp_f32_e32 v48, v48
	v_mov_b32_e32 v54, v49
	v_mov_b32_e32 v52, v73
	v_add_f32_e32 v48, 1.0, v48
	v_rcp_f32_e32 v55, v48
	s_nop 0
	v_pk_mul_f32 v[48:49], v[54:55], v[52:53]
	s_nop 0
	v_mul_f32_e32 v48, v48, v49
	v_lshlrev_b32_e32 v53, 16, v81
	v_cvt_pk_bf16_f32 v48, v2, v48
	v_mul_f32_e32 v2, 0xbfb8aa3b, v53
	v_exp_f32_e32 v2, v2
	v_mov_b32_e32 v54, v50
	v_mov_b32_e32 v52, v74
	v_add_f32_e32 v2, 1.0, v2
	v_rcp_f32_e32 v55, v2
	s_nop 0
	v_pk_mul_f32 v[52:53], v[54:55], v[52:53]
	s_nop 0
	v_mul_f32_e32 v2, v52, v53
	v_and_b32_e32 v53, 0xffff0000, v81
	v_mul_f32_e32 v49, 0xbfb8aa3b, v53
	v_exp_f32_e32 v49, v49
	v_mov_b32_e32 v54, v51
	v_mov_b32_e32 v52, v75
	v_add_f32_e32 v49, 1.0, v49
	v_rcp_f32_e32 v55, v49
	s_nop 0
	v_pk_mul_f32 v[50:51], v[54:55], v[52:53]
	s_nop 0
	v_mul_f32_e32 v49, v50, v51
	v_lshlrev_b32_e32 v51, 16, v82
	v_cvt_pk_bf16_f32 v49, v2, v49
	v_mul_f32_e32 v2, 0xbfb8aa3b, v51
	v_exp_f32_e32 v2, v2
	v_mov_b32_e32 v52, v44
	v_mov_b32_e32 v50, v68
	v_add_f32_e32 v2, 1.0, v2
	v_rcp_f32_e32 v53, v2
	s_nop 0
	v_pk_mul_f32 v[50:51], v[52:53], v[50:51]
	s_nop 0
	v_mul_f32_e32 v2, v50, v51
	v_and_b32_e32 v51, 0xffff0000, v82
	v_mul_f32_e32 v44, 0xbfb8aa3b, v51
	v_exp_f32_e32 v44, v44
	v_mov_b32_e32 v52, v45
	v_mov_b32_e32 v50, v69
	v_add_f32_e32 v44, 1.0, v44
	v_rcp_f32_e32 v53, v44
	s_nop 0
	v_pk_mul_f32 v[44:45], v[52:53], v[50:51]
	s_nop 0
	v_mul_f32_e32 v44, v44, v45
	v_lshlrev_b32_e32 v45, 16, v83
	v_cvt_pk_bf16_f32 v50, v2, v44
	v_mul_f32_e32 v2, 0xbfb8aa3b, v45
	v_exp_f32_e32 v2, v2
	v_mov_b32_e32 v52, v46
	v_mov_b32_e32 v44, v70
	v_mov_b32_e32 v46, v40
	v_add_f32_e32 v2, 1.0, v2
	v_rcp_f32_e32 v53, v2
	s_nop 0
	v_pk_mul_f32 v[44:45], v[52:53], v[44:45]
	s_nop 0
	v_mul_f32_e32 v2, v44, v45
	v_and_b32_e32 v45, 0xffff0000, v83
	v_mul_f32_e32 v44, 0xbfb8aa3b, v45
	v_exp_f32_e32 v44, v44
	v_mov_b32_e32 v52, v47
	v_add_f32_e32 v44, 1.0, v44
	v_rcp_f32_e32 v53, v44
	v_mov_b32_e32 v44, v71
	v_pk_mul_f32 v[44:45], v[52:53], v[44:45]
	s_nop 0
	v_mul_f32_e32 v44, v44, v45
	v_lshlrev_b32_e32 v45, 16, v76
	v_cvt_pk_bf16_f32 v51, v2, v44
	v_mul_f32_e32 v2, 0xbfb8aa3b, v45
	v_exp_f32_e32 v2, v2
	v_mov_b32_e32 v44, v72
	flat_store_dwordx4 v[128:129], v[48:51] offset:256
	v_add_f32_e32 v2, 1.0, v2
	v_rcp_f32_e32 v47, v2
	s_nop 0
	v_pk_mul_f32 v[44:45], v[46:47], v[44:45]
	s_nop 0
	v_mul_f32_e32 v2, v44, v45
	v_and_b32_e32 v45, 0xffff0000, v76
	v_mul_f32_e32 v40, 0xbfb8aa3b, v45
	v_exp_f32_e32 v40, v40
	v_mov_b32_e32 v46, v41
	v_mov_b32_e32 v44, v73
	v_add_f32_e32 v40, 1.0, v40
	v_rcp_f32_e32 v47, v40
	s_nop 0
	v_pk_mul_f32 v[40:41], v[46:47], v[44:45]
	s_nop 0
	v_mul_f32_e32 v40, v40, v41
	v_lshlrev_b32_e32 v45, 16, v77
	v_cvt_pk_bf16_f32 v40, v2, v40
	v_mul_f32_e32 v2, 0xbfb8aa3b, v45
	v_exp_f32_e32 v2, v2
	v_mov_b32_e32 v46, v42
	v_mov_b32_e32 v44, v74
	v_add_f32_e32 v2, 1.0, v2
	v_rcp_f32_e32 v47, v2
	s_nop 0
	v_pk_mul_f32 v[44:45], v[46:47], v[44:45]
	s_nop 0
	v_mul_f32_e32 v2, v44, v45
	v_and_b32_e32 v45, 0xffff0000, v77
	v_mul_f32_e32 v41, 0xbfb8aa3b, v45
	v_exp_f32_e32 v41, v41
	v_mov_b32_e32 v46, v43
	v_mov_b32_e32 v44, v75
	v_add_f32_e32 v41, 1.0, v41
	v_rcp_f32_e32 v47, v41
	s_nop 0
	v_pk_mul_f32 v[42:43], v[46:47], v[44:45]
	s_nop 0
	v_mul_f32_e32 v41, v42, v43
	v_lshlrev_b32_e32 v43, 16, v78
	v_cvt_pk_bf16_f32 v41, v2, v41
	v_mul_f32_e32 v2, 0xbfb8aa3b, v43
	v_exp_f32_e32 v2, v2
	v_mov_b32_e32 v44, v36
	v_mov_b32_e32 v42, v68
	v_add_f32_e32 v2, 1.0, v2
	v_rcp_f32_e32 v45, v2
	s_nop 0
	v_pk_mul_f32 v[42:43], v[44:45], v[42:43]
	s_nop 0
	v_mul_f32_e32 v2, v42, v43
	v_and_b32_e32 v43, 0xffff0000, v78
	v_mul_f32_e32 v36, 0xbfb8aa3b, v43
	v_exp_f32_e32 v36, v36
	v_mov_b32_e32 v44, v37
	v_mov_b32_e32 v42, v69
	v_add_f32_e32 v36, 1.0, v36
	v_rcp_f32_e32 v45, v36
	s_nop 0
	v_pk_mul_f32 v[36:37], v[44:45], v[42:43]
	s_nop 0
	v_mul_f32_e32 v36, v36, v37
	v_lshlrev_b32_e32 v37, 16, v79
	v_cvt_pk_bf16_f32 v42, v2, v36
	v_mul_f32_e32 v2, 0xbfb8aa3b, v37
	v_exp_f32_e32 v2, v2
	v_mov_b32_e32 v44, v38
	v_mov_b32_e32 v36, v70
	v_add_f32_e32 v2, 1.0, v2
	v_rcp_f32_e32 v45, v2
	s_nop 0
	v_pk_mul_f32 v[36:37], v[44:45], v[36:37]
	s_nop 0
	v_mul_f32_e32 v2, v36, v37
	v_and_b32_e32 v37, 0xffff0000, v79
	v_mul_f32_e32 v36, 0xbfb8aa3b, v37
	v_exp_f32_e32 v36, v36
	v_mov_b32_e32 v44, v39
	v_add_f32_e32 v36, 1.0, v36
	v_rcp_f32_e32 v45, v36
	v_mov_b32_e32 v36, v71
	v_pk_mul_f32 v[36:37], v[44:45], v[36:37]
	s_nop 0
	v_mul_f32_e32 v36, v36, v37
	v_cvt_pk_bf16_f32 v43, v2, v36
	flat_store_dwordx4 v[126:127], v[40:43] offset:256
	v_lshl_add_u64 v[36:37], v[94:95], 0, v[130:131]
	flat_load_dwordx4 v[48:51], v[36:37]
	v_lshl_add_u64 v[36:37], v[94:95], 0, v[132:133]
	flat_load_dwordx4 v[44:47], v[36:37]
	v_lshl_add_u64 v[36:37], v[94:95], 0, v[134:135]
	flat_load_dwordx4 v[40:43], v[36:37]
	v_lshl_add_u64 v[36:37], v[94:95], 0, v[138:139]
	flat_load_dwordx4 v[36:39], v[36:37]
	s_waitcnt vmcnt(0) lgkmcnt(0)
; __device__ __forceinline__ float bflo(unsigned v) { return __uint_as_float(v << 16); }
; __device__ __forceinline__ float bfhi(unsigned v) { return __uint_as_float(v & 0xffff0000u); }
; __device__ __forceinline__ float siluf_(float x) { return x * __builtin_amdgcn_rcpf(1.0f + __expf(-x)); }
;   __device__ __forceinline__ void operator()(EPI_ARGS) const {
;     ...
;         for (int m = 0; m < 4; ++m) {
;           const size_t row = row0 + ai * HALF + m * 16;
;           const f32x4 v0 = acc[ai][bj][m][0], v1 = acc[ai][bj][m][1];
;           u32x4 o;
;           o.x = pack2(v0[0] * s0[0] * siluf_(bflo(z[m].x)), v0[1] * s0[1] * siluf_(bfhi(z[m].x)));
;           o.y = pack2(v0[2] * s0[2] * siluf_(bflo(z[m].y)), v0[3] * s0[3] * siluf_(bfhi(z[m].y)));
;           o.z = pack2(v1[0] * s1[0] * siluf_(bflo(z[m].z)), v1[1] * s1[1] * siluf_(bfhi(z[m].z)));
;           o.w = pack2(v1[2] * s1[2] * siluf_(bflo(z[m].w)), v1[3] * s1[3] * siluf_(bfhi(z[m].w)));
;           *(u32x4*)(y0 + row * DM + c) = o;
	v_lshlrev_b32_e32 v53, 16, v48
	v_mul_f32_e32 v2, 0xbfb8aa3b, v53
	v_exp_f32_e32 v2, v2
	v_mov_b32_e32 v54, v32
	v_mov_b32_e32 v52, v72
	s_and_b64 vcc, exec, s[18:19]
	v_add_f32_e32 v2, 1.0, v2
	v_rcp_f32_e32 v55, v2
	s_mov_b32 s33, s16
	s_mov_b32 s2, s14
	s_mov_b64 s[4:5], s[22:23]
	v_pk_mul_f32 v[52:53], v[54:55], v[52:53]
	v_mov_b32_e32 v54, v33
	v_mul_f32_e32 v2, v52, v53
	v_and_b32_e32 v53, 0xffff0000, v48
	v_mul_f32_e32 v32, 0xbfb8aa3b, v53
	v_exp_f32_e32 v32, v32
	v_mov_b32_e32 v52, v73
	v_mov_b32_e32 v48, v75
	s_mov_b64 s[6:7], s[20:21]
	v_add_f32_e32 v32, 1.0, v32
	v_rcp_f32_e32 v55, v32
	s_nop 0
	v_pk_mul_f32 v[32:33], v[54:55], v[52:53]
	s_nop 0
	v_mul_f32_e32 v32, v32, v33
	v_lshlrev_b32_e32 v53, 16, v49
	v_cvt_pk_bf16_f32 v32, v2, v32
	v_mul_f32_e32 v2, 0xbfb8aa3b, v53
	v_exp_f32_e32 v2, v2
	v_and_b32_e32 v49, 0xffff0000, v49
	v_mul_f32_e32 v33, 0xbfb8aa3b, v49
	v_exp_f32_e32 v33, v33
	v_add_f32_e32 v2, 1.0, v2
	v_rcp_f32_e32 v55, v2
	v_mov_b32_e32 v54, v34
	v_mov_b32_e32 v52, v74
	v_add_f32_e32 v33, 1.0, v33
	v_pk_mul_f32 v[52:53], v[54:55], v[52:53]
	s_nop 0
	v_mul_f32_e32 v2, v52, v53
	v_rcp_f32_e32 v53, v33
	v_mov_b32_e32 v52, v35
	v_pk_mul_f32 v[34:35], v[52:53], v[48:49]
	s_nop 0
	v_mul_f32_e32 v33, v34, v35
	v_lshlrev_b32_e32 v35, 16, v50
	v_cvt_pk_bf16_f32 v33, v2, v33
	v_mul_f32_e32 v2, 0xbfb8aa3b, v35
	v_exp_f32_e32 v2, v2
	v_mov_b32_e32 v48, v28
	v_mov_b32_e32 v34, v68
	v_add_f32_e32 v2, 1.0, v2
	v_rcp_f32_e32 v49, v2
	s_nop 0
	v_pk_mul_f32 v[34:35], v[48:49], v[34:35]
	s_nop 0
	v_mul_f32_e32 v2, v34, v35
	v_and_b32_e32 v35, 0xffff0000, v50
	v_mul_f32_e32 v28, 0xbfb8aa3b, v35
	v_exp_f32_e32 v28, v28
	v_mov_b32_e32 v48, v29
	v_mov_b32_e32 v34, v69
	v_add_f32_e32 v28, 1.0, v28
	v_rcp_f32_e32 v49, v28
	s_nop 0
	v_pk_mul_f32 v[28:29], v[48:49], v[34:35]
	s_nop 0
	v_mul_f32_e32 v28, v28, v29
	v_lshlrev_b32_e32 v29, 16, v51
	v_cvt_pk_bf16_f32 v34, v2, v28
	v_mul_f32_e32 v2, 0xbfb8aa3b, v29
	v_exp_f32_e32 v2, v2
	v_mov_b32_e32 v48, v30
	v_mov_b32_e32 v28, v70
	v_mov_b32_e32 v30, v24
	v_add_f32_e32 v2, 1.0, v2
	v_rcp_f32_e32 v49, v2
	s_nop 0
	v_pk_mul_f32 v[28:29], v[48:49], v[28:29]
	s_nop 0
	v_mul_f32_e32 v2, v28, v29
	v_and_b32_e32 v29, 0xffff0000, v51
	v_mul_f32_e32 v28, 0xbfb8aa3b, v29
	v_exp_f32_e32 v28, v28
	v_mov_b32_e32 v48, v31
	v_add_f32_e32 v28, 1.0, v28
	v_rcp_f32_e32 v49, v28
	v_mov_b32_e32 v28, v71
	v_pk_mul_f32 v[28:29], v[48:49], v[28:29]
	s_nop 0
	v_mul_f32_e32 v28, v28, v29
	v_lshlrev_b32_e32 v29, 16, v44
	v_cvt_pk_bf16_f32 v35, v2, v28
	v_mul_f32_e32 v2, 0xbfb8aa3b, v29
	v_exp_f32_e32 v2, v2
	v_mov_b32_e32 v28, v72
	flat_store_dwordx4 v[96:97], v[32:35] offset:256
	v_add_f32_e32 v2, 1.0, v2
	v_rcp_f32_e32 v31, v2
	s_nop 0
	v_pk_mul_f32 v[28:29], v[30:31], v[28:29]
	s_nop 0
	v_mul_f32_e32 v2, v28, v29
	v_and_b32_e32 v29, 0xffff0000, v44
	v_mul_f32_e32 v24, 0xbfb8aa3b, v29
	v_exp_f32_e32 v24, v24
	v_mov_b32_e32 v30, v25
	v_mov_b32_e32 v28, v73
	v_add_f32_e32 v24, 1.0, v24
	v_rcp_f32_e32 v31, v24
	s_nop 0
	v_pk_mul_f32 v[24:25], v[30:31], v[28:29]
	s_nop 0
	v_mul_f32_e32 v24, v24, v25
	v_lshlrev_b32_e32 v29, 16, v45
	v_cvt_pk_bf16_f32 v24, v2, v24
	v_mul_f32_e32 v2, 0xbfb8aa3b, v29
	v_exp_f32_e32 v2, v2
	v_mov_b32_e32 v30, v26
	v_mov_b32_e32 v28, v74
	v_add_f32_e32 v2, 1.0, v2
	v_rcp_f32_e32 v31, v2
	s_nop 0
	v_pk_mul_f32 v[28:29], v[30:31], v[28:29]
	s_nop 0
	v_mul_f32_e32 v2, v28, v29
	v_and_b32_e32 v29, 0xffff0000, v45
	v_mul_f32_e32 v25, 0xbfb8aa3b, v29
	v_exp_f32_e32 v25, v25
	v_mov_b32_e32 v30, v27
	v_mov_b32_e32 v28, v75
	v_add_f32_e32 v25, 1.0, v25
	v_rcp_f32_e32 v31, v25
	s_nop 0
	v_pk_mul_f32 v[26:27], v[30:31], v[28:29]
	s_nop 0
	v_mul_f32_e32 v25, v26, v27
	v_lshlrev_b32_e32 v27, 16, v46
	v_cvt_pk_bf16_f32 v25, v2, v25
	v_mul_f32_e32 v2, 0xbfb8aa3b, v27
	v_exp_f32_e32 v2, v2
	v_mov_b32_e32 v28, v20
	v_mov_b32_e32 v26, v68
	v_add_f32_e32 v2, 1.0, v2
	v_rcp_f32_e32 v29, v2
	s_nop 0
	v_pk_mul_f32 v[26:27], v[28:29], v[26:27]
	s_nop 0
	v_mul_f32_e32 v2, v26, v27
	v_and_b32_e32 v27, 0xffff0000, v46
	v_mul_f32_e32 v20, 0xbfb8aa3b, v27
	v_exp_f32_e32 v20, v20
	v_mov_b32_e32 v28, v21
	v_mov_b32_e32 v26, v69
	v_add_f32_e32 v20, 1.0, v20
	v_rcp_f32_e32 v29, v20
	s_nop 0
	v_pk_mul_f32 v[20:21], v[28:29], v[26:27]
	s_nop 0
	v_mul_f32_e32 v20, v20, v21
	v_lshlrev_b32_e32 v21, 16, v47
	v_cvt_pk_bf16_f32 v26, v2, v20
	v_mul_f32_e32 v2, 0xbfb8aa3b, v21
	v_exp_f32_e32 v2, v2
	v_mov_b32_e32 v28, v22
	v_mov_b32_e32 v20, v70
	v_mov_b32_e32 v22, v16
	v_add_f32_e32 v2, 1.0, v2
	v_rcp_f32_e32 v29, v2
	s_nop 0
	v_pk_mul_f32 v[20:21], v[28:29], v[20:21]
	s_nop 0
	v_mul_f32_e32 v2, v20, v21
	v_and_b32_e32 v21, 0xffff0000, v47
	v_mul_f32_e32 v20, 0xbfb8aa3b, v21
	v_exp_f32_e32 v20, v20
	v_mov_b32_e32 v28, v23
	v_add_f32_e32 v20, 1.0, v20
	v_rcp_f32_e32 v29, v20
	v_mov_b32_e32 v20, v71
	v_pk_mul_f32 v[20:21], v[28:29], v[20:21]
	s_nop 0
	v_mul_f32_e32 v20, v20, v21
	v_lshlrev_b32_e32 v21, 16, v40
	v_cvt_pk_bf16_f32 v27, v2, v20
	v_mul_f32_e32 v2, 0xbfb8aa3b, v21
	v_exp_f32_e32 v2, v2
	v_mov_b32_e32 v20, v72
	flat_store_dwordx4 v[98:99], v[24:27] offset:256
; __device__ __forceinline__ float bflo(unsigned v) { return __uint_as_float(v << 16); }
; __device__ __forceinline__ float bfhi(unsigned v) { return __uint_as_float(v & 0xffff0000u); }
; __device__ __forceinline__ float siluf_(float x) { return x * __builtin_amdgcn_rcpf(1.0f + __expf(-x)); }
; #define PG8_WAIT_V(n) asm volatile("s_waitcnt vmcnt(" #n ")" ::: "memory")
; #define PG8_BAR __builtin_amdgcn_s_barrier()
; template <class Epi, class AddrA, class AddrB>
; __device__ __forceinline__ void gemm_phase(const Sched S, const int lda, const int ldb, const int K, const AddrA addrA,
;                                            const AddrB addrB, const Epi E) {
;     ...
;   PG8_WAIT_V(0);
;   if (wr == 0) PG8_BAR;
;   PG8_BAR;
;   __device__ __forceinline__ void operator()(EPI_ARGS) const {
;     ...
;         for (int m = 0; m < 4; ++m) {
;           const size_t row = row0 + ai * HALF + m * 16;
;           const f32x4 v0 = acc[ai][bj][m][0], v1 = acc[ai][bj][m][1];
;           u32x4 o;
;           o.x = pack2(v0[0] * s0[0] * siluf_(bflo(z[m].x)), v0[1] * s0[1] * siluf_(bfhi(z[m].x)));
;           o.y = pack2(v0[2] * s0[2] * siluf_(bflo(z[m].y)), v0[3] * s0[3] * siluf_(bfhi(z[m].y)));
;           o.z = pack2(v1[0] * s1[0] * siluf_(bflo(z[m].z)), v1[1] * s1[1] * siluf_(bfhi(z[m].z)));
;           o.w = pack2(v1[2] * s1[2] * siluf_(bflo(z[m].w)), v1[3] * s1[3] * siluf_(bfhi(z[m].w)));
;           *(u32x4*)(y0 + row * DM + c) = o;
	v_add_f32_e32 v2, 1.0, v2
	v_rcp_f32_e32 v23, v2
	s_nop 0
	v_pk_mul_f32 v[20:21], v[22:23], v[20:21]
	s_nop 0
	v_mul_f32_e32 v2, v20, v21
	v_and_b32_e32 v21, 0xffff0000, v40
	v_mul_f32_e32 v16, 0xbfb8aa3b, v21
	v_exp_f32_e32 v16, v16
	v_mov_b32_e32 v22, v17
	v_mov_b32_e32 v20, v73
	v_add_f32_e32 v16, 1.0, v16
	v_rcp_f32_e32 v23, v16
	s_nop 0
	v_pk_mul_f32 v[16:17], v[22:23], v[20:21]
	s_nop 0
	v_mul_f32_e32 v16, v16, v17
	v_lshlrev_b32_e32 v21, 16, v41
	v_cvt_pk_bf16_f32 v16, v2, v16
	v_mul_f32_e32 v2, 0xbfb8aa3b, v21
	v_exp_f32_e32 v2, v2
	v_mov_b32_e32 v22, v18
	v_mov_b32_e32 v20, v74
	v_add_f32_e32 v2, 1.0, v2
	v_rcp_f32_e32 v23, v2
	s_nop 0
	v_pk_mul_f32 v[20:21], v[22:23], v[20:21]
	s_nop 0
	v_mul_f32_e32 v2, v20, v21
	v_and_b32_e32 v21, 0xffff0000, v41
	v_mul_f32_e32 v17, 0xbfb8aa3b, v21
	v_exp_f32_e32 v17, v17
	v_mov_b32_e32 v22, v19
	v_mov_b32_e32 v20, v75
	v_add_f32_e32 v17, 1.0, v17
	v_rcp_f32_e32 v23, v17
	s_nop 0
	v_pk_mul_f32 v[18:19], v[22:23], v[20:21]
	s_nop 0
	v_mul_f32_e32 v17, v18, v19
	v_lshlrev_b32_e32 v19, 16, v42
	v_cvt_pk_bf16_f32 v17, v2, v17
	v_mul_f32_e32 v2, 0xbfb8aa3b, v19
	v_exp_f32_e32 v2, v2
	v_mov_b32_e32 v20, v12
	v_mov_b32_e32 v18, v68
	v_add_f32_e32 v2, 1.0, v2
	v_rcp_f32_e32 v21, v2
	s_nop 0
	v_pk_mul_f32 v[18:19], v[20:21], v[18:19]
	s_nop 0
	v_mul_f32_e32 v2, v18, v19
	v_and_b32_e32 v19, 0xffff0000, v42
	v_mul_f32_e32 v12, 0xbfb8aa3b, v19
	v_exp_f32_e32 v12, v12
	v_mov_b32_e32 v20, v13
	v_mov_b32_e32 v18, v69
	v_add_f32_e32 v12, 1.0, v12
	v_rcp_f32_e32 v21, v12
	s_nop 0
	v_pk_mul_f32 v[12:13], v[20:21], v[18:19]
	s_nop 0
	v_mul_f32_e32 v12, v12, v13
	v_lshlrev_b32_e32 v13, 16, v43
	v_cvt_pk_bf16_f32 v18, v2, v12
	v_mul_f32_e32 v2, 0xbfb8aa3b, v13
	v_exp_f32_e32 v2, v2
	v_mov_b32_e32 v20, v14
	v_mov_b32_e32 v12, v70
	v_mov_b32_e32 v14, v8
	v_add_f32_e32 v2, 1.0, v2
	v_rcp_f32_e32 v21, v2
	s_nop 0
	v_pk_mul_f32 v[12:13], v[20:21], v[12:13]
	s_nop 0
	v_mul_f32_e32 v2, v12, v13
	v_and_b32_e32 v13, 0xffff0000, v43
	v_mul_f32_e32 v12, 0xbfb8aa3b, v13
	v_exp_f32_e32 v12, v12
	v_mov_b32_e32 v20, v15
	v_add_f32_e32 v12, 1.0, v12
	v_rcp_f32_e32 v21, v12
	v_mov_b32_e32 v12, v71
	v_pk_mul_f32 v[12:13], v[20:21], v[12:13]
	s_nop 0
	v_mul_f32_e32 v12, v12, v13
	v_lshlrev_b32_e32 v13, 16, v36
	v_cvt_pk_bf16_f32 v19, v2, v12
	v_mul_f32_e32 v2, 0xbfb8aa3b, v13
	v_exp_f32_e32 v2, v2
	v_mov_b32_e32 v12, v72
	flat_store_dwordx4 v[104:105], v[16:19] offset:256
	v_add_f32_e32 v2, 1.0, v2
	v_rcp_f32_e32 v15, v2
	s_nop 0
	v_pk_mul_f32 v[12:13], v[14:15], v[12:13]
	s_nop 0
	v_mul_f32_e32 v2, v12, v13
	v_and_b32_e32 v13, 0xffff0000, v36
	v_mul_f32_e32 v8, 0xbfb8aa3b, v13
	v_exp_f32_e32 v8, v8
	v_mov_b32_e32 v14, v9
	v_mov_b32_e32 v12, v73
	v_add_f32_e32 v8, 1.0, v8
	v_rcp_f32_e32 v15, v8
	s_nop 0
	v_pk_mul_f32 v[8:9], v[14:15], v[12:13]
	s_nop 0
	v_mul_f32_e32 v8, v8, v9
	v_lshlrev_b32_e32 v13, 16, v37
	v_cvt_pk_bf16_f32 v8, v2, v8
	v_mul_f32_e32 v2, 0xbfb8aa3b, v13
	v_exp_f32_e32 v2, v2
	v_mov_b32_e32 v14, v10
	v_mov_b32_e32 v12, v74
	v_add_f32_e32 v2, 1.0, v2
	v_rcp_f32_e32 v15, v2
	s_nop 0
	v_pk_mul_f32 v[12:13], v[14:15], v[12:13]
	s_nop 0
	v_mul_f32_e32 v2, v12, v13
	v_and_b32_e32 v13, 0xffff0000, v37
	v_mul_f32_e32 v9, 0xbfb8aa3b, v13
	v_exp_f32_e32 v9, v9
	v_mov_b32_e32 v14, v11
	v_mov_b32_e32 v12, v75
	v_add_f32_e32 v9, 1.0, v9
	v_rcp_f32_e32 v15, v9
	s_nop 0
	v_pk_mul_f32 v[10:11], v[14:15], v[12:13]
	s_nop 0
	v_mul_f32_e32 v9, v10, v11
	v_lshlrev_b32_e32 v11, 16, v38
	v_cvt_pk_bf16_f32 v9, v2, v9
	v_mul_f32_e32 v2, 0xbfb8aa3b, v11
	v_exp_f32_e32 v2, v2
	v_mov_b32_e32 v12, v4
	v_mov_b32_e32 v10, v68
	v_add_f32_e32 v2, 1.0, v2
	v_rcp_f32_e32 v13, v2
	s_nop 0
	v_pk_mul_f32 v[10:11], v[12:13], v[10:11]
	s_nop 0
	v_mul_f32_e32 v2, v10, v11
	v_and_b32_e32 v11, 0xffff0000, v38
	v_mul_f32_e32 v4, 0xbfb8aa3b, v11
	v_exp_f32_e32 v4, v4
	v_mov_b32_e32 v12, v5
	v_mov_b32_e32 v10, v69
	v_add_f32_e32 v4, 1.0, v4
	v_rcp_f32_e32 v13, v4
	s_nop 0
	v_pk_mul_f32 v[4:5], v[12:13], v[10:11]
	s_nop 0
	v_mul_f32_e32 v4, v4, v5
	v_lshlrev_b32_e32 v5, 16, v39
	v_cvt_pk_bf16_f32 v10, v2, v4
	v_mul_f32_e32 v2, 0xbfb8aa3b, v5
	v_exp_f32_e32 v2, v2
	v_mov_b32_e32 v12, v6
	v_mov_b32_e32 v4, v70
	v_add_f32_e32 v2, 1.0, v2
	v_rcp_f32_e32 v13, v2
	s_nop 0
	v_pk_mul_f32 v[4:5], v[12:13], v[4:5]
	s_nop 0
	v_mul_f32_e32 v2, v4, v5
	v_and_b32_e32 v5, 0xffff0000, v39
	v_mul_f32_e32 v4, 0xbfb8aa3b, v5
	v_exp_f32_e32 v4, v4
	v_mov_b32_e32 v12, v7
	v_add_f32_e32 v4, 1.0, v4
	v_rcp_f32_e32 v13, v4
	v_mov_b32_e32 v4, v71
	v_pk_mul_f32 v[4:5], v[12:13], v[4:5]
	s_nop 0
	v_mul_f32_e32 v4, v4, v5
	v_cvt_pk_bf16_f32 v11, v2, v4
	flat_store_dwordx4 v[92:93], v[8:11] offset:256
	s_cbranch_vccz .LBB0_482
	s_waitcnt vmcnt(0)
	v_readlane_b32 s44, v244, 59
	v_readlane_b32 s40, v243, 18
	s_cmpk_gt_u32 s24, 0xff
	s_mov_b32 s43, 0x800000
	v_readlane_b32 s45, v244, 60
	v_readlane_b32 s46, v244, 61
	v_readlane_b32 s47, v244, 62
	v_readlane_b32 s48, v244, 63
	v_readlane_b32 s49, v243, 0
	v_readlane_b32 s50, v243, 1
	v_readlane_b32 s51, v243, 2
	v_readlane_b32 s41, v243, 19
	s_cbranch_scc1 .LBB0_489
	s_barrier

; #define PG8_WAIT_V(n) asm volatile("s_waitcnt vmcnt(" #n ")" ::: "memory")
; #define PG8_WAIT_L(n) asm volatile("s_waitcnt lgkmcnt(" #n ")" ::: "memory")
; #define PG8_BAR __builtin_amdgcn_s_barrier()
; #define PG8_SCHED __builtin_amdgcn_sched_barrier(0)
; template <class Epi, class AddrA, class AddrB>
; __device__ __forceinline__ void gemm_phase(const Sched S, const int lda, const int ldb, const int K, const AddrA addrA,
;                                            const AddrB addrB, const Epi E) {
;     ...
;       PG8_LDB(B0, 0, 0); PG8_SCHED; PG8_LDA(At, 0, 0); PG8_STAGE(PG8_SA(1, 1), a1 + hstepA, voffA);
;       PG8_WAIT_L(8); PG8_BAR; PG8_WAIT_L(0); PG8_MMA(0, 0, At, B0); PG8_BAR; PG8_SCHED;
;       PG8_LDB(B1, 0, 1); PG8_STAGE(PG8_SB(0, 0), b2, voffB);
;       PG8_BAR; PG8_WAIT_L(0); PG8_MMA(0, 1, At, B1); PG8_BAR;
;       PG8_LDA(At, 0, 1); PG8_STAGE(PG8_SA(0, 0), a2, voffA);
;       PG8_BAR; PG8_WAIT_L(0); PG8_MMA(1, 0, At, B0); PG8_BAR; PG8_SCHED;
;       PG8_STAGE(PG8_SB(0, 1), b2 + hstepB, voffB);
;       PG8_WAIT_V(6); PG8_BAR; PG8_MMA(1, 1, At, B1); PG8_BAR;
.LBB0_543:
	s_add_i32 s43, 0, 0x10000
	v_add_u32_e32 v0, s43, v167
	ds_read_b128 v[132:135], v0
	ds_read_b128 v[136:139], v0 offset:1024
	ds_read_b128 v[140:143], v0 offset:2048
	ds_read_b128 v[144:147], v0 offset:3072
	v_lshl_add_u64 v[0:1], s[2:3], 0, v[180:181]
	s_add_i32 m0, s28, 0xc000
	ds_read_b128 v[148:151], v188
	ds_read_b128 v[152:155], v188 offset:1024
	ds_read_b128 v[156:159], v188 offset:2048
	ds_read_b128 v[160:163], v188 offset:3072
	ds_read_b128 v[182:185], v188 offset:4096
	ds_read_b128 v[190:193], v188 offset:5120
	ds_read_b128 v[194:197], v188 offset:6144
	ds_read_b128 v[212:215], v188 offset:7168
	global_load_lds_dwordx4 v[0:1], off
	v_lshl_add_u64 v[0:1], s[2:3], 0, v[178:179]
	s_add_i32 m0, s28, 0xe000
	s_nop 0
	global_load_lds_dwordx4 v[0:1], off
	s_waitcnt lgkmcnt(6)
	s_setprio 1
	s_barrier
	v_mfma_f32_16x16x32_bf16 v[128:131], v[132:135], v[148:151], v[128:131]
	v_mfma_f32_16x16x32_bf16 v[128:131], v[136:139], v[152:155], v[128:131]
	s_waitcnt lgkmcnt(0)
	v_mfma_f32_16x16x32_bf16 v[120:123], v[132:135], v[156:159], v[120:123]
	v_mfma_f32_16x16x32_bf16 v[120:123], v[136:139], v[160:163], v[120:123]
	v_mfma_f32_16x16x32_bf16 v[112:115], v[132:135], v[182:185], v[112:115]
	v_mfma_f32_16x16x32_bf16 v[112:115], v[136:139], v[190:193], v[112:115]
	v_mfma_f32_16x16x32_bf16 v[104:107], v[132:135], v[194:197], v[104:107]
	v_mfma_f32_16x16x32_bf16 v[104:107], v[136:139], v[212:215], v[104:107]
	v_mfma_f32_16x16x32_bf16 v[124:127], v[140:143], v[148:151], v[124:127]
	v_mfma_f32_16x16x32_bf16 v[124:127], v[144:147], v[152:155], v[124:127]
	v_mfma_f32_16x16x32_bf16 v[116:119], v[140:143], v[156:159], v[116:119]
	v_mfma_f32_16x16x32_bf16 v[116:119], v[144:147], v[160:163], v[116:119]
	v_mfma_f32_16x16x32_bf16 v[108:111], v[140:143], v[182:185], v[108:111]
	v_mfma_f32_16x16x32_bf16 v[108:111], v[144:147], v[190:193], v[108:111]
	v_mfma_f32_16x16x32_bf16 v[100:103], v[140:143], v[194:197], v[100:103]
	v_mfma_f32_16x16x32_bf16 v[100:103], v[144:147], v[212:215], v[100:103]
	s_barrier
	s_setprio 0
	s_add_u32 s4, s2, 0xfff80080
	s_addc_u32 s5, s3, -1
	s_cmp_eq_u32 s42, 28
	s_cselect_b32 s7, s1, s5
	s_cselect_b32 s6, s9, s4
	s_cselect_b32 s5, s13, s41
	s_cselect_b32 s4, s15, s33
	s_add_i32 s46, 0, 0x14000
	v_add_u32_e32 v0, s46, v167
	s_add_i32 s43, s43, s27
	ds_read_b128 v[216:219], v0
	ds_read_b128 v[220:223], v0 offset:1024
	ds_read_b128 v[224:227], v0 offset:2048
	ds_read_b128 v[228:231], v0 offset:3072
	v_lshl_add_u64 v[0:1], s[4:5], 0, v[172:173]
	s_mov_b32 m0, s43
	v_lshl_add_u64 v[232:233], s[4:5], 0, v[168:169]
	global_load_lds_dwordx4 v[0:1], off
	s_add_i32 m0, s43, 0x2000
	s_nop 0
	global_load_lds_dwordx4 v[232:233], off
	s_mov_b32 m0, s28
	v_lshl_add_u64 v[234:235], s[6:7], 0, v[174:175]
	s_waitcnt lgkmcnt(2)
	s_setprio 1
	s_barrier
	v_mfma_f32_16x16x32_bf16 v[96:99], v[216:219], v[148:151], v[96:99]
	v_mfma_f32_16x16x32_bf16 v[96:99], v[220:223], v[152:155], v[96:99]
	s_waitcnt lgkmcnt(0)
	v_mfma_f32_16x16x32_bf16 v[88:91], v[216:219], v[156:159], v[88:91]
	v_mfma_f32_16x16x32_bf16 v[88:91], v[220:223], v[160:163], v[88:91]
	v_mfma_f32_16x16x32_bf16 v[80:83], v[216:219], v[182:185], v[80:83]
	v_mfma_f32_16x16x32_bf16 v[80:83], v[220:223], v[190:193], v[80:83]
	v_mfma_f32_16x16x32_bf16 v[72:75], v[216:219], v[194:197], v[72:75]
	v_mfma_f32_16x16x32_bf16 v[72:75], v[220:223], v[212:215], v[72:75]
	v_mfma_f32_16x16x32_bf16 v[92:95], v[224:227], v[148:151], v[92:95]
	v_mfma_f32_16x16x32_bf16 v[92:95], v[228:231], v[152:155], v[92:95]
	v_mfma_f32_16x16x32_bf16 v[84:87], v[224:227], v[156:159], v[84:87]
	v_mfma_f32_16x16x32_bf16 v[84:87], v[228:231], v[160:163], v[84:87]
	v_mfma_f32_16x16x32_bf16 v[76:79], v[224:227], v[182:185], v[76:79]
	v_mfma_f32_16x16x32_bf16 v[76:79], v[228:231], v[190:193], v[76:79]
	v_mfma_f32_16x16x32_bf16 v[68:71], v[224:227], v[194:197], v[68:71]
	v_mfma_f32_16x16x32_bf16 v[68:71], v[228:231], v[212:215], v[68:71]
	s_barrier
	s_setprio 0
	ds_read_b128 v[148:151], v188 offset:16384
	ds_read_b128 v[152:155], v188 offset:17408
	ds_read_b128 v[156:159], v188 offset:18432
	ds_read_b128 v[160:163], v188 offset:19456
	ds_read_b128 v[182:185], v188 offset:20480
	ds_read_b128 v[190:193], v188 offset:21504
	ds_read_b128 v[194:197], v188 offset:22528
	ds_read_b128 v[212:215], v188 offset:23552
	global_load_lds_dwordx4 v[234:235], off
	v_lshl_add_u64 v[236:237], s[6:7], 0, v[170:171]
	s_mov_b32 m0, s29
	s_nop 0
	global_load_lds_dwordx4 v[236:237], off
	s_waitcnt lgkmcnt(6)
	s_setprio 1
	s_barrier
	v_mfma_f32_16x16x32_bf16 v[64:67], v[132:135], v[148:151], v[64:67]
	v_mfma_f32_16x16x32_bf16 v[64:67], v[136:139], v[152:155], v[64:67]
	s_waitcnt lgkmcnt(0)
	v_mfma_f32_16x16x32_bf16 v[56:59], v[132:135], v[156:159], v[56:59]
	v_mfma_f32_16x16x32_bf16 v[56:59], v[136:139], v[160:163], v[56:59]
	v_mfma_f32_16x16x32_bf16 v[48:51], v[132:135], v[182:185], v[48:51]
	v_mfma_f32_16x16x32_bf16 v[48:51], v[136:139], v[190:193], v[48:51]
	v_mfma_f32_16x16x32_bf16 v[40:43], v[132:135], v[194:197], v[40:43]
	v_mfma_f32_16x16x32_bf16 v[40:43], v[136:139], v[212:215], v[40:43]
	v_mfma_f32_16x16x32_bf16 v[60:63], v[140:143], v[148:151], v[60:63]
	v_mfma_f32_16x16x32_bf16 v[60:63], v[144:147], v[152:155], v[60:63]
	v_mfma_f32_16x16x32_bf16 v[52:55], v[140:143], v[156:159], v[52:55]
	v_mfma_f32_16x16x32_bf16 v[52:55], v[144:147], v[160:163], v[52:55]
	v_mfma_f32_16x16x32_bf16 v[44:47], v[140:143], v[182:185], v[44:47]
	v_mfma_f32_16x16x32_bf16 v[44:47], v[144:147], v[190:193], v[44:47]
	v_mfma_f32_16x16x32_bf16 v[36:39], v[140:143], v[194:197], v[36:39]
	v_mfma_f32_16x16x32_bf16 v[36:39], v[144:147], v[212:215], v[36:39]
	s_barrier
; #define PG8_WAIT_V(n) asm volatile("s_waitcnt vmcnt(" #n ")" ::: "memory")
; #define PG8_WAIT_L(n) asm volatile("s_waitcnt lgkmcnt(" #n ")" ::: "memory")
; #define PG8_BAR __builtin_amdgcn_s_barrier()
; #define PG8_SCHED __builtin_amdgcn_sched_barrier(0)
; template <class Epi, class AddrA, class AddrB>
; __device__ __forceinline__ void gemm_phase(const Sched S, const int lda, const int ldb, const int K, const AddrA addrA,
;                                            const AddrB addrB, const Epi E) {
;     ...
;       PG8_BAR; PG8_WAIT_L(0); PG8_MMA(1, 0, At, B0); PG8_BAR; PG8_SCHED;
;       PG8_STAGE(PG8_SB(0, 1), b2 + hstepB, voffB);
;       PG8_WAIT_V(6); PG8_BAR; PG8_MMA(1, 1, At, B1); PG8_BAR;
;       PG8_LDB(B0, 1, 0); PG8_SCHED; PG8_LDA(At, 1, 0); PG8_STAGE(PG8_SA(0, 1), a2 + hstepA, voffA);
;       PG8_WAIT_L(8); PG8_BAR; PG8_WAIT_L(0); PG8_MMA(0, 0, At, B0); PG8_BAR; PG8_SCHED;
;       PG8_LDB(B1, 1, 1); PG8_STAGE(PG8_SB(1, 0), b3, voffB);
;       PG8_BAR; PG8_WAIT_L(0); PG8_MMA(0, 1, At, B1); PG8_BAR;
;       PG8_LDA(At, 1, 1); PG8_STAGE(PG8_SA(1, 0), a3, voffA);
;       PG8_BAR; PG8_WAIT_L(0); PG8_MMA(1, 0, At, B0); PG8_BAR; PG8_SCHED;
	s_setprio 0
	s_add_u32 s44, s4, 0x80000
	s_addc_u32 s45, s5, 0
	s_add_i32 s43, s46, s27
	v_lshl_add_u64 v[132:133], s[44:45], 0, v[172:173]
	s_mov_b32 m0, s43
	s_nop 0
	global_load_lds_dwordx4 v[132:133], off
	v_lshl_add_u64 v[132:133], s[44:45], 0, v[168:169]
	s_add_i32 m0, s43, 0x2000
	s_nop 0
	global_load_lds_dwordx4 v[132:133], off
	s_add_i32 s43, 0, 0x18000
	v_add_u32_e32 v2, s43, v167
	s_waitcnt vmcnt(6)
	s_setprio 1
	s_barrier
	v_mfma_f32_16x16x32_bf16 v[32:35], v[216:219], v[148:151], v[32:35]
	v_mfma_f32_16x16x32_bf16 v[32:35], v[220:223], v[152:155], v[32:35]
	v_mfma_f32_16x16x32_bf16 v[24:27], v[216:219], v[156:159], v[24:27]
	v_mfma_f32_16x16x32_bf16 v[24:27], v[220:223], v[160:163], v[24:27]
	v_mfma_f32_16x16x32_bf16 v[16:19], v[216:219], v[182:185], v[16:19]
	v_mfma_f32_16x16x32_bf16 v[16:19], v[220:223], v[190:193], v[16:19]
	v_mfma_f32_16x16x32_bf16 v[8:11], v[216:219], v[194:197], v[8:11]
	v_mfma_f32_16x16x32_bf16 v[8:11], v[220:223], v[212:215], v[8:11]
	v_mfma_f32_16x16x32_bf16 v[28:31], v[224:227], v[148:151], v[28:31]
	v_mfma_f32_16x16x32_bf16 v[28:31], v[228:231], v[152:155], v[28:31]
	v_mfma_f32_16x16x32_bf16 v[20:23], v[224:227], v[156:159], v[20:23]
	v_mfma_f32_16x16x32_bf16 v[20:23], v[228:231], v[160:163], v[20:23]
	v_mfma_f32_16x16x32_bf16 v[12:15], v[224:227], v[182:185], v[12:15]
	v_mfma_f32_16x16x32_bf16 v[12:15], v[228:231], v[190:193], v[12:15]
	v_mfma_f32_16x16x32_bf16 v[4:7], v[224:227], v[194:197], v[4:7]
	v_mfma_f32_16x16x32_bf16 v[4:7], v[228:231], v[212:215], v[4:7]
	s_barrier
	s_setprio 0
	ds_read_b128 v[132:135], v2
	ds_read_b128 v[136:139], v2 offset:1024
	ds_read_b128 v[140:143], v2 offset:2048
	ds_read_b128 v[144:147], v2 offset:3072
	s_add_u32 s6, s6, 0x80000
	s_addc_u32 s7, s7, 0
	s_mov_b32 m0, s30
	v_lshl_add_u64 v[216:217], s[6:7], 0, v[174:175]
	ds_read_b128 v[148:151], v188 offset:32768
	ds_read_b128 v[152:155], v188 offset:33792
	ds_read_b128 v[156:159], v188 offset:34816
	ds_read_b128 v[160:163], v188 offset:35840
	ds_read_b128 v[182:185], v188 offset:36864
	ds_read_b128 v[190:193], v188 offset:37888
	ds_read_b128 v[194:197], v188 offset:38912
	ds_read_b128 v[212:215], v188 offset:39936
	global_load_lds_dwordx4 v[216:217], off
	v_lshl_add_u64 v[216:217], s[6:7], 0, v[170:171]
	s_mov_b32 m0, s31
	s_nop 0
	global_load_lds_dwordx4 v[216:217], off
	s_waitcnt lgkmcnt(6)
	s_setprio 1
	s_barrier
	v_mfma_f32_16x16x32_bf16 v[128:131], v[132:135], v[148:151], v[128:131]
	v_mfma_f32_16x16x32_bf16 v[128:131], v[136:139], v[152:155], v[128:131]
	s_waitcnt lgkmcnt(0)
	v_mfma_f32_16x16x32_bf16 v[120:123], v[132:135], v[156:159], v[120:123]
	v_mfma_f32_16x16x32_bf16 v[120:123], v[136:139], v[160:163], v[120:123]
	v_mfma_f32_16x16x32_bf16 v[112:115], v[132:135], v[182:185], v[112:115]
	v_mfma_f32_16x16x32_bf16 v[112:115], v[136:139], v[190:193], v[112:115]
	v_mfma_f32_16x16x32_bf16 v[104:107], v[132:135], v[194:197], v[104:107]
	v_mfma_f32_16x16x32_bf16 v[104:107], v[136:139], v[212:215], v[104:107]
	v_mfma_f32_16x16x32_bf16 v[124:127], v[140:143], v[148:151], v[124:127]
	v_mfma_f32_16x16x32_bf16 v[124:127], v[144:147], v[152:155], v[124:127]
	v_mfma_f32_16x16x32_bf16 v[116:119], v[140:143], v[156:159], v[116:119]
	v_mfma_f32_16x16x32_bf16 v[116:119], v[144:147], v[160:163], v[116:119]
	v_mfma_f32_16x16x32_bf16 v[108:111], v[140:143], v[182:185], v[108:111]
	v_mfma_f32_16x16x32_bf16 v[108:111], v[144:147], v[190:193], v[108:111]
	v_mfma_f32_16x16x32_bf16 v[100:103], v[140:143], v[194:197], v[100:103]
	v_mfma_f32_16x16x32_bf16 v[100:103], v[144:147], v[212:215], v[100:103]
	s_barrier
	s_setprio 0
	s_add_i32 s6, 0, 0x1c000
	s_add_i32 s7, s43, s27
	v_add_u32_e32 v2, s6, v167
	v_lshl_add_u64 v[0:1], v[0:1], 0, s[52:53]
	s_mov_b32 m0, s7
	ds_read_b128 v[216:219], v2
	ds_read_b128 v[220:223], v2 offset:1024
	ds_read_b128 v[224:227], v2 offset:2048
	ds_read_b128 v[228:231], v2 offset:3072
	global_load_lds_dwordx4 v[0:1], off
	v_lshl_add_u64 v[0:1], v[232:233], 0, s[52:53]
	s_add_i32 m0, s7, 0x2000
	s_nop 0
	global_load_lds_dwordx4 v[0:1], off
	s_mov_b32 m0, s38
	v_lshl_add_u64 v[0:1], v[234:235], 0, s[52:53]
	s_waitcnt lgkmcnt(2)
	s_setprio 1
	s_barrier
	v_mfma_f32_16x16x32_bf16 v[96:99], v[216:219], v[148:151], v[96:99]
	v_mfma_f32_16x16x32_bf16 v[96:99], v[220:223], v[152:155], v[96:99]
	s_waitcnt lgkmcnt(0)
	v_mfma_f32_16x16x32_bf16 v[88:91], v[216:219], v[156:159], v[88:91]
	v_mfma_f32_16x16x32_bf16 v[88:91], v[220:223], v[160:163], v[88:91]
	v_mfma_f32_16x16x32_bf16 v[80:83], v[216:219], v[182:185], v[80:83]
	v_mfma_f32_16x16x32_bf16 v[80:83], v[220:223], v[190:193], v[80:83]
	v_mfma_f32_16x16x32_bf16 v[72:75], v[216:219], v[194:197], v[72:75]
	v_mfma_f32_16x16x32_bf16 v[72:75], v[220:223], v[212:215], v[72:75]
	v_mfma_f32_16x16x32_bf16 v[92:95], v[224:227], v[148:151], v[92:95]
	v_mfma_f32_16x16x32_bf16 v[92:95], v[228:231], v[152:155], v[92:95]
	v_mfma_f32_16x16x32_bf16 v[84:87], v[224:227], v[156:159], v[84:87]
	v_mfma_f32_16x16x32_bf16 v[84:87], v[228:231], v[160:163], v[84:87]
	v_mfma_f32_16x16x32_bf16 v[76:79], v[224:227], v[182:185], v[76:79]
	v_mfma_f32_16x16x32_bf16 v[76:79], v[228:231], v[190:193], v[76:79]
	v_mfma_f32_16x16x32_bf16 v[68:71], v[224:227], v[194:197], v[68:71]
	v_mfma_f32_16x16x32_bf16 v[68:71], v[228:231], v[212:215], v[68:71]
	s_barrier
	s_setprio 0
	ds_read_b128 v[148:151], v188 offset:49152
	ds_read_b128 v[152:155], v188 offset:50176
	ds_read_b128 v[156:159], v188 offset:51200
	ds_read_b128 v[160:163], v188 offset:52224
	ds_read_b128 v[182:185], v188 offset:53248
	ds_read_b128 v[190:193], v188 offset:54272
	ds_read_b128 v[194:197], v188 offset:55296
	ds_read_b128 v[212:215], v188 offset:56320
	global_load_lds_dwordx4 v[0:1], off
	v_lshl_add_u64 v[0:1], v[236:237], 0, s[52:53]
	s_mov_b32 m0, s39
	s_nop 0
	global_load_lds_dwordx4 v[0:1], off
	s_waitcnt lgkmcnt(6)
	s_setprio 1
	s_barrier
; #define PG8_WAIT_V(n) asm volatile("s_waitcnt vmcnt(" #n ")" ::: "memory")
; #define PG8_WAIT_L(n) asm volatile("s_waitcnt lgkmcnt(" #n ")" ::: "memory")
; #define PG8_BAR __builtin_amdgcn_s_barrier()
; #define PG8_SCHED __builtin_amdgcn_sched_barrier(0)
; template <class Epi, class AddrA, class AddrB>
; __device__ __forceinline__ void gemm_phase(const Sched S, const int lda, const int ldb, const int K, const AddrA addrA,
;                                            const AddrB addrB, const Epi E) {
;     ...
;       PG8_BAR; PG8_WAIT_L(0); PG8_MMA(1, 0, At, B0); PG8_BAR; PG8_SCHED;
;       PG8_STAGE(PG8_SB(1, 1), b3 + hstepB, voffB);
;       PG8_WAIT_V(6); PG8_BAR; PG8_MMA(1, 1, At, B1); PG8_BAR;
;     }
;   __device__ __forceinline__ void operator()(EPI_ARGS) const {
;     const int col0 = u.pn * 256 + wc * 32 + 8 * fq;
;     const int br = u.br, brn = br < 2 ? br + 1 : 2;
;     const unsigned loff0 = (unsigned)((wr * 64 + fr) * PLD + wc * 32 + 8 * fq);
;     const bf16_t* pc = proj + ((size_t)((GT + br * DM) / 256 + u.pn) * MTOK + (size_t)u.pm * 256) * PLD;
;     const bf16_t* pn_ = proj + ((size_t)((GT + brn * DM) / 256 + u.pn) * MTOK + (size_t)u.pm * 256) * PLD;
;     bf16_t* mrow = merged + ((size_t)u.pm * 256 + wr * 64 + fr) * DM + col0;
; #pragma unroll
;     for (int bj = 0; bj < 2; ++bj) {
;       const int c = col0 + bj * HALF;
;       float gc[8], gn[8];
;       {
;         const f32x4 a0 = *(const f32x4*)(bg + br * DM + c), a1 = *(const f32x4*)(bg + br * DM + c + 4);
;         const f32x4 b0 = *(const f32x4*)(bg + brn * DM + c), b1 = *(const f32x4*)(bg + brn * DM + c + 4);
; #pragma unroll
;         for (int k = 0; k < 4; ++k) { gc[k] = a0[k]; gc[4 + k] = a1[k]; gn[k] = b0[k]; gn[4 + k] = b1[k]; }
;       }
; #pragma unroll
;       for (int ai = 0; ai < 2; ++ai) {
;         unsigned loff = loff0;
;         asm volatile("" : "+v"(loff));
;         u32x4 zc[4], zn[4];
; #pragma unroll
;         for (int m = 0; m < 4; ++m) {
;           const unsigned o = loff + (unsigned)((ai * HALF + m * 16) * PLD + bj * HALF);
;           zc[m] = *(const u32x4*)(pc + o);
;           zn[m] = *(const u32x4*)(pn_ + o);
;         }
;         __builtin_amdgcn_sched_barrier(0);
	v_mfma_f32_16x16x32_bf16 v[64:67], v[132:135], v[148:151], v[64:67]
	v_mfma_f32_16x16x32_bf16 v[64:67], v[136:139], v[152:155], v[64:67]
	s_waitcnt lgkmcnt(0)
	v_mfma_f32_16x16x32_bf16 v[56:59], v[132:135], v[156:159], v[56:59]
	v_mfma_f32_16x16x32_bf16 v[56:59], v[136:139], v[160:163], v[56:59]
	v_mfma_f32_16x16x32_bf16 v[48:51], v[132:135], v[182:185], v[48:51]
	v_mfma_f32_16x16x32_bf16 v[48:51], v[136:139], v[190:193], v[48:51]
	v_mfma_f32_16x16x32_bf16 v[40:43], v[132:135], v[194:197], v[40:43]
	v_mfma_f32_16x16x32_bf16 v[40:43], v[136:139], v[212:215], v[40:43]
	v_mfma_f32_16x16x32_bf16 v[60:63], v[140:143], v[148:151], v[60:63]
	v_mfma_f32_16x16x32_bf16 v[60:63], v[144:147], v[152:155], v[60:63]
	v_mfma_f32_16x16x32_bf16 v[52:55], v[140:143], v[156:159], v[52:55]
	v_mfma_f32_16x16x32_bf16 v[52:55], v[144:147], v[160:163], v[52:55]
	v_mfma_f32_16x16x32_bf16 v[44:47], v[140:143], v[182:185], v[44:47]
	v_mfma_f32_16x16x32_bf16 v[44:47], v[144:147], v[190:193], v[44:47]
	v_mfma_f32_16x16x32_bf16 v[36:39], v[140:143], v[194:197], v[36:39]
	v_mfma_f32_16x16x32_bf16 v[36:39], v[144:147], v[212:215], v[36:39]
	s_barrier
	s_setprio 0
	s_add_u32 s4, s4, 0x80080
	s_addc_u32 s5, s5, 0
	s_add_i32 s6, s6, s27
	v_lshl_add_u64 v[0:1], s[4:5], 0, v[172:173]
	s_mov_b32 m0, s6
	s_nop 0
	global_load_lds_dwordx4 v[0:1], off
	v_lshl_add_u64 v[0:1], s[4:5], 0, v[168:169]
	s_add_i32 m0, s6, 0x2000
	s_nop 0
	global_load_lds_dwordx4 v[0:1], off
	s_add_i32 s42, s42, 2
	s_add_u32 s33, s33, 0x100
	s_addc_u32 s41, s41, 0
	s_add_u32 s2, s2, 0x100
	s_addc_u32 s3, s3, 0
	s_waitcnt vmcnt(6)
	s_setprio 1
	s_barrier
	v_mfma_f32_16x16x32_bf16 v[32:35], v[216:219], v[148:151], v[32:35]
	v_mfma_f32_16x16x32_bf16 v[32:35], v[220:223], v[152:155], v[32:35]
	v_mfma_f32_16x16x32_bf16 v[24:27], v[216:219], v[156:159], v[24:27]
	v_mfma_f32_16x16x32_bf16 v[24:27], v[220:223], v[160:163], v[24:27]
	v_mfma_f32_16x16x32_bf16 v[16:19], v[216:219], v[182:185], v[16:19]
	v_mfma_f32_16x16x32_bf16 v[16:19], v[220:223], v[190:193], v[16:19]
	v_mfma_f32_16x16x32_bf16 v[8:11], v[216:219], v[194:197], v[8:11]
	v_mfma_f32_16x16x32_bf16 v[8:11], v[220:223], v[212:215], v[8:11]
	v_mfma_f32_16x16x32_bf16 v[28:31], v[224:227], v[148:151], v[28:31]
	v_mfma_f32_16x16x32_bf16 v[28:31], v[228:231], v[152:155], v[28:31]
	v_mfma_f32_16x16x32_bf16 v[20:23], v[224:227], v[156:159], v[20:23]
	v_mfma_f32_16x16x32_bf16 v[20:23], v[228:231], v[160:163], v[20:23]
	v_mfma_f32_16x16x32_bf16 v[12:15], v[224:227], v[182:185], v[12:15]
	v_mfma_f32_16x16x32_bf16 v[12:15], v[228:231], v[190:193], v[12:15]
	v_mfma_f32_16x16x32_bf16 v[4:7], v[224:227], v[194:197], v[4:7]
	v_mfma_f32_16x16x32_bf16 v[4:7], v[228:231], v[212:215], v[4:7]
	s_barrier
	s_setprio 0
	s_cmp_gt_u32 s42, 29
	s_cbranch_scc0 .LBB0_543
	s_cmp_gt_i32 s10, 1
	s_cselect_b64 s[6:7], -1, 0
	s_lshl_b32 s42, s10, 11
	s_add_i32 s2, s42, 0x4c00
	s_ashr_i32 s2, s2, 8
	s_add_i32 s2, s2, s11
	s_ashr_i32 s3, s2, 31
	s_min_i32 s1, s10, 1
	s_ashr_i32 s9, s8, 31
	s_lshl_b64 s[2:3], s[2:3], 23
	s_add_u32 s2, s34, s2
	s_addc_u32 s3, s35, s3
	s_lshl_b64 s[4:5], s[8:9], 17
	s_add_u32 s2, s2, s4
	s_addc_u32 s3, s3, s5
	s_lshl_b32 s1, s1, 11
	s_add_i32 s44, s1, 0x800
	s_addk_i32 s1, 0x5400
	s_ashr_i32 s1, s1, 8
	s_add_i32 s46, s1, s11
	s_ashr_i32 s47, s46, 31
	s_lshl_b64 s[46:47], s[46:47], 23
	s_add_u32 s1, s34, s46
	v_lshl_or_b32 v132, s11, 8, v187
	s_addc_u32 s11, s35, s47
	s_add_u32 s4, s1, s4
	s_addc_u32 s5, s11, s5
	s_ashr_i32 s43, s42, 31
	s_lshl_b64 s[8:9], s[8:9], 20
	s_ashr_i32 s45, s44, 31
	s_lshl_b64 s[42:43], s[42:43], 2
	s_add_u32 s42, s36, s42
	s_addc_u32 s43, s37, s43
	s_lshl_b64 s[44:45], s[44:45], 2
	s_add_u32 s44, s36, s44
	v_lshl_add_u64 v[0:1], v[176:177], 0, s[8:9]
	v_ashrrev_i32_e32 v133, 31, v132
	s_addc_u32 s45, s37, s45
	v_lshl_add_u64 v[0:1], v[132:133], 1, v[0:1]
	v_lshlrev_b64 v[132:133], 2, v[132:133]
	v_lshl_add_u64 v[182:183], s[42:43], 0, v[132:133]
	v_lshl_add_u64 v[184:185], s[44:45], 0, v[132:133]
	v_mov_b32_e32 v2, v186
	global_load_dwordx4 v[144:147], v[182:183], off
	global_load_dwordx4 v[136:139], v[182:183], off offset:16
	global_load_dwordx4 v[140:143], v[184:185], off
	global_load_dwordx4 v[132:135], v[184:185], off offset:16
	s_cmp_lt_i32 s10, 2
	v_lshlrev_b64 v[148:149], 1, v[2:3]
	v_lshl_add_u64 v[150:151], s[2:3], 0, v[148:149]
	v_lshl_add_u64 v[148:149], s[4:5], 0, v[148:149]
	flat_load_dwordx4 v[190:193], v[150:151]
	flat_load_dwordx4 v[160:163], v[148:149]
	v_add_u32_e32 v148, 0x1000, v2
	v_mov_b32_e32 v149, v3
	v_lshlrev_b64 v[148:149], 1, v[148:149]
	v_lshl_add_u64 v[150:151], s[2:3], 0, v[148:149]
	v_lshl_add_u64 v[148:149], s[4:5], 0, v[148:149]
	flat_load_dwordx4 v[194:197], v[150:151]
	flat_load_dwordx4 v[156:159], v[148:149]
	v_add_u32_e32 v148, 0x2000, v2
	v_mov_b32_e32 v149, v3
	v_lshlrev_b64 v[148:149], 1, v[148:149]
	v_lshl_add_u64 v[150:151], s[2:3], 0, v[148:149]
	v_lshl_add_u64 v[148:149], s[4:5], 0, v[148:149]
	v_add_u32_e32 v2, 0x3000, v2
	flat_load_dwordx4 v[234:237], v[150:151]
	flat_load_dwordx4 v[152:155], v[148:149]
	v_lshlrev_b64 v[148:149], 1, v[2:3]
	v_lshl_add_u64 v[150:151], s[2:3], 0, v[148:149]
	v_lshl_add_u64 v[148:149], s[4:5], 0, v[148:149]
	flat_load_dwordx4 v[238:241], v[150:151]
	s_nop 0
	flat_load_dwordx4 v[148:151], v[148:149]
	s_waitcnt vmcnt(0) lgkmcnt(0)
; __device__ __forceinline__ float sigmoidf_(float x) { return __builtin_amdgcn_rcpf(1.0f + __expf(-x)); }
;   __device__ __forceinline__ void operator()(EPI_ARGS) const {
;     ...
;         if (br < 2) {
; #pragma unroll
;           for (int m = 0; m < 4; ++m) {
;             float xc[8], xn[8];
;             unpack8(zc[m], xc);
;             unpack8(zn[m], xn);
; #pragma unroll
;             for (int k = 0; k < 8; ++k) {
;               const float ec = __expf(-fmaxf(xc[k] + gc[k], -40.f)), en = __expf(-fmaxf(xn[k] + gn[k], -40.f));
;               const float f = (1.0f + en) * __builtin_amdgcn_rcpf(1.0f + ec);
;               acc[ai][bj][m][k >> 2][k & 3] *= f;
;             }
;           }
;         } else {
; #pragma unroll
;           for (int m = 0; m < 4; ++m) {
;             float xc[8], y[8];
;             unpack8(zc[m], xc);
; #pragma unroll
;             for (int k = 0; k < 8; ++k) y[k] = acc[ai][bj][m][k >> 2][k & 3] * sigmoidf_(fmaxf(xc[k] + gc[k], -40.f));
;             u32x4 o;
;             o.x = pack2(y[0], y[1]); o.y = pack2(y[2], y[3]); o.z = pack2(y[4], y[5]); o.w = pack2(y[6], y[7]);
;             *(u32x4*)(mrow + (size_t)(ai * HALF + m * 16) * DM + bj * HALF) = o;
;           }
	v_lshlrev_b32_e32 v2, 16, v190
	v_and_b32_e32 v189, 0xffff0000, v190
	v_lshlrev_b32_e32 v190, 16, v191
	v_and_b32_e32 v191, 0xffff0000, v191
	v_lshlrev_b32_e32 v212, 16, v192
	v_and_b32_e32 v192, 0xffff0000, v192
	v_lshlrev_b32_e32 v213, 16, v193
	v_and_b32_e32 v193, 0xffff0000, v193
	v_add_f32_e32 v2, v144, v2
	v_add_f32_e32 v189, v145, v189
	v_add_f32_e32 v190, v146, v190
	v_add_f32_e32 v191, v147, v191
	v_add_f32_e32 v212, v136, v212
	v_add_f32_e32 v192, v137, v192
	v_add_f32_e32 v213, v138, v213
	v_add_f32_e32 v193, v139, v193
	s_mov_b64 s[8:9], -1
	v_max_f32_e32 v233, 0xc2200000, v2
	v_max_f32_e32 v232, 0xc2200000, v189
	v_max_f32_e32 v231, 0xc2200000, v190
	v_max_f32_e32 v230, 0xc2200000, v191
	v_max_f32_e32 v229, 0xc2200000, v212
	v_max_f32_e32 v228, 0xc2200000, v192
	v_max_f32_e32 v227, 0xc2200000, v213
	v_max_f32_e32 v226, 0xc2200000, v193
	v_lshlrev_b32_e32 v225, 16, v194
	v_and_b32_e32 v224, 0xffff0000, v194
	v_lshlrev_b32_e32 v223, 16, v195
	v_and_b32_e32 v222, 0xffff0000, v195
	v_lshlrev_b32_e32 v221, 16, v196
	v_and_b32_e32 v220, 0xffff0000, v196
	v_lshlrev_b32_e32 v219, 16, v197
	v_and_b32_e32 v218, 0xffff0000, v197
	v_lshlrev_b32_e32 v217, 16, v234
	v_and_b32_e32 v216, 0xffff0000, v234
	v_lshlrev_b32_e32 v215, 16, v235
	v_and_b32_e32 v214, 0xffff0000, v235
	v_lshlrev_b32_e32 v213, 16, v236
	v_and_b32_e32 v212, 0xffff0000, v236
	v_lshlrev_b32_e32 v197, 16, v237
	v_and_b32_e32 v196, 0xffff0000, v237
	v_lshlrev_b32_e32 v195, 16, v238
	v_and_b32_e32 v194, 0xffff0000, v238
	v_lshlrev_b32_e32 v193, 16, v239
	v_and_b32_e32 v192, 0xffff0000, v239
	v_lshlrev_b32_e32 v191, 16, v240
	v_and_b32_e32 v190, 0xffff0000, v240
	v_lshlrev_b32_e32 v189, 16, v241
	v_and_b32_e32 v2, 0xffff0000, v241
	s_cbranch_scc1 .LBB0_546
	v_mul_f32_e32 v234, 0xbfb8aa3b, v233
	v_mul_f32_e32 v235, 0xbfb8aa3b, v232
	v_mul_f32_e32 v236, 0xbfb8aa3b, v231
	v_exp_f32_e32 v234, v234
	v_exp_f32_e32 v235, v235
	v_exp_f32_e32 v236, v236
	v_mul_f32_e32 v237, 0xbfb8aa3b, v230
	v_exp_f32_e32 v237, v237
	v_mul_f32_e32 v238, 0xbfb8aa3b, v229
	v_mul_f32_e32 v239, 0xbfb8aa3b, v228
	v_add_f32_e32 v234, 1.0, v234
	v_add_f32_e32 v235, 1.0, v235
	v_add_f32_e32 v236, 1.0, v236
	v_exp_f32_e32 v238, v238
	v_exp_f32_e32 v239, v239
	v_mul_f32_e32 v240, 0xbfb8aa3b, v227
	v_mul_f32_e32 v241, 0xbfb8aa3b, v226
	v_rcp_f32_e32 v234, v234
	v_rcp_f32_e32 v235, v235
	v_rcp_f32_e32 v236, v236
	v_add_f32_e32 v237, 1.0, v237
	v_exp_f32_e32 v240, v240
	v_exp_f32_e32 v241, v241
	v_rcp_f32_e32 v237, v237
	v_add_f32_e32 v238, 1.0, v238
	v_add_f32_e32 v239, 1.0, v239
	v_mul_f32_e32 v234, v128, v234
	v_mul_f32_e32 v235, v129, v235
	v_mul_f32_e32 v236, v130, v236
	v_rcp_f32_e32 v238, v238
	v_rcp_f32_e32 v239, v239
	v_add_f32_e32 v240, 1.0, v240
	v_add_f32_e32 v241, 1.0, v241
	v_mul_f32_e32 v237, v131, v237
	v_rcp_f32_e32 v240, v240
	v_rcp_f32_e32 v241, v241
	v_cvt_pk_bf16_f32 v234, v234, v235
	v_cvt_pk_bf16_f32 v235, v236, v237
	v_add_f32_e32 v236, v144, v225
	v_max_f32_e32 v236, 0xc2200000, v236
	v_mul_f32_e32 v236, 0xbfb8aa3b, v236
	v_mul_f32_e32 v238, v124, v238
	v_mul_f32_e32 v239, v125, v239
	v_exp_f32_e32 v242, v236
	v_cvt_pk_bf16_f32 v236, v238, v239
	v_mul_f32_e32 v240, v126, v240
	v_mul_f32_e32 v241, v127, v241
	v_cvt_pk_bf16_f32 v237, v240, v241
	flat_store_dwordx4 v[0:1], v[234:237]
	v_add_f32_e32 v238, v136, v221
	v_max_f32_e32 v238, 0xc2200000, v238
	v_add_f32_e32 v235, v145, v224
	v_add_f32_e32 v236, v146, v223
	v_max_f32_e32 v235, 0xc2200000, v235
	v_max_f32_e32 v236, 0xc2200000, v236
	v_add_f32_e32 v237, v147, v222
	v_add_f32_e32 v239, v137, v220
	v_mul_f32_e32 v235, 0xbfb8aa3b, v235
	v_mul_f32_e32 v236, 0xbfb8aa3b, v236
	v_max_f32_e32 v237, 0xc2200000, v237
	v_mul_f32_e32 v238, 0xbfb8aa3b, v238
	v_max_f32_e32 v239, 0xc2200000, v239
	v_exp_f32_e32 v235, v235
	v_exp_f32_e32 v236, v236
	v_mul_f32_e32 v237, 0xbfb8aa3b, v237
	v_exp_f32_e32 v238, v238
	v_mul_f32_e32 v239, 0xbfb8aa3b, v239
	v_add_f32_e32 v240, v138, v219
	v_exp_f32_e32 v237, v237
	v_exp_f32_e32 v239, v239
	v_max_f32_e32 v240, 0xc2200000, v240
	v_add_f32_e32 v241, v139, v218
	v_mul_f32_e32 v240, 0xbfb8aa3b, v240
	v_max_f32_e32 v241, 0xc2200000, v241
	v_exp_f32_e32 v240, v240
	v_mul_f32_e32 v241, 0xbfb8aa3b, v241
	v_add_f32_e32 v234, 1.0, v242
	v_add_f32_e32 v235, 1.0, v235
	v_add_f32_e32 v236, 1.0, v236
	v_add_f32_e32 v238, 1.0, v238
	v_exp_f32_e32 v241, v241
	v_rcp_f32_e32 v234, v234
	v_rcp_f32_e32 v235, v235
	v_rcp_f32_e32 v236, v236
	v_add_f32_e32 v237, 1.0, v237
	v_rcp_f32_e32 v238, v238
	v_add_f32_e32 v239, 1.0, v239
	v_rcp_f32_e32 v237, v237
	v_rcp_f32_e32 v239, v239
	v_add_f32_e32 v240, 1.0, v240
	v_rcp_f32_e32 v240, v240
	v_add_f32_e32 v241, 1.0, v241
	v_mul_f32_e32 v234, v120, v234
; __device__ __forceinline__ float sigmoidf_(float x) { return __builtin_amdgcn_rcpf(1.0f + __expf(-x)); }
;   __device__ __forceinline__ void operator()(EPI_ARGS) const {
;     ...
;           for (int m = 0; m < 4; ++m) {
;             float xc[8], y[8];
;             unpack8(zc[m], xc);
; #pragma unroll
;             for (int k = 0; k < 8; ++k) y[k] = acc[ai][bj][m][k >> 2][k & 3] * sigmoidf_(fmaxf(xc[k] + gc[k], -40.f));
;             u32x4 o;
;             o.x = pack2(y[0], y[1]); o.y = pack2(y[2], y[3]); o.z = pack2(y[4], y[5]); o.w = pack2(y[6], y[7]);
;             *(u32x4*)(mrow + (size_t)(ai * HALF + m * 16) * DM + bj * HALF) = o;
;           }
	v_mul_f32_e32 v235, v121, v235
	v_mul_f32_e32 v236, v122, v236
	v_rcp_f32_e32 v241, v241
	v_mul_f32_e32 v238, v116, v238
	v_mul_f32_e32 v237, v123, v237
	v_mul_f32_e32 v239, v117, v239
	v_cvt_pk_bf16_f32 v234, v234, v235
	v_cvt_pk_bf16_f32 v235, v236, v237
	v_cvt_pk_bf16_f32 v236, v238, v239
	v_add_f32_e32 v238, v144, v217
	v_max_f32_e32 v238, 0xc2200000, v238
	v_mul_f32_e32 v240, v118, v240
	v_mul_f32_e32 v238, 0xbfb8aa3b, v238
	v_mul_f32_e32 v241, v119, v241
	v_cvt_pk_bf16_f32 v237, v240, v241
	v_exp_f32_e32 v240, v238
	v_add_co_u32_e32 v238, vcc, s67, v0
	v_add_f32_e32 v241, v139, v196
	s_nop 0
	v_addc_co_u32_e32 v239, vcc, 0, v1, vcc
	flat_store_dwordx4 v[238:239], v[234:237]
	v_add_f32_e32 v238, v136, v213
	v_max_f32_e32 v238, 0xc2200000, v238
	v_add_f32_e32 v235, v145, v216
	v_add_f32_e32 v236, v146, v215
	v_max_f32_e32 v235, 0xc2200000, v235
	v_max_f32_e32 v236, 0xc2200000, v236
	v_add_f32_e32 v237, v147, v214
	v_add_f32_e32 v239, v137, v212
	v_mul_f32_e32 v235, 0xbfb8aa3b, v235
	v_mul_f32_e32 v236, 0xbfb8aa3b, v236
	v_max_f32_e32 v237, 0xc2200000, v237
	v_mul_f32_e32 v238, 0xbfb8aa3b, v238
	v_max_f32_e32 v239, 0xc2200000, v239
	v_add_f32_e32 v234, 1.0, v240
	v_exp_f32_e32 v235, v235
	v_exp_f32_e32 v236, v236
	v_mul_f32_e32 v237, 0xbfb8aa3b, v237
	v_exp_f32_e32 v238, v238
	v_mul_f32_e32 v239, 0xbfb8aa3b, v239
	v_add_f32_e32 v240, v138, v197
	v_exp_f32_e32 v237, v237
	v_exp_f32_e32 v239, v239
	v_max_f32_e32 v240, 0xc2200000, v240
	v_mul_f32_e32 v240, 0xbfb8aa3b, v240
	v_max_f32_e32 v241, 0xc2200000, v241
	v_exp_f32_e32 v240, v240
	v_mul_f32_e32 v241, 0xbfb8aa3b, v241
	v_add_f32_e32 v235, 1.0, v235
	v_add_f32_e32 v236, 1.0, v236
	v_add_f32_e32 v238, 1.0, v238
	v_exp_f32_e32 v241, v241
	v_rcp_f32_e32 v234, v234
	v_rcp_f32_e32 v235, v235
	v_rcp_f32_e32 v236, v236
	v_add_f32_e32 v237, 1.0, v237
	v_rcp_f32_e32 v238, v238
	v_add_f32_e32 v239, 1.0, v239
	v_rcp_f32_e32 v237, v237
	v_rcp_f32_e32 v239, v239
	v_add_f32_e32 v240, 1.0, v240
	v_rcp_f32_e32 v240, v240
	v_add_f32_e32 v241, 1.0, v241
	v_mul_f32_e32 v234, v112, v234
	v_mul_f32_e32 v235, v113, v235
	v_mul_f32_e32 v236, v114, v236
	v_rcp_f32_e32 v241, v241
	v_mul_f32_e32 v238, v108, v238
	v_mul_f32_e32 v237, v115, v237
	v_mul_f32_e32 v239, v109, v239
	v_cvt_pk_bf16_f32 v234, v234, v235
	v_cvt_pk_bf16_f32 v235, v236, v237
	v_cvt_pk_bf16_f32 v236, v238, v239
	v_add_f32_e32 v238, v144, v195
	v_max_f32_e32 v238, 0xc2200000, v238
	v_mul_f32_e32 v240, v110, v240
	v_mul_f32_e32 v238, 0xbfb8aa3b, v238
	s_mov_b32 s1, 0x20000
	v_mul_f32_e32 v241, v111, v241
	v_cvt_pk_bf16_f32 v237, v240, v241
	v_exp_f32_e32 v240, v238
	v_add_co_u32_e32 v238, vcc, s1, v0
	v_add_f32_e32 v241, v139, v2
	s_nop 0
	v_addc_co_u32_e32 v239, vcc, 0, v1, vcc
	flat_store_dwordx4 v[238:239], v[234:237]
	v_add_f32_e32 v238, v136, v191
	v_max_f32_e32 v238, 0xc2200000, v238
	v_add_f32_e32 v235, v145, v194
	v_add_f32_e32 v236, v146, v193
	v_max_f32_e32 v235, 0xc2200000, v235
	v_max_f32_e32 v236, 0xc2200000, v236
	v_add_f32_e32 v237, v147, v192
	v_add_f32_e32 v239, v137, v190
	v_mul_f32_e32 v235, 0xbfb8aa3b, v235
	v_mul_f32_e32 v236, 0xbfb8aa3b, v236
	v_max_f32_e32 v237, 0xc2200000, v237
	v_mul_f32_e32 v238, 0xbfb8aa3b, v238
	v_max_f32_e32 v239, 0xc2200000, v239
	v_add_f32_e32 v234, 1.0, v240
	v_exp_f32_e32 v235, v235
	v_exp_f32_e32 v236, v236
	v_mul_f32_e32 v237, 0xbfb8aa3b, v237
	v_exp_f32_e32 v238, v238
	v_mul_f32_e32 v239, 0xbfb8aa3b, v239
	v_add_f32_e32 v240, v138, v189
	v_exp_f32_e32 v237, v237
	v_exp_f32_e32 v239, v239
	v_max_f32_e32 v240, 0xc2200000, v240
	v_max_f32_e32 v241, 0xc2200000, v241
	v_mul_f32_e32 v240, 0xbfb8aa3b, v240
	v_mul_f32_e32 v241, 0xbfb8aa3b, v241
	v_exp_f32_e32 v240, v240
	v_exp_f32_e32 v241, v241
	v_add_f32_e32 v235, 1.0, v235
	v_add_f32_e32 v236, 1.0, v236
	v_add_f32_e32 v238, 1.0, v238
	v_rcp_f32_e32 v234, v234
	v_rcp_f32_e32 v235, v235
	v_rcp_f32_e32 v236, v236
	v_add_f32_e32 v237, 1.0, v237
	v_rcp_f32_e32 v238, v238
	v_add_f32_e32 v239, 1.0, v239
	v_rcp_f32_e32 v237, v237
	v_rcp_f32_e32 v239, v239
	v_add_f32_e32 v240, 1.0, v240
	v_add_f32_e32 v241, 1.0, v241
	v_rcp_f32_e32 v240, v240
	v_rcp_f32_e32 v241, v241
	v_mul_f32_e32 v234, v104, v234
	v_mul_f32_e32 v235, v105, v235
	v_mul_f32_e32 v236, v106, v236
	v_mul_f32_e32 v238, v100, v238
	v_mul_f32_e32 v237, v107, v237
	v_mul_f32_e32 v239, v101, v239
	v_cvt_pk_bf16_f32 v234, v234, v235
	v_cvt_pk_bf16_f32 v235, v236, v237
	v_cvt_pk_bf16_f32 v236, v238, v239
	v_add_co_u32_e32 v238, vcc, 0x30000, v0
	s_mov_b64 s[8:9], 0
	s_nop 0
	v_addc_co_u32_e32 v239, vcc, 0, v1, vcc
	v_mul_f32_e32 v240, v102, v240
	v_mul_f32_e32 v241, v103, v241
	v_cvt_pk_bf16_f32 v237, v240, v241
	flat_store_dwordx4 v[238:239], v[234:237]

; #define PG8_WAIT_L(n) asm volatile("s_waitcnt lgkmcnt(" #n ")" ::: "memory")
; #define PG8_BAR __builtin_amdgcn_s_barrier()
; #define PG8_SCHED __builtin_amdgcn_sched_barrier(0)
; template <class Epi, class AddrA, class AddrB>
; __device__ __forceinline__ void gemm_phase(const Sched S, const int lda, const int ldb, const int K, const AddrA addrA,
;                                            const AddrB addrB, const Epi E) {
;     ...
;       PG8_LDB(B0, 0, 0); PG8_SCHED; PG8_LDA(At, 0, 0); PG8_STAGE(PG8_SA(1, 1), a1 + hstepA, voffA);
;       PG8_WAIT_L(8); PG8_BAR; PG8_WAIT_L(0); PG8_MMA(0, 0, At, B0); PG8_BAR; PG8_SCHED;
;       PG8_LDB(B1, 0, 1); PG8_STAGE(PG8_SB(0, 0), b2, voffB);
;       PG8_BAR; PG8_WAIT_L(0); PG8_MMA(0, 1, At, B1); PG8_BAR;
;       PG8_LDA(At, 0, 1); PG8_STAGE(PG8_SA(0, 0), a2, voffA);
;       PG8_BAR; PG8_WAIT_L(0); PG8_MMA(1, 0, At, B0); PG8_BAR; PG8_SCHED;
.LBB0_618:
	s_ashr_i32 s3, s2, 31
	s_lshl_b64 s[8:9], s[2:3], 20
	s_add_u32 s8, s23, s8
	s_addc_u32 s9, s24, s9
	s_and_b64 s[10:11], s[18:19], exec
	s_cselect_b32 s3, s9, s17
	s_cselect_b32 s13, s8, s16
	s_ashr_i32 s5, s4, 31
	s_lshl_b64 s[10:11], s[4:5], 20
	s_add_u32 s10, s21, s10
	s_addc_u32 s11, s22, s11
	s_and_b64 s[18:19], s[18:19], exec
	s_cselect_b32 s5, s11, s15
	s_cselect_b32 s35, s10, s14
	s_add_u32 s36, s14, 0x100
	s_addc_u32 s37, s15, 0
	s_add_u32 s14, s16, 0x80080
	s_addc_u32 s15, s17, 0
	s_mov_b32 s38, -2
	s_add_i32 s39, 0, 0x10000
	v_add_u32_e32 v142, s39, v144
	ds_read_b128 v[148:151], v142
	ds_read_b128 v[152:155], v142 offset:1024
	ds_read_b128 v[156:159], v142 offset:2048
	ds_read_b128 v[160:163], v142 offset:3072
	v_lshl_add_u64 v[142:143], s[14:15], 0, v[140:141]
	s_add_i32 m0, s26, 0xc000
	ds_read_b128 v[168:171], v146
	ds_read_b128 v[172:175], v146 offset:1024
	ds_read_b128 v[176:179], v146 offset:2048
	ds_read_b128 v[180:183], v146 offset:3072
	ds_read_b128 v[184:187], v146 offset:4096
	ds_read_b128 v[188:191], v146 offset:5120
	ds_read_b128 v[192:195], v146 offset:6144
	ds_read_b128 v[212:215], v146 offset:7168
	global_load_lds_dwordx4 v[142:143], off
	v_lshl_add_u64 v[142:143], s[14:15], 0, v[138:139]
	s_add_i32 m0, s26, 0xe000
	s_nop 0
	global_load_lds_dwordx4 v[142:143], off
	s_waitcnt lgkmcnt(6)
	s_setprio 1
	s_barrier
	v_mfma_f32_16x16x32_bf16 v[128:131], v[148:151], v[168:171], 0
	v_mfma_f32_16x16x32_bf16 v[128:131], v[152:155], v[172:175], v[128:131]
	s_waitcnt lgkmcnt(0)
	v_mfma_f32_16x16x32_bf16 v[120:123], v[148:151], v[176:179], 0
	v_mfma_f32_16x16x32_bf16 v[120:123], v[152:155], v[180:183], v[120:123]
	v_mfma_f32_16x16x32_bf16 v[112:115], v[148:151], v[184:187], 0
	v_mfma_f32_16x16x32_bf16 v[112:115], v[152:155], v[188:191], v[112:115]
	v_mfma_f32_16x16x32_bf16 v[104:107], v[148:151], v[192:195], 0
	v_mfma_f32_16x16x32_bf16 v[104:107], v[152:155], v[212:215], v[104:107]
	v_mfma_f32_16x16x32_bf16 v[124:127], v[156:159], v[168:171], 0
	v_mfma_f32_16x16x32_bf16 v[124:127], v[160:163], v[172:175], v[124:127]
	v_mfma_f32_16x16x32_bf16 v[116:119], v[156:159], v[176:179], 0
	v_mfma_f32_16x16x32_bf16 v[116:119], v[160:163], v[180:183], v[116:119]
	v_mfma_f32_16x16x32_bf16 v[108:111], v[156:159], v[184:187], 0
	v_mfma_f32_16x16x32_bf16 v[108:111], v[160:163], v[188:191], v[108:111]
	v_mfma_f32_16x16x32_bf16 v[100:103], v[156:159], v[192:195], 0
	v_mfma_f32_16x16x32_bf16 v[100:103], v[160:163], v[212:215], v[100:103]
	s_barrier
	s_setprio 0
	s_add_u32 s16, s14, 0xfff80080
	s_addc_u32 s17, s15, -1
	s_cmp_eq_u32 s38, 28
	s_cselect_b32 s19, s3, s17
	s_cselect_b32 s18, s13, s16
	s_cselect_b32 s17, s5, s37
	s_cselect_b32 s16, s35, s36
	s_add_i32 s42, 0, 0x14000
	v_add_u32_e32 v142, s42, v144
	s_add_i32 s39, s39, s25
	ds_read_b128 v[216:219], v142
	ds_read_b128 v[220:223], v142 offset:1024
	ds_read_b128 v[224:227], v142 offset:2048
	ds_read_b128 v[228:231], v142 offset:3072
	v_lshl_add_u64 v[142:143], s[16:17], 0, v[2:3]
	s_mov_b32 m0, s39
	v_lshl_add_u64 v[196:197], s[16:17], 0, v[0:1]
	global_load_lds_dwordx4 v[142:143], off
	s_add_i32 m0, s39, 0x2000
	s_nop 0
	global_load_lds_dwordx4 v[196:197], off
	s_mov_b32 m0, s26
	v_lshl_add_u64 v[232:233], s[18:19], 0, v[134:135]
	s_waitcnt lgkmcnt(2)
	s_setprio 1
	s_barrier
	v_mfma_f32_16x16x32_bf16 v[96:99], v[216:219], v[168:171], 0
	v_mfma_f32_16x16x32_bf16 v[96:99], v[220:223], v[172:175], v[96:99]
	s_waitcnt lgkmcnt(0)
	v_mfma_f32_16x16x32_bf16 v[88:91], v[216:219], v[176:179], 0
	v_mfma_f32_16x16x32_bf16 v[88:91], v[220:223], v[180:183], v[88:91]
	v_mfma_f32_16x16x32_bf16 v[80:83], v[216:219], v[184:187], 0
	v_mfma_f32_16x16x32_bf16 v[80:83], v[220:223], v[188:191], v[80:83]
	v_mfma_f32_16x16x32_bf16 v[72:75], v[216:219], v[192:195], 0
	v_mfma_f32_16x16x32_bf16 v[72:75], v[220:223], v[212:215], v[72:75]
	v_mfma_f32_16x16x32_bf16 v[92:95], v[224:227], v[168:171], 0
	v_mfma_f32_16x16x32_bf16 v[92:95], v[228:231], v[172:175], v[92:95]
	v_mfma_f32_16x16x32_bf16 v[84:87], v[224:227], v[176:179], 0
	v_mfma_f32_16x16x32_bf16 v[84:87], v[228:231], v[180:183], v[84:87]
	v_mfma_f32_16x16x32_bf16 v[76:79], v[224:227], v[184:187], 0
	v_mfma_f32_16x16x32_bf16 v[76:79], v[228:231], v[188:191], v[76:79]
	v_mfma_f32_16x16x32_bf16 v[68:71], v[224:227], v[192:195], 0
	v_mfma_f32_16x16x32_bf16 v[68:71], v[228:231], v[212:215], v[68:71]
	s_barrier
	s_setprio 0
	ds_read_b128 v[168:171], v146 offset:16384
	ds_read_b128 v[172:175], v146 offset:17408
	ds_read_b128 v[176:179], v146 offset:18432
	ds_read_b128 v[180:183], v146 offset:19456
	ds_read_b128 v[184:187], v146 offset:20480
	ds_read_b128 v[188:191], v146 offset:21504
	ds_read_b128 v[192:195], v146 offset:22528
	ds_read_b128 v[212:215], v146 offset:23552
	global_load_lds_dwordx4 v[232:233], off
	v_lshl_add_u64 v[234:235], s[18:19], 0, v[132:133]
	s_mov_b32 m0, s27
	s_nop 0
	global_load_lds_dwordx4 v[234:235], off
	s_waitcnt lgkmcnt(6)
	s_setprio 1
	s_barrier
	v_mfma_f32_16x16x32_bf16 v[64:67], v[148:151], v[168:171], 0
	v_mfma_f32_16x16x32_bf16 v[64:67], v[152:155], v[172:175], v[64:67]
	s_waitcnt lgkmcnt(0)
	v_mfma_f32_16x16x32_bf16 v[56:59], v[148:151], v[176:179], 0
	v_mfma_f32_16x16x32_bf16 v[56:59], v[152:155], v[180:183], v[56:59]
	v_mfma_f32_16x16x32_bf16 v[48:51], v[148:151], v[184:187], 0
	v_mfma_f32_16x16x32_bf16 v[48:51], v[152:155], v[188:191], v[48:51]
	v_mfma_f32_16x16x32_bf16 v[40:43], v[148:151], v[192:195], 0
	v_mfma_f32_16x16x32_bf16 v[40:43], v[152:155], v[212:215], v[40:43]
	v_mfma_f32_16x16x32_bf16 v[60:63], v[156:159], v[168:171], 0
	v_mfma_f32_16x16x32_bf16 v[60:63], v[160:163], v[172:175], v[60:63]
	v_mfma_f32_16x16x32_bf16 v[52:55], v[156:159], v[176:179], 0
	v_mfma_f32_16x16x32_bf16 v[52:55], v[160:163], v[180:183], v[52:55]
	v_mfma_f32_16x16x32_bf16 v[44:47], v[156:159], v[184:187], 0
	v_mfma_f32_16x16x32_bf16 v[44:47], v[160:163], v[188:191], v[44:47]
	v_mfma_f32_16x16x32_bf16 v[36:39], v[156:159], v[192:195], 0
	v_mfma_f32_16x16x32_bf16 v[36:39], v[160:163], v[212:215], v[36:39]
	s_barrier
; #define PG8_WAIT_V(n) asm volatile("s_waitcnt vmcnt(" #n ")" ::: "memory")
; #define PG8_WAIT_L(n) asm volatile("s_waitcnt lgkmcnt(" #n ")" ::: "memory")
; #define PG8_BAR __builtin_amdgcn_s_barrier()
; #define PG8_SCHED __builtin_amdgcn_sched_barrier(0)
; template <class Epi, class AddrA, class AddrB>
; __device__ __forceinline__ void gemm_phase(const Sched S, const int lda, const int ldb, const int K, const AddrA addrA,
;                                            const AddrB addrB, const Epi E) {
;     ...
;       PG8_BAR; PG8_WAIT_L(0); PG8_MMA(1, 0, At, B0); PG8_BAR; PG8_SCHED;
;       PG8_STAGE(PG8_SB(0, 1), b2 + hstepB, voffB);
;       PG8_WAIT_V(6); PG8_BAR; PG8_MMA(1, 1, At, B1); PG8_BAR;
;       PG8_LDB(B0, 1, 0); PG8_SCHED; PG8_LDA(At, 1, 0); PG8_STAGE(PG8_SA(0, 1), a2 + hstepA, voffA);
;       PG8_WAIT_L(8); PG8_BAR; PG8_WAIT_L(0); PG8_MMA(0, 0, At, B0); PG8_BAR; PG8_SCHED;
;       PG8_LDB(B1, 1, 1); PG8_STAGE(PG8_SB(1, 0), b3, voffB);
;       PG8_BAR; PG8_WAIT_L(0); PG8_MMA(0, 1, At, B1); PG8_BAR;
	s_setprio 0
	s_add_u32 s40, s16, 0x80000
	s_addc_u32 s41, s17, 0
	s_add_i32 s39, s42, s25
	v_lshl_add_u64 v[148:149], s[40:41], 0, v[2:3]
	s_mov_b32 m0, s39
	s_nop 0
	global_load_lds_dwordx4 v[148:149], off
	v_lshl_add_u64 v[148:149], s[40:41], 0, v[0:1]
	s_add_i32 m0, s39, 0x2000
	s_nop 0
	global_load_lds_dwordx4 v[148:149], off
	s_add_i32 s39, 0, 0x18000
	v_add_u32_e32 v147, s39, v144
	s_waitcnt vmcnt(6)
	s_setprio 1
	s_barrier
	v_mfma_f32_16x16x32_bf16 v[32:35], v[216:219], v[168:171], 0
	v_mfma_f32_16x16x32_bf16 v[32:35], v[220:223], v[172:175], v[32:35]
	v_mfma_f32_16x16x32_bf16 v[24:27], v[216:219], v[176:179], 0
	v_mfma_f32_16x16x32_bf16 v[24:27], v[220:223], v[180:183], v[24:27]
	v_mfma_f32_16x16x32_bf16 v[16:19], v[216:219], v[184:187], 0
	v_mfma_f32_16x16x32_bf16 v[16:19], v[220:223], v[188:191], v[16:19]
	v_mfma_f32_16x16x32_bf16 v[8:11], v[216:219], v[192:195], 0
	v_mfma_f32_16x16x32_bf16 v[8:11], v[220:223], v[212:215], v[8:11]
	v_mfma_f32_16x16x32_bf16 v[28:31], v[224:227], v[168:171], 0
	v_mfma_f32_16x16x32_bf16 v[28:31], v[228:231], v[172:175], v[28:31]
	v_mfma_f32_16x16x32_bf16 v[20:23], v[224:227], v[176:179], 0
	v_mfma_f32_16x16x32_bf16 v[20:23], v[228:231], v[180:183], v[20:23]
	v_mfma_f32_16x16x32_bf16 v[12:15], v[224:227], v[184:187], 0
	v_mfma_f32_16x16x32_bf16 v[12:15], v[228:231], v[188:191], v[12:15]
	v_mfma_f32_16x16x32_bf16 v[4:7], v[224:227], v[192:195], 0
	v_mfma_f32_16x16x32_bf16 v[4:7], v[228:231], v[212:215], v[4:7]
	s_barrier
	s_setprio 0
	ds_read_b128 v[148:151], v147
	ds_read_b128 v[152:155], v147 offset:1024
	ds_read_b128 v[156:159], v147 offset:2048
	ds_read_b128 v[160:163], v147 offset:3072
	s_add_u32 s18, s18, 0x80000
	s_addc_u32 s19, s19, 0
	s_mov_b32 m0, s28
	v_lshl_add_u64 v[216:217], s[18:19], 0, v[134:135]
	ds_read_b128 v[168:171], v146 offset:32768
	ds_read_b128 v[172:175], v146 offset:33792
	ds_read_b128 v[176:179], v146 offset:34816
	ds_read_b128 v[180:183], v146 offset:35840
	ds_read_b128 v[184:187], v146 offset:36864
	ds_read_b128 v[188:191], v146 offset:37888
	ds_read_b128 v[192:195], v146 offset:38912
	ds_read_b128 v[212:215], v146 offset:39936
	global_load_lds_dwordx4 v[216:217], off
	v_lshl_add_u64 v[216:217], s[18:19], 0, v[132:133]
	s_mov_b32 m0, s29
	s_nop 0
	global_load_lds_dwordx4 v[216:217], off
	s_waitcnt lgkmcnt(6)
	s_setprio 1
	s_barrier
	v_mfma_f32_16x16x32_bf16 v[128:131], v[148:151], v[168:171], v[128:131]
	v_mfma_f32_16x16x32_bf16 v[128:131], v[152:155], v[172:175], v[128:131]
	s_waitcnt lgkmcnt(0)
	v_mfma_f32_16x16x32_bf16 v[120:123], v[148:151], v[176:179], v[120:123]
	v_mfma_f32_16x16x32_bf16 v[120:123], v[152:155], v[180:183], v[120:123]
	v_mfma_f32_16x16x32_bf16 v[112:115], v[148:151], v[184:187], v[112:115]
	v_mfma_f32_16x16x32_bf16 v[112:115], v[152:155], v[188:191], v[112:115]
	v_mfma_f32_16x16x32_bf16 v[104:107], v[148:151], v[192:195], v[104:107]
	v_mfma_f32_16x16x32_bf16 v[104:107], v[152:155], v[212:215], v[104:107]
	v_mfma_f32_16x16x32_bf16 v[124:127], v[156:159], v[168:171], v[124:127]
	v_mfma_f32_16x16x32_bf16 v[124:127], v[160:163], v[172:175], v[124:127]
	v_mfma_f32_16x16x32_bf16 v[116:119], v[156:159], v[176:179], v[116:119]
	v_mfma_f32_16x16x32_bf16 v[116:119], v[160:163], v[180:183], v[116:119]
	v_mfma_f32_16x16x32_bf16 v[108:111], v[156:159], v[184:187], v[108:111]
	v_mfma_f32_16x16x32_bf16 v[108:111], v[160:163], v[188:191], v[108:111]
	v_mfma_f32_16x16x32_bf16 v[100:103], v[156:159], v[192:195], v[100:103]
	v_mfma_f32_16x16x32_bf16 v[100:103], v[160:163], v[212:215], v[100:103]
	s_barrier
	s_setprio 0
	s_add_i32 s18, 0, 0x1c000
	s_add_i32 s19, s39, s25
	v_add_u32_e32 v147, s18, v144
	v_lshl_add_u64 v[142:143], v[142:143], 0, s[52:53]
	s_mov_b32 m0, s19
	ds_read_b128 v[216:219], v147
	ds_read_b128 v[220:223], v147 offset:1024
	ds_read_b128 v[224:227], v147 offset:2048
	ds_read_b128 v[228:231], v147 offset:3072
	global_load_lds_dwordx4 v[142:143], off
	v_lshl_add_u64 v[142:143], v[196:197], 0, s[52:53]
	s_add_i32 m0, s19, 0x2000
	s_nop 0
	global_load_lds_dwordx4 v[142:143], off
	s_mov_b32 m0, s30
	v_lshl_add_u64 v[142:143], v[232:233], 0, s[52:53]
	s_waitcnt lgkmcnt(2)
	s_setprio 1
	s_barrier
	v_mfma_f32_16x16x32_bf16 v[96:99], v[216:219], v[168:171], v[96:99]
	v_mfma_f32_16x16x32_bf16 v[96:99], v[220:223], v[172:175], v[96:99]
	s_waitcnt lgkmcnt(0)
	v_mfma_f32_16x16x32_bf16 v[88:91], v[216:219], v[176:179], v[88:91]
	v_mfma_f32_16x16x32_bf16 v[88:91], v[220:223], v[180:183], v[88:91]
	v_mfma_f32_16x16x32_bf16 v[80:83], v[216:219], v[184:187], v[80:83]
	v_mfma_f32_16x16x32_bf16 v[80:83], v[220:223], v[188:191], v[80:83]
	v_mfma_f32_16x16x32_bf16 v[72:75], v[216:219], v[192:195], v[72:75]
	v_mfma_f32_16x16x32_bf16 v[72:75], v[220:223], v[212:215], v[72:75]
	v_mfma_f32_16x16x32_bf16 v[92:95], v[224:227], v[168:171], v[92:95]
	v_mfma_f32_16x16x32_bf16 v[92:95], v[228:231], v[172:175], v[92:95]
	v_mfma_f32_16x16x32_bf16 v[84:87], v[224:227], v[176:179], v[84:87]
	v_mfma_f32_16x16x32_bf16 v[84:87], v[228:231], v[180:183], v[84:87]
	v_mfma_f32_16x16x32_bf16 v[76:79], v[224:227], v[184:187], v[76:79]
	v_mfma_f32_16x16x32_bf16 v[76:79], v[228:231], v[188:191], v[76:79]
	v_mfma_f32_16x16x32_bf16 v[68:71], v[224:227], v[192:195], v[68:71]
	v_mfma_f32_16x16x32_bf16 v[68:71], v[228:231], v[212:215], v[68:71]
	s_barrier
	s_setprio 0
	ds_read_b128 v[168:171], v146 offset:49152
	ds_read_b128 v[172:175], v146 offset:50176
	ds_read_b128 v[176:179], v146 offset:51200
	ds_read_b128 v[180:183], v146 offset:52224
	ds_read_b128 v[184:187], v146 offset:53248
	ds_read_b128 v[188:191], v146 offset:54272
	ds_read_b128 v[192:195], v146 offset:55296
	ds_read_b128 v[212:215], v146 offset:56320
	global_load_lds_dwordx4 v[142:143], off
	v_lshl_add_u64 v[142:143], v[234:235], 0, s[52:53]
	s_mov_b32 m0, s31
	s_nop 0
	global_load_lds_dwordx4 v[142:143], off
	s_waitcnt lgkmcnt(6)
	s_setprio 1
	s_barrier
; #define PG8_WAIT_V(n) asm volatile("s_waitcnt vmcnt(" #n ")" ::: "memory")
; #define PG8_WAIT_L(n) asm volatile("s_waitcnt lgkmcnt(" #n ")" ::: "memory")
; #define PG8_BAR __builtin_amdgcn_s_barrier()
; #define PG8_SCHED __builtin_amdgcn_sched_barrier(0)
; template <class Epi, class AddrA, class AddrB>
; __device__ __forceinline__ void gemm_phase(const Sched S, const int lda, const int ldb, const int K, const AddrA addrA,
;                                            const AddrB addrB, const Epi E) {
;     ...
;       PG8_LDB(B0, 0, 0); PG8_SCHED; PG8_LDA(At, 0, 0); PG8_STAGE(PG8_SA(1, 1), a1 + hstepA, voffA);
;       PG8_WAIT_L(8); PG8_BAR; PG8_WAIT_L(0); PG8_MMA(0, 0, At, B0); PG8_BAR; PG8_SCHED;
;       PG8_LDB(B1, 0, 1); PG8_STAGE(PG8_SB(0, 0), b2, voffB);
;       PG8_BAR; PG8_WAIT_L(0); PG8_MMA(0, 1, At, B1); PG8_BAR;
;       PG8_LDA(At, 0, 1); PG8_STAGE(PG8_SA(0, 0), a2, voffA);
;       PG8_BAR; PG8_WAIT_L(0); PG8_MMA(1, 0, At, B0); PG8_BAR; PG8_SCHED;
;       PG8_STAGE(PG8_SB(0, 1), b2 + hstepB, voffB);
;       PG8_WAIT_V(6); PG8_BAR; PG8_MMA(1, 1, At, B1); PG8_BAR;
;       PG8_LDB(B0, 1, 0); PG8_SCHED; PG8_LDA(At, 1, 0); PG8_STAGE(PG8_SA(0, 1), a2 + hstepA, voffA);
;       PG8_WAIT_L(8); PG8_BAR; PG8_WAIT_L(0); PG8_MMA(0, 0, At, B0); PG8_BAR; PG8_SCHED;
;       PG8_LDB(B1, 1, 1); PG8_STAGE(PG8_SB(1, 0), b3, voffB);
;       PG8_BAR; PG8_WAIT_L(0); PG8_MMA(0, 1, At, B1); PG8_BAR;
;       PG8_LDA(At, 1, 1); PG8_STAGE(PG8_SA(1, 0), a3, voffA);
;       PG8_BAR; PG8_WAIT_L(0); PG8_MMA(1, 0, At, B0); PG8_BAR; PG8_SCHED;
;       PG8_STAGE(PG8_SB(1, 1), b3 + hstepB, voffB);
;       PG8_WAIT_V(6); PG8_BAR; PG8_MMA(1, 1, At, B1); PG8_BAR;
	v_mfma_f32_16x16x32_bf16 v[64:67], v[148:151], v[168:171], v[64:67]
	v_mfma_f32_16x16x32_bf16 v[64:67], v[152:155], v[172:175], v[64:67]
	s_waitcnt lgkmcnt(0)
	v_mfma_f32_16x16x32_bf16 v[56:59], v[148:151], v[176:179], v[56:59]
	v_mfma_f32_16x16x32_bf16 v[56:59], v[152:155], v[180:183], v[56:59]
	v_mfma_f32_16x16x32_bf16 v[48:51], v[148:151], v[184:187], v[48:51]
	v_mfma_f32_16x16x32_bf16 v[48:51], v[152:155], v[188:191], v[48:51]
	v_mfma_f32_16x16x32_bf16 v[40:43], v[148:151], v[192:195], v[40:43]
	v_mfma_f32_16x16x32_bf16 v[40:43], v[152:155], v[212:215], v[40:43]
	v_mfma_f32_16x16x32_bf16 v[60:63], v[156:159], v[168:171], v[60:63]
	v_mfma_f32_16x16x32_bf16 v[60:63], v[160:163], v[172:175], v[60:63]
	v_mfma_f32_16x16x32_bf16 v[52:55], v[156:159], v[176:179], v[52:55]
	v_mfma_f32_16x16x32_bf16 v[52:55], v[160:163], v[180:183], v[52:55]
	v_mfma_f32_16x16x32_bf16 v[44:47], v[156:159], v[184:187], v[44:47]
	v_mfma_f32_16x16x32_bf16 v[44:47], v[160:163], v[188:191], v[44:47]
	v_mfma_f32_16x16x32_bf16 v[36:39], v[156:159], v[192:195], v[36:39]
	v_mfma_f32_16x16x32_bf16 v[36:39], v[160:163], v[212:215], v[36:39]
	s_barrier
	s_setprio 0
	s_add_u32 s16, s16, 0x80080
	s_addc_u32 s17, s17, 0
	s_add_i32 s18, s18, s25
	v_lshl_add_u64 v[142:143], s[16:17], 0, v[2:3]
	s_mov_b32 m0, s18
	s_nop 0
	global_load_lds_dwordx4 v[142:143], off
	v_lshl_add_u64 v[142:143], s[16:17], 0, v[0:1]
	s_add_i32 m0, s18, 0x2000
	s_nop 0
	global_load_lds_dwordx4 v[142:143], off
	s_add_i32 s38, s38, 2
	s_add_u32 s36, s36, 0x100
	s_addc_u32 s37, s37, 0
	s_add_u32 s14, s14, 0x100
	s_addc_u32 s15, s15, 0
	s_waitcnt vmcnt(6)
	s_setprio 1
	s_barrier
	v_mfma_f32_16x16x32_bf16 v[32:35], v[216:219], v[168:171], v[32:35]
	v_mfma_f32_16x16x32_bf16 v[32:35], v[220:223], v[172:175], v[32:35]
	v_mfma_f32_16x16x32_bf16 v[24:27], v[216:219], v[176:179], v[24:27]
	v_mfma_f32_16x16x32_bf16 v[24:27], v[220:223], v[180:183], v[24:27]
	v_mfma_f32_16x16x32_bf16 v[16:19], v[216:219], v[184:187], v[16:19]
	v_mfma_f32_16x16x32_bf16 v[16:19], v[220:223], v[188:191], v[16:19]
	v_mfma_f32_16x16x32_bf16 v[8:11], v[216:219], v[192:195], v[8:11]
	v_mfma_f32_16x16x32_bf16 v[8:11], v[220:223], v[212:215], v[8:11]
	v_mfma_f32_16x16x32_bf16 v[28:31], v[224:227], v[168:171], v[28:31]
	v_mfma_f32_16x16x32_bf16 v[28:31], v[228:231], v[172:175], v[28:31]
	v_mfma_f32_16x16x32_bf16 v[20:23], v[224:227], v[176:179], v[20:23]
	v_mfma_f32_16x16x32_bf16 v[20:23], v[228:231], v[180:183], v[20:23]
	v_mfma_f32_16x16x32_bf16 v[12:15], v[224:227], v[184:187], v[12:15]
	v_mfma_f32_16x16x32_bf16 v[12:15], v[228:231], v[188:191], v[12:15]
	v_mfma_f32_16x16x32_bf16 v[4:7], v[224:227], v[192:195], v[4:7]
	v_mfma_f32_16x16x32_bf16 v[4:7], v[228:231], v[212:215], v[4:7]
	s_barrier
	s_setprio 0
	s_cmp_gt_u32 s38, 29
.LBB0_619:
	s_add_i32 s39, 0, 0x10000
	v_add_u32_e32 v142, s39, v144
	ds_read_b128 v[148:151], v142
	ds_read_b128 v[152:155], v142 offset:1024
	ds_read_b128 v[156:159], v142 offset:2048
	ds_read_b128 v[160:163], v142 offset:3072
	v_lshl_add_u64 v[142:143], s[14:15], 0, v[140:141]
	s_add_i32 m0, s26, 0xc000
	ds_read_b128 v[168:171], v146
	ds_read_b128 v[172:175], v146 offset:1024
	ds_read_b128 v[176:179], v146 offset:2048
	ds_read_b128 v[180:183], v146 offset:3072
	ds_read_b128 v[184:187], v146 offset:4096
	ds_read_b128 v[188:191], v146 offset:5120
	ds_read_b128 v[192:195], v146 offset:6144
	ds_read_b128 v[212:215], v146 offset:7168
	global_load_lds_dwordx4 v[142:143], off
	v_lshl_add_u64 v[142:143], s[14:15], 0, v[138:139]
	s_add_i32 m0, s26, 0xe000
	s_nop 0
	global_load_lds_dwordx4 v[142:143], off
	s_waitcnt lgkmcnt(6)
	s_setprio 1
	s_barrier
	v_mfma_f32_16x16x32_bf16 v[128:131], v[148:151], v[168:171], v[128:131]
	v_mfma_f32_16x16x32_bf16 v[128:131], v[152:155], v[172:175], v[128:131]
	s_waitcnt lgkmcnt(0)
	v_mfma_f32_16x16x32_bf16 v[120:123], v[148:151], v[176:179], v[120:123]
	v_mfma_f32_16x16x32_bf16 v[120:123], v[152:155], v[180:183], v[120:123]
	v_mfma_f32_16x16x32_bf16 v[112:115], v[148:151], v[184:187], v[112:115]
	v_mfma_f32_16x16x32_bf16 v[112:115], v[152:155], v[188:191], v[112:115]
	v_mfma_f32_16x16x32_bf16 v[104:107], v[148:151], v[192:195], v[104:107]
	v_mfma_f32_16x16x32_bf16 v[104:107], v[152:155], v[212:215], v[104:107]
	v_mfma_f32_16x16x32_bf16 v[124:127], v[156:159], v[168:171], v[124:127]
	v_mfma_f32_16x16x32_bf16 v[124:127], v[160:163], v[172:175], v[124:127]
	v_mfma_f32_16x16x32_bf16 v[116:119], v[156:159], v[176:179], v[116:119]
	v_mfma_f32_16x16x32_bf16 v[116:119], v[160:163], v[180:183], v[116:119]
	v_mfma_f32_16x16x32_bf16 v[108:111], v[156:159], v[184:187], v[108:111]
	v_mfma_f32_16x16x32_bf16 v[108:111], v[160:163], v[188:191], v[108:111]
	v_mfma_f32_16x16x32_bf16 v[100:103], v[156:159], v[192:195], v[100:103]
	v_mfma_f32_16x16x32_bf16 v[100:103], v[160:163], v[212:215], v[100:103]
	s_barrier
	s_setprio 0
	s_add_u32 s16, s14, 0xfff80080
	s_addc_u32 s17, s15, -1
	s_cmp_eq_u32 s38, 28
	s_cselect_b32 s19, s3, s17
	s_cselect_b32 s18, s13, s16
	s_cselect_b32 s17, s5, s37
	s_cselect_b32 s16, s35, s36
	s_add_i32 s42, 0, 0x14000
	v_add_u32_e32 v142, s42, v144
	s_add_i32 s39, s39, s25
	ds_read_b128 v[216:219], v142
	ds_read_b128 v[220:223], v142 offset:1024
	ds_read_b128 v[224:227], v142 offset:2048
	ds_read_b128 v[228:231], v142 offset:3072
	v_lshl_add_u64 v[142:143], s[16:17], 0, v[2:3]
	s_mov_b32 m0, s39
	v_lshl_add_u64 v[196:197], s[16:17], 0, v[0:1]
	global_load_lds_dwordx4 v[142:143], off
	s_add_i32 m0, s39, 0x2000
	s_nop 0
	global_load_lds_dwordx4 v[196:197], off
	s_mov_b32 m0, s26
	v_lshl_add_u64 v[232:233], s[18:19], 0, v[134:135]
	s_waitcnt lgkmcnt(2)
	s_setprio 1
	s_barrier
; #define PG8_WAIT_V(n) asm volatile("s_waitcnt vmcnt(" #n ")" ::: "memory")
; #define PG8_WAIT_L(n) asm volatile("s_waitcnt lgkmcnt(" #n ")" ::: "memory")
; #define PG8_BAR __builtin_amdgcn_s_barrier()
; #define PG8_SCHED __builtin_amdgcn_sched_barrier(0)
; template <class Epi, class AddrA, class AddrB>
; __device__ __forceinline__ void gemm_phase(const Sched S, const int lda, const int ldb, const int K, const AddrA addrA,
;                                            const AddrB addrB, const Epi E) {
;     ...
;       PG8_WAIT_L(8); PG8_BAR; PG8_WAIT_L(0); PG8_MMA(0, 0, At, B0); PG8_BAR; PG8_SCHED;
;       PG8_LDB(B1, 0, 1); PG8_STAGE(PG8_SB(0, 0), b2, voffB);
;       PG8_BAR; PG8_WAIT_L(0); PG8_MMA(0, 1, At, B1); PG8_BAR;
;       PG8_LDA(At, 0, 1); PG8_STAGE(PG8_SA(0, 0), a2, voffA);
;       PG8_BAR; PG8_WAIT_L(0); PG8_MMA(1, 0, At, B0); PG8_BAR; PG8_SCHED;
;       PG8_STAGE(PG8_SB(0, 1), b2 + hstepB, voffB);
;       PG8_WAIT_V(6); PG8_BAR; PG8_MMA(1, 1, At, B1); PG8_BAR;
;       PG8_LDB(B0, 1, 0); PG8_SCHED; PG8_LDA(At, 1, 0); PG8_STAGE(PG8_SA(0, 1), a2 + hstepA, voffA);
;       PG8_WAIT_L(8); PG8_BAR; PG8_WAIT_L(0); PG8_MMA(0, 0, At, B0); PG8_BAR; PG8_SCHED;
	v_mfma_f32_16x16x32_bf16 v[96:99], v[216:219], v[168:171], v[96:99]
	v_mfma_f32_16x16x32_bf16 v[96:99], v[220:223], v[172:175], v[96:99]
	s_waitcnt lgkmcnt(0)
	v_mfma_f32_16x16x32_bf16 v[88:91], v[216:219], v[176:179], v[88:91]
	v_mfma_f32_16x16x32_bf16 v[88:91], v[220:223], v[180:183], v[88:91]
	v_mfma_f32_16x16x32_bf16 v[80:83], v[216:219], v[184:187], v[80:83]
	v_mfma_f32_16x16x32_bf16 v[80:83], v[220:223], v[188:191], v[80:83]
	v_mfma_f32_16x16x32_bf16 v[72:75], v[216:219], v[192:195], v[72:75]
	v_mfma_f32_16x16x32_bf16 v[72:75], v[220:223], v[212:215], v[72:75]
	v_mfma_f32_16x16x32_bf16 v[92:95], v[224:227], v[168:171], v[92:95]
	v_mfma_f32_16x16x32_bf16 v[92:95], v[228:231], v[172:175], v[92:95]
	v_mfma_f32_16x16x32_bf16 v[84:87], v[224:227], v[176:179], v[84:87]
	v_mfma_f32_16x16x32_bf16 v[84:87], v[228:231], v[180:183], v[84:87]
	v_mfma_f32_16x16x32_bf16 v[76:79], v[224:227], v[184:187], v[76:79]
	v_mfma_f32_16x16x32_bf16 v[76:79], v[228:231], v[188:191], v[76:79]
	v_mfma_f32_16x16x32_bf16 v[68:71], v[224:227], v[192:195], v[68:71]
	v_mfma_f32_16x16x32_bf16 v[68:71], v[228:231], v[212:215], v[68:71]
	s_barrier
	s_setprio 0
	ds_read_b128 v[168:171], v146 offset:16384
	ds_read_b128 v[172:175], v146 offset:17408
	ds_read_b128 v[176:179], v146 offset:18432
	ds_read_b128 v[180:183], v146 offset:19456
	ds_read_b128 v[184:187], v146 offset:20480
	ds_read_b128 v[188:191], v146 offset:21504
	ds_read_b128 v[192:195], v146 offset:22528
	ds_read_b128 v[212:215], v146 offset:23552
	global_load_lds_dwordx4 v[232:233], off
	v_lshl_add_u64 v[234:235], s[18:19], 0, v[132:133]
	s_mov_b32 m0, s27
	s_nop 0
	global_load_lds_dwordx4 v[234:235], off
	s_waitcnt lgkmcnt(6)
	s_setprio 1
	s_barrier
	v_mfma_f32_16x16x32_bf16 v[64:67], v[148:151], v[168:171], v[64:67]
	v_mfma_f32_16x16x32_bf16 v[64:67], v[152:155], v[172:175], v[64:67]
	s_waitcnt lgkmcnt(0)
	v_mfma_f32_16x16x32_bf16 v[56:59], v[148:151], v[176:179], v[56:59]
	v_mfma_f32_16x16x32_bf16 v[56:59], v[152:155], v[180:183], v[56:59]
	v_mfma_f32_16x16x32_bf16 v[48:51], v[148:151], v[184:187], v[48:51]
	v_mfma_f32_16x16x32_bf16 v[48:51], v[152:155], v[188:191], v[48:51]
	v_mfma_f32_16x16x32_bf16 v[40:43], v[148:151], v[192:195], v[40:43]
	v_mfma_f32_16x16x32_bf16 v[40:43], v[152:155], v[212:215], v[40:43]
	v_mfma_f32_16x16x32_bf16 v[60:63], v[156:159], v[168:171], v[60:63]
	v_mfma_f32_16x16x32_bf16 v[60:63], v[160:163], v[172:175], v[60:63]
	v_mfma_f32_16x16x32_bf16 v[52:55], v[156:159], v[176:179], v[52:55]
	v_mfma_f32_16x16x32_bf16 v[52:55], v[160:163], v[180:183], v[52:55]
	v_mfma_f32_16x16x32_bf16 v[44:47], v[156:159], v[184:187], v[44:47]
	v_mfma_f32_16x16x32_bf16 v[44:47], v[160:163], v[188:191], v[44:47]
	v_mfma_f32_16x16x32_bf16 v[36:39], v[156:159], v[192:195], v[36:39]
	v_mfma_f32_16x16x32_bf16 v[36:39], v[160:163], v[212:215], v[36:39]
	s_barrier
	s_setprio 0
	s_add_u32 s40, s16, 0x80000
	s_addc_u32 s41, s17, 0
	s_add_i32 s39, s42, s25
	v_lshl_add_u64 v[148:149], s[40:41], 0, v[2:3]
	s_mov_b32 m0, s39
	s_nop 0
	global_load_lds_dwordx4 v[148:149], off
	v_lshl_add_u64 v[148:149], s[40:41], 0, v[0:1]
	s_add_i32 m0, s39, 0x2000
	s_nop 0
	global_load_lds_dwordx4 v[148:149], off
	s_add_i32 s39, 0, 0x18000
	v_add_u32_e32 v147, s39, v144
	s_waitcnt vmcnt(6)
	s_setprio 1
	s_barrier
	v_mfma_f32_16x16x32_bf16 v[32:35], v[216:219], v[168:171], v[32:35]
	v_mfma_f32_16x16x32_bf16 v[32:35], v[220:223], v[172:175], v[32:35]
	v_mfma_f32_16x16x32_bf16 v[24:27], v[216:219], v[176:179], v[24:27]
	v_mfma_f32_16x16x32_bf16 v[24:27], v[220:223], v[180:183], v[24:27]
	v_mfma_f32_16x16x32_bf16 v[16:19], v[216:219], v[184:187], v[16:19]
	v_mfma_f32_16x16x32_bf16 v[16:19], v[220:223], v[188:191], v[16:19]
	v_mfma_f32_16x16x32_bf16 v[8:11], v[216:219], v[192:195], v[8:11]
	v_mfma_f32_16x16x32_bf16 v[8:11], v[220:223], v[212:215], v[8:11]
	v_mfma_f32_16x16x32_bf16 v[28:31], v[224:227], v[168:171], v[28:31]
	v_mfma_f32_16x16x32_bf16 v[28:31], v[228:231], v[172:175], v[28:31]
	v_mfma_f32_16x16x32_bf16 v[20:23], v[224:227], v[176:179], v[20:23]
	v_mfma_f32_16x16x32_bf16 v[20:23], v[228:231], v[180:183], v[20:23]
	v_mfma_f32_16x16x32_bf16 v[12:15], v[224:227], v[184:187], v[12:15]
	v_mfma_f32_16x16x32_bf16 v[12:15], v[228:231], v[188:191], v[12:15]
	v_mfma_f32_16x16x32_bf16 v[4:7], v[224:227], v[192:195], v[4:7]
	v_mfma_f32_16x16x32_bf16 v[4:7], v[228:231], v[212:215], v[4:7]
	s_barrier
	s_setprio 0
	ds_read_b128 v[148:151], v147
	ds_read_b128 v[152:155], v147 offset:1024
	ds_read_b128 v[156:159], v147 offset:2048
	ds_read_b128 v[160:163], v147 offset:3072
	s_add_u32 s18, s18, 0x80000
	s_addc_u32 s19, s19, 0
	s_mov_b32 m0, s28
	v_lshl_add_u64 v[216:217], s[18:19], 0, v[134:135]
	ds_read_b128 v[168:171], v146 offset:32768
	ds_read_b128 v[172:175], v146 offset:33792
	ds_read_b128 v[176:179], v146 offset:34816
	ds_read_b128 v[180:183], v146 offset:35840
	ds_read_b128 v[184:187], v146 offset:36864
	ds_read_b128 v[188:191], v146 offset:37888
	ds_read_b128 v[192:195], v146 offset:38912
	ds_read_b128 v[212:215], v146 offset:39936
	global_load_lds_dwordx4 v[216:217], off
	v_lshl_add_u64 v[216:217], s[18:19], 0, v[132:133]
	s_mov_b32 m0, s29
	s_nop 0
	global_load_lds_dwordx4 v[216:217], off
	s_waitcnt lgkmcnt(6)
	s_setprio 1
	s_barrier
; #define PG8_WAIT_V(n) asm volatile("s_waitcnt vmcnt(" #n ")" ::: "memory")
; #define PG8_WAIT_L(n) asm volatile("s_waitcnt lgkmcnt(" #n ")" ::: "memory")
; #define PG8_BAR __builtin_amdgcn_s_barrier()
; #define PG8_SCHED __builtin_amdgcn_sched_barrier(0)
; template <class Epi, class AddrA, class AddrB>
; __device__ __forceinline__ void gemm_phase(const Sched S, const int lda, const int ldb, const int K, const AddrA addrA,
;                                            const AddrB addrB, const Epi E) {
;     ...
;       PG8_WAIT_L(8); PG8_BAR; PG8_WAIT_L(0); PG8_MMA(0, 0, At, B0); PG8_BAR; PG8_SCHED;
;       PG8_LDB(B1, 1, 1); PG8_STAGE(PG8_SB(1, 0), b3, voffB);
;       PG8_BAR; PG8_WAIT_L(0); PG8_MMA(0, 1, At, B1); PG8_BAR;
;       PG8_LDA(At, 1, 1); PG8_STAGE(PG8_SA(1, 0), a3, voffA);
;       PG8_BAR; PG8_WAIT_L(0); PG8_MMA(1, 0, At, B0); PG8_BAR; PG8_SCHED;
;       PG8_STAGE(PG8_SB(1, 1), b3 + hstepB, voffB);
;       PG8_WAIT_V(6); PG8_BAR; PG8_MMA(1, 1, At, B1); PG8_BAR;
	v_mfma_f32_16x16x32_bf16 v[128:131], v[148:151], v[168:171], v[128:131]
	v_mfma_f32_16x16x32_bf16 v[128:131], v[152:155], v[172:175], v[128:131]
	s_waitcnt lgkmcnt(0)
	v_mfma_f32_16x16x32_bf16 v[120:123], v[148:151], v[176:179], v[120:123]
	v_mfma_f32_16x16x32_bf16 v[120:123], v[152:155], v[180:183], v[120:123]
	v_mfma_f32_16x16x32_bf16 v[112:115], v[148:151], v[184:187], v[112:115]
	v_mfma_f32_16x16x32_bf16 v[112:115], v[152:155], v[188:191], v[112:115]
	v_mfma_f32_16x16x32_bf16 v[104:107], v[148:151], v[192:195], v[104:107]
	v_mfma_f32_16x16x32_bf16 v[104:107], v[152:155], v[212:215], v[104:107]
	v_mfma_f32_16x16x32_bf16 v[124:127], v[156:159], v[168:171], v[124:127]
	v_mfma_f32_16x16x32_bf16 v[124:127], v[160:163], v[172:175], v[124:127]
	v_mfma_f32_16x16x32_bf16 v[116:119], v[156:159], v[176:179], v[116:119]
	v_mfma_f32_16x16x32_bf16 v[116:119], v[160:163], v[180:183], v[116:119]
	v_mfma_f32_16x16x32_bf16 v[108:111], v[156:159], v[184:187], v[108:111]
	v_mfma_f32_16x16x32_bf16 v[108:111], v[160:163], v[188:191], v[108:111]
	v_mfma_f32_16x16x32_bf16 v[100:103], v[156:159], v[192:195], v[100:103]
	v_mfma_f32_16x16x32_bf16 v[100:103], v[160:163], v[212:215], v[100:103]
	s_barrier
	s_setprio 0
	s_add_i32 s18, 0, 0x1c000
	s_add_i32 s19, s39, s25
	v_add_u32_e32 v147, s18, v144
	v_lshl_add_u64 v[142:143], v[142:143], 0, s[52:53]
	s_mov_b32 m0, s19
	ds_read_b128 v[216:219], v147
	ds_read_b128 v[220:223], v147 offset:1024
	ds_read_b128 v[224:227], v147 offset:2048
	ds_read_b128 v[228:231], v147 offset:3072
	global_load_lds_dwordx4 v[142:143], off
	v_lshl_add_u64 v[142:143], v[196:197], 0, s[52:53]
	s_add_i32 m0, s19, 0x2000
	s_nop 0
	global_load_lds_dwordx4 v[142:143], off
	s_mov_b32 m0, s30
	v_lshl_add_u64 v[142:143], v[232:233], 0, s[52:53]
	s_waitcnt lgkmcnt(2)
	s_setprio 1
	s_barrier
	v_mfma_f32_16x16x32_bf16 v[96:99], v[216:219], v[168:171], v[96:99]
	v_mfma_f32_16x16x32_bf16 v[96:99], v[220:223], v[172:175], v[96:99]
	s_waitcnt lgkmcnt(0)
	v_mfma_f32_16x16x32_bf16 v[88:91], v[216:219], v[176:179], v[88:91]
	v_mfma_f32_16x16x32_bf16 v[88:91], v[220:223], v[180:183], v[88:91]
	v_mfma_f32_16x16x32_bf16 v[80:83], v[216:219], v[184:187], v[80:83]
	v_mfma_f32_16x16x32_bf16 v[80:83], v[220:223], v[188:191], v[80:83]
	v_mfma_f32_16x16x32_bf16 v[72:75], v[216:219], v[192:195], v[72:75]
	v_mfma_f32_16x16x32_bf16 v[72:75], v[220:223], v[212:215], v[72:75]
	v_mfma_f32_16x16x32_bf16 v[92:95], v[224:227], v[168:171], v[92:95]
	v_mfma_f32_16x16x32_bf16 v[92:95], v[228:231], v[172:175], v[92:95]
	v_mfma_f32_16x16x32_bf16 v[84:87], v[224:227], v[176:179], v[84:87]
	v_mfma_f32_16x16x32_bf16 v[84:87], v[228:231], v[180:183], v[84:87]
	v_mfma_f32_16x16x32_bf16 v[76:79], v[224:227], v[184:187], v[76:79]
	v_mfma_f32_16x16x32_bf16 v[76:79], v[228:231], v[188:191], v[76:79]
	v_mfma_f32_16x16x32_bf16 v[68:71], v[224:227], v[192:195], v[68:71]
	v_mfma_f32_16x16x32_bf16 v[68:71], v[228:231], v[212:215], v[68:71]
	s_barrier
	s_setprio 0
	ds_read_b128 v[168:171], v146 offset:49152
	ds_read_b128 v[172:175], v146 offset:50176
	ds_read_b128 v[176:179], v146 offset:51200
	ds_read_b128 v[180:183], v146 offset:52224
	ds_read_b128 v[184:187], v146 offset:53248
	ds_read_b128 v[188:191], v146 offset:54272
	ds_read_b128 v[192:195], v146 offset:55296
	ds_read_b128 v[212:215], v146 offset:56320
	global_load_lds_dwordx4 v[142:143], off
	v_lshl_add_u64 v[142:143], v[234:235], 0, s[52:53]
	s_mov_b32 m0, s31
	s_nop 0
	global_load_lds_dwordx4 v[142:143], off
	s_waitcnt lgkmcnt(6)
	s_setprio 1
	s_barrier
	v_mfma_f32_16x16x32_bf16 v[64:67], v[148:151], v[168:171], v[64:67]
	v_mfma_f32_16x16x32_bf16 v[64:67], v[152:155], v[172:175], v[64:67]
	s_waitcnt lgkmcnt(0)
	v_mfma_f32_16x16x32_bf16 v[56:59], v[148:151], v[176:179], v[56:59]
	v_mfma_f32_16x16x32_bf16 v[56:59], v[152:155], v[180:183], v[56:59]
	v_mfma_f32_16x16x32_bf16 v[48:51], v[148:151], v[184:187], v[48:51]
	v_mfma_f32_16x16x32_bf16 v[48:51], v[152:155], v[188:191], v[48:51]
	v_mfma_f32_16x16x32_bf16 v[40:43], v[148:151], v[192:195], v[40:43]
	v_mfma_f32_16x16x32_bf16 v[40:43], v[152:155], v[212:215], v[40:43]
	v_mfma_f32_16x16x32_bf16 v[60:63], v[156:159], v[168:171], v[60:63]
	v_mfma_f32_16x16x32_bf16 v[60:63], v[160:163], v[172:175], v[60:63]
	v_mfma_f32_16x16x32_bf16 v[52:55], v[156:159], v[176:179], v[52:55]
	v_mfma_f32_16x16x32_bf16 v[52:55], v[160:163], v[180:183], v[52:55]
	v_mfma_f32_16x16x32_bf16 v[44:47], v[156:159], v[184:187], v[44:47]
	v_mfma_f32_16x16x32_bf16 v[44:47], v[160:163], v[188:191], v[44:47]
	v_mfma_f32_16x16x32_bf16 v[36:39], v[156:159], v[192:195], v[36:39]
	v_mfma_f32_16x16x32_bf16 v[36:39], v[160:163], v[212:215], v[36:39]
	s_barrier
	s_setprio 0
	s_add_u32 s16, s16, 0x80080
	s_addc_u32 s17, s17, 0
	s_add_i32 s18, s18, s25
	v_lshl_add_u64 v[142:143], s[16:17], 0, v[2:3]
	s_mov_b32 m0, s18
	s_nop 0
	global_load_lds_dwordx4 v[142:143], off
	v_lshl_add_u64 v[142:143], s[16:17], 0, v[0:1]
	s_add_i32 m0, s18, 0x2000
	s_nop 0
	global_load_lds_dwordx4 v[142:143], off
	s_add_i32 s38, s38, 2
	s_add_u32 s36, s36, 0x100
	s_addc_u32 s37, s37, 0
	s_add_u32 s14, s14, 0x100
	s_addc_u32 s15, s15, 0
	s_waitcnt vmcnt(6)
	s_setprio 1
	s_barrier
;   __device__ __forceinline__ void operator()(EPI_ARGS) const {
;     ...
;         f32x4 x0[4], x1[4];
; #pragma unroll
;         for (int m = 0; m < 4; ++m) {
;           const size_t o = (row0 + ai * HALF + m * 16) * DM + col0 + bj * HALF;
;           x0[m] = *(const f32x4*)(xres + o);
;           x1[m] = *(const f32x4*)(xres + o + 4);
;         }
;         __builtin_amdgcn_sched_barrier(0);
; #pragma unroll
;         for (int m = 0; m < 4; ++m) {
;           const size_t o = (row0 + ai * HALF + m * 16) * DM + col0 + bj * HALF;
;           *(f32x4*)(hbuf + o) = acc[ai][bj][m][0] + x0[m] * ALPHA;
;           *(f32x4*)(hbuf + o + 4) = acc[ai][bj][m][1] + x1[m] * ALPHA;
;         }
	v_mfma_f32_16x16x32_bf16 v[32:35], v[216:219], v[168:171], v[32:35]
	v_mfma_f32_16x16x32_bf16 v[32:35], v[220:223], v[172:175], v[32:35]
	v_mfma_f32_16x16x32_bf16 v[24:27], v[216:219], v[176:179], v[24:27]
	v_mfma_f32_16x16x32_bf16 v[24:27], v[220:223], v[180:183], v[24:27]
	v_mfma_f32_16x16x32_bf16 v[16:19], v[216:219], v[184:187], v[16:19]
	v_mfma_f32_16x16x32_bf16 v[16:19], v[220:223], v[188:191], v[16:19]
	v_mfma_f32_16x16x32_bf16 v[8:11], v[216:219], v[192:195], v[8:11]
	v_mfma_f32_16x16x32_bf16 v[8:11], v[220:223], v[212:215], v[8:11]
	v_mfma_f32_16x16x32_bf16 v[28:31], v[224:227], v[168:171], v[28:31]
	v_mfma_f32_16x16x32_bf16 v[28:31], v[228:231], v[172:175], v[28:31]
	v_mfma_f32_16x16x32_bf16 v[20:23], v[224:227], v[176:179], v[20:23]
	v_mfma_f32_16x16x32_bf16 v[20:23], v[228:231], v[180:183], v[20:23]
	v_mfma_f32_16x16x32_bf16 v[12:15], v[224:227], v[184:187], v[12:15]
	v_mfma_f32_16x16x32_bf16 v[12:15], v[228:231], v[188:191], v[12:15]
	v_mfma_f32_16x16x32_bf16 v[4:7], v[224:227], v[192:195], v[4:7]
	v_mfma_f32_16x16x32_bf16 v[4:7], v[228:231], v[212:215], v[4:7]
	s_barrier
	s_setprio 0
	s_cmp_gt_u32 s38, 29
	s_cbranch_scc0 .LBB0_619
	s_ashr_i32 s13, s12, 31
	v_lshl_or_b32 v142, s34, 8, v145
	v_ashrrev_i32_e32 v143, 31, v142
	s_lshl_b64 s[12:13], s[12:13], 21
	v_lshlrev_b64 v[184:185], 2, v[142:143]
	v_lshl_add_u64 v[188:189], s[12:13], 0, v[136:137]
	v_lshl_add_u64 v[186:187], s[0:1], 0, v[184:185]
	v_or_b32_e32 v190, 0x20000, v188
	v_mov_b32_e32 v191, v189
	v_or_b32_e32 v192, 0x40000, v188
	v_mov_b32_e32 v193, v189
	v_or_b32_e32 v194, 0x60000, v188
	v_mov_b32_e32 v195, v189
	v_lshl_add_u64 v[142:143], v[186:187], 0, v[188:189]
	v_lshl_add_u64 v[160:161], v[186:187], 0, v[190:191]
	v_lshl_add_u64 v[172:173], v[186:187], 0, v[192:193]
	v_lshl_add_u64 v[180:181], v[186:187], 0, v[194:195]
	flat_load_dwordx4 v[148:151], v[142:143]
	flat_load_dwordx4 v[152:155], v[142:143] offset:16
	flat_load_dwordx4 v[156:159], v[160:161]
	s_nop 0
	flat_load_dwordx4 v[160:163], v[160:161] offset:16
	s_nop 0
	flat_load_dwordx4 v[168:171], v[172:173]
	s_nop 0
	flat_load_dwordx4 v[172:175], v[172:173] offset:16
	s_nop 0
	flat_load_dwordx4 v[176:179], v[180:181]
	s_nop 0
	flat_load_dwordx4 v[180:183], v[180:181] offset:16
	v_lshl_add_u64 v[184:185], s[48:49], 0, v[184:185]
	s_mov_b32 s14, 0x3fb504f3
	s_waitcnt vmcnt(0) lgkmcnt(0)
	v_pk_fma_f32 v[148:149], v[148:149], s[14:15], v[128:129] op_sel_hi:[1,0,1]
	v_lshl_add_u64 v[128:129], v[184:185], 0, v[188:189]
	v_pk_fma_f32 v[126:127], v[154:155], s[14:15], v[126:127] op_sel_hi:[1,0,1]
	v_pk_fma_f32 v[124:125], v[152:153], s[14:15], v[124:125] op_sel_hi:[1,0,1]
	global_store_dwordx4 v[128:129], v[124:127], off offset:16
	v_pk_fma_f32 v[118:119], v[162:163], s[14:15], v[118:119] op_sel_hi:[1,0,1]
	v_pk_fma_f32 v[116:117], v[160:161], s[14:15], v[116:117] op_sel_hi:[1,0,1]
	v_lshl_add_u64 v[124:125], v[184:185], 0, v[190:191]
	v_pk_fma_f32 v[122:123], v[158:159], s[14:15], v[122:123] op_sel_hi:[1,0,1]
	v_pk_fma_f32 v[120:121], v[156:157], s[14:15], v[120:121] op_sel_hi:[1,0,1]
	global_store_dwordx4 v[124:125], v[116:119], off offset:16
	v_pk_fma_f32 v[110:111], v[174:175], s[14:15], v[110:111] op_sel_hi:[1,0,1]
	v_pk_fma_f32 v[108:109], v[172:173], s[14:15], v[108:109] op_sel_hi:[1,0,1]
	v_lshl_add_u64 v[116:117], v[184:185], 0, v[192:193]
	s_mov_b64 s[12:13], 0x200
	v_pk_fma_f32 v[150:151], v[150:151], s[14:15], v[130:131] op_sel_hi:[1,0,1]
	global_store_dwordx4 v[124:125], v[120:123], off
	v_pk_fma_f32 v[114:115], v[170:171], s[14:15], v[114:115] op_sel_hi:[1,0,1]
	v_pk_fma_f32 v[112:113], v[168:169], s[14:15], v[112:113] op_sel_hi:[1,0,1]
	global_store_dwordx4 v[116:117], v[108:111], off offset:16
	v_pk_fma_f32 v[106:107], v[178:179], s[14:15], v[106:107] op_sel_hi:[1,0,1]
	v_pk_fma_f32 v[104:105], v[176:177], s[14:15], v[104:105] op_sel_hi:[1,0,1]
	v_lshl_add_u64 v[108:109], v[184:185], 0, v[194:195]
	v_pk_fma_f32 v[102:103], v[182:183], s[14:15], v[102:103] op_sel_hi:[1,0,1]
	v_pk_fma_f32 v[100:101], v[180:181], s[14:15], v[100:101] op_sel_hi:[1,0,1]
	v_lshl_add_u64 v[124:125], v[186:187], 0, s[12:13]
	global_store_dwordx4 v[128:129], v[148:151], off
	global_store_dwordx4 v[116:117], v[112:115], off
	global_store_dwordx4 v[108:109], v[104:107], off
	global_store_dwordx4 v[108:109], v[100:103], off offset:16
	v_lshl_add_u64 v[112:113], v[124:125], 0, v[190:191]
	v_lshl_add_u64 v[120:121], v[124:125], 0, v[192:193]
	v_lshl_add_u64 v[130:131], v[124:125], 0, v[194:195]
	flat_load_dwordx4 v[100:103], v[142:143] offset:512
	flat_load_dwordx4 v[104:107], v[142:143] offset:528
	flat_load_dwordx4 v[108:111], v[112:113]
	s_nop 0
	flat_load_dwordx4 v[112:115], v[112:113] offset:16
	s_nop 0
	flat_load_dwordx4 v[116:119], v[120:121]
	s_nop 0
	flat_load_dwordx4 v[120:123], v[120:121] offset:16
	s_nop 0
	flat_load_dwordx4 v[124:127], v[130:131]
	flat_load_dwordx4 v[148:151], v[130:131] offset:16
	s_mov_b32 s3, 0x100000
	s_waitcnt vmcnt(0) lgkmcnt(0)
;   __device__ __forceinline__ void operator()(EPI_ARGS) const {
;     ...
;         f32x4 x0[4], x1[4];
; #pragma unroll
;         for (int m = 0; m < 4; ++m) {
;           const size_t o = (row0 + ai * HALF + m * 16) * DM + col0 + bj * HALF;
;           x0[m] = *(const f32x4*)(xres + o);
;           x1[m] = *(const f32x4*)(xres + o + 4);
;         }
;         __builtin_amdgcn_sched_barrier(0);
; #pragma unroll
;         for (int m = 0; m < 4; ++m) {
;           const size_t o = (row0 + ai * HALF + m * 16) * DM + col0 + bj * HALF;
;           *(f32x4*)(hbuf + o) = acc[ai][bj][m][0] + x0[m] * ALPHA;
;           *(f32x4*)(hbuf + o + 4) = acc[ai][bj][m][1] + x1[m] * ALPHA;
;         }
	v_pk_fma_f32 v[96:97], v[100:101], s[14:15], v[96:97] op_sel_hi:[1,0,1]
	v_add_co_u32_e32 v100, vcc, s3, v142
	s_mov_b32 s5, 0x120000
	s_nop 0
	v_addc_co_u32_e32 v101, vcc, 0, v143, vcc
	v_pk_fma_f32 v[98:99], v[102:103], s[14:15], v[98:99] op_sel_hi:[1,0,1]
	v_add_co_u32_e32 v102, vcc, s5, v142
	v_lshl_add_u64 v[130:131], v[184:185], 0, s[12:13]
	v_pk_fma_f32 v[94:95], v[106:107], s[14:15], v[94:95] op_sel_hi:[1,0,1]
	v_pk_fma_f32 v[92:93], v[104:105], s[14:15], v[92:93] op_sel_hi:[1,0,1]
	v_addc_co_u32_e32 v103, vcc, 0, v143, vcc
	s_mov_b32 s12, 0x140000
	global_store_dwordx4 v[128:129], v[92:95], off offset:528
	v_pk_fma_f32 v[86:87], v[114:115], s[14:15], v[86:87] op_sel_hi:[1,0,1]
	v_pk_fma_f32 v[84:85], v[112:113], s[14:15], v[84:85] op_sel_hi:[1,0,1]
	v_lshl_add_u64 v[92:93], v[130:131], 0, v[190:191]
	v_add_co_u32_e32 v104, vcc, s12, v142
	global_store_dwordx4 v[92:93], v[84:87], off offset:16
	v_pk_fma_f32 v[78:79], v[122:123], s[14:15], v[78:79] op_sel_hi:[1,0,1]
	v_pk_fma_f32 v[76:77], v[120:121], s[14:15], v[76:77] op_sel_hi:[1,0,1]
	v_lshl_add_u64 v[84:85], v[130:131], 0, v[192:193]
	v_addc_co_u32_e32 v105, vcc, 0, v143, vcc
	s_mov_b32 s13, 0x160000
	v_pk_fma_f32 v[90:91], v[110:111], s[14:15], v[90:91] op_sel_hi:[1,0,1]
	v_pk_fma_f32 v[88:89], v[108:109], s[14:15], v[88:89] op_sel_hi:[1,0,1]
	v_pk_fma_f32 v[82:83], v[118:119], s[14:15], v[82:83] op_sel_hi:[1,0,1]
	v_pk_fma_f32 v[80:81], v[116:117], s[14:15], v[80:81] op_sel_hi:[1,0,1]
	global_store_dwordx4 v[84:85], v[76:79], off offset:16
	v_pk_fma_f32 v[74:75], v[126:127], s[14:15], v[74:75] op_sel_hi:[1,0,1]
	v_pk_fma_f32 v[72:73], v[124:125], s[14:15], v[72:73] op_sel_hi:[1,0,1]
	v_lshl_add_u64 v[76:77], v[130:131], 0, v[194:195]
	v_pk_fma_f32 v[70:71], v[150:151], s[14:15], v[70:71] op_sel_hi:[1,0,1]
	v_pk_fma_f32 v[68:69], v[148:149], s[14:15], v[68:69] op_sel_hi:[1,0,1]
	s_mov_b64 s[16:17], 0x100000
	s_mov_b64 s[18:19], 0x120000
	s_mov_b64 s[34:35], 0x140000
	s_mov_b64 s[36:37], 0x160000
	v_add_co_u32_e32 v106, vcc, s13, v142
	global_store_dwordx4 v[128:129], v[96:99], off offset:512
	global_store_dwordx4 v[92:93], v[88:91], off
	global_store_dwordx4 v[84:85], v[80:83], off
	global_store_dwordx4 v[76:77], v[72:75], off
	global_store_dwordx4 v[76:77], v[68:71], off offset:16
	v_lshl_add_u64 v[80:81], v[142:143], 0, s[18:19]
	v_lshl_add_u64 v[72:73], v[142:143], 0, s[16:17]
	v_lshl_add_u64 v[88:89], v[142:143], 0, s[34:35]
	v_lshl_add_u64 v[96:97], v[142:143], 0, s[36:37]
	v_addc_co_u32_e32 v107, vcc, 0, v143, vcc
	flat_load_dwordx4 v[68:71], v[100:101]
	s_nop 0
	flat_load_dwordx4 v[72:75], v[72:73] offset:16
	s_nop 0
	flat_load_dwordx4 v[76:79], v[102:103]
	s_nop 0
	flat_load_dwordx4 v[80:83], v[80:81] offset:16
	s_nop 0
	flat_load_dwordx4 v[84:87], v[104:105]
	s_nop 0
	flat_load_dwordx4 v[88:91], v[88:89] offset:16
	s_nop 0
	flat_load_dwordx4 v[92:95], v[106:107]
	s_nop 0
	flat_load_dwordx4 v[96:99], v[96:97] offset:16
	s_waitcnt vmcnt(0) lgkmcnt(0)
; #define PG8_WAIT_V(n) asm volatile("s_waitcnt vmcnt(" #n ")" ::: "memory")
; #define PG8_BAR __builtin_amdgcn_s_barrier()
; template <class Epi, class AddrA, class AddrB>
; __device__ __forceinline__ void gemm_phase(const Sched S, const int lda, const int ldb, const int K, const AddrA addrA,
;                                            const AddrB addrB, const Epi E) {
;     ...
;     if (!has_next) break;
;     if (!(Epi::KEEP && cur.br + 1 < S.nbr)) {
; #pragma unroll
;       for (int a = 0; a < 2; ++a)
; #pragma unroll
;         for (int b = 0; b < 2; ++b)
; #pragma unroll
;           for (int m = 0; m < 4; ++m)
; #pragma unroll
;             for (int n = 0; n < 2; ++n) acc[a][b][m][n] = (f32x4){0.f, 0.f, 0.f, 0.f};
;     }
;     cur = nxt; cA = nA; cB = nB; ++ui;
;   }
;   PG8_WAIT_V(0);
;   if (wr == 0) PG8_BAR;
;   PG8_BAR;
;   __device__ __forceinline__ void operator()(EPI_ARGS) const {
;     ...
;         f32x4 x0[4], x1[4];
; #pragma unroll
;         for (int m = 0; m < 4; ++m) {
;           const size_t o = (row0 + ai * HALF + m * 16) * DM + col0 + bj * HALF;
;           x0[m] = *(const f32x4*)(xres + o);
;           x1[m] = *(const f32x4*)(xres + o + 4);
;         }
;         __builtin_amdgcn_sched_barrier(0);
; #pragma unroll
;         for (int m = 0; m < 4; ++m) {
;           const size_t o = (row0 + ai * HALF + m * 16) * DM + col0 + bj * HALF;
;           *(f32x4*)(hbuf + o) = acc[ai][bj][m][0] + x0[m] * ALPHA;
;           *(f32x4*)(hbuf + o + 4) = acc[ai][bj][m][1] + x1[m] * ALPHA;
;         }
	v_pk_fma_f32 v[66:67], v[70:71], s[14:15], v[66:67] op_sel_hi:[1,0,1]
	v_add_co_u32_e32 v70, vcc, s3, v128
	v_pk_fma_f32 v[64:65], v[68:69], s[14:15], v[64:65] op_sel_hi:[1,0,1]
	v_lshl_add_u64 v[68:69], v[128:129], 0, s[16:17]
	v_addc_co_u32_e32 v71, vcc, 0, v129, vcc
	v_pk_fma_f32 v[62:63], v[74:75], s[14:15], v[62:63] op_sel_hi:[1,0,1]
	v_pk_fma_f32 v[60:61], v[72:73], s[14:15], v[60:61] op_sel_hi:[1,0,1]
	global_store_dwordx4 v[68:69], v[60:63], off offset:16
	v_add_co_u32_e32 v68, vcc, s5, v128
	s_nop 0
	v_lshl_add_u64 v[60:61], v[128:129], 0, s[18:19]
	v_addc_co_u32_e32 v69, vcc, 0, v129, vcc
	v_add_co_u32_e32 v72, vcc, s12, v128
	v_pk_fma_f32 v[54:55], v[82:83], s[14:15], v[54:55] op_sel_hi:[1,0,1]
	v_pk_fma_f32 v[52:53], v[80:81], s[14:15], v[52:53] op_sel_hi:[1,0,1]
	v_addc_co_u32_e32 v73, vcc, 0, v129, vcc
	global_store_dwordx4 v[60:61], v[52:55], off offset:16
	v_pk_fma_f32 v[46:47], v[90:91], s[14:15], v[46:47] op_sel_hi:[1,0,1]
	v_pk_fma_f32 v[44:45], v[88:89], s[14:15], v[44:45] op_sel_hi:[1,0,1]
	v_lshl_add_u64 v[52:53], v[128:129], 0, s[34:35]
	v_add_co_u32_e32 v74, vcc, s13, v128
	v_pk_fma_f32 v[58:59], v[78:79], s[14:15], v[58:59] op_sel_hi:[1,0,1]
	v_pk_fma_f32 v[56:57], v[76:77], s[14:15], v[56:57] op_sel_hi:[1,0,1]
	v_pk_fma_f32 v[50:51], v[86:87], s[14:15], v[50:51] op_sel_hi:[1,0,1]
	v_pk_fma_f32 v[48:49], v[84:85], s[14:15], v[48:49] op_sel_hi:[1,0,1]
	global_store_dwordx4 v[52:53], v[44:47], off offset:16
	v_pk_fma_f32 v[42:43], v[94:95], s[14:15], v[42:43] op_sel_hi:[1,0,1]
	v_pk_fma_f32 v[40:41], v[92:93], s[14:15], v[40:41] op_sel_hi:[1,0,1]
	v_lshl_add_u64 v[44:45], v[128:129], 0, s[36:37]
	v_addc_co_u32_e32 v75, vcc, 0, v129, vcc
	v_pk_fma_f32 v[38:39], v[98:99], s[14:15], v[38:39] op_sel_hi:[1,0,1]
	v_pk_fma_f32 v[36:37], v[96:97], s[14:15], v[36:37] op_sel_hi:[1,0,1]
	s_mov_b64 s[12:13], 0x100200
	s_mov_b64 s[16:17], 0x120200
	s_mov_b64 s[18:19], 0x140200
	s_mov_b64 s[34:35], 0x160200
	global_store_dwordx4 v[70:71], v[64:67], off
	global_store_dwordx4 v[68:69], v[56:59], off
	global_store_dwordx4 v[72:73], v[48:51], off
	global_store_dwordx4 v[74:75], v[40:43], off
	global_store_dwordx4 v[44:45], v[36:39], off offset:16
	v_lshl_add_u64 v[44:45], v[142:143], 0, s[12:13]
	v_lshl_add_u64 v[48:49], v[142:143], 0, s[16:17]
	v_lshl_add_u64 v[60:61], v[142:143], 0, s[18:19]
	v_lshl_add_u64 v[64:65], v[142:143], 0, s[34:35]
	flat_load_dwordx4 v[36:39], v[100:101] offset:512
	flat_load_dwordx4 v[40:43], v[102:103] offset:512
	s_nop 0
	flat_load_dwordx4 v[44:47], v[44:45] offset:16
	s_nop 0
	flat_load_dwordx4 v[48:51], v[48:49] offset:16
	s_nop 0
	flat_load_dwordx4 v[52:55], v[104:105] offset:512
	flat_load_dwordx4 v[56:59], v[106:107] offset:512
	s_nop 0
	flat_load_dwordx4 v[60:63], v[60:61] offset:16
	s_nop 0
	flat_load_dwordx4 v[64:67], v[64:65] offset:16
	s_waitcnt vmcnt(0) lgkmcnt(0)
	v_pk_fma_f32 v[32:33], v[36:37], s[14:15], v[32:33] op_sel_hi:[1,0,1]
	v_lshl_add_u64 v[36:37], v[128:129], 0, s[12:13]
	v_pk_fma_f32 v[30:31], v[46:47], s[14:15], v[30:31] op_sel_hi:[1,0,1]
	v_pk_fma_f32 v[28:29], v[44:45], s[14:15], v[28:29] op_sel_hi:[1,0,1]
	global_store_dwordx4 v[36:37], v[28:31], off offset:16
	v_pk_fma_f32 v[22:23], v[50:51], s[14:15], v[22:23] op_sel_hi:[1,0,1]
	v_pk_fma_f32 v[20:21], v[48:49], s[14:15], v[20:21] op_sel_hi:[1,0,1]
	v_lshl_add_u64 v[28:29], v[128:129], 0, s[16:17]
	global_store_dwordx4 v[28:29], v[20:23], off offset:16
	v_pk_fma_f32 v[14:15], v[62:63], s[14:15], v[14:15] op_sel_hi:[1,0,1]
	v_pk_fma_f32 v[12:13], v[60:61], s[14:15], v[12:13] op_sel_hi:[1,0,1]
	v_lshl_add_u64 v[20:21], v[128:129], 0, s[18:19]
	v_pk_fma_f32 v[34:35], v[38:39], s[14:15], v[34:35] op_sel_hi:[1,0,1]
	v_pk_fma_f32 v[26:27], v[42:43], s[14:15], v[26:27] op_sel_hi:[1,0,1]
	v_pk_fma_f32 v[24:25], v[40:41], s[14:15], v[24:25] op_sel_hi:[1,0,1]
	v_pk_fma_f32 v[18:19], v[54:55], s[14:15], v[18:19] op_sel_hi:[1,0,1]
	v_pk_fma_f32 v[16:17], v[52:53], s[14:15], v[16:17] op_sel_hi:[1,0,1]
	global_store_dwordx4 v[20:21], v[12:15], off offset:16
	v_pk_fma_f32 v[10:11], v[58:59], s[14:15], v[10:11] op_sel_hi:[1,0,1]
	v_pk_fma_f32 v[8:9], v[56:57], s[14:15], v[8:9] op_sel_hi:[1,0,1]
	v_lshl_add_u64 v[12:13], v[128:129], 0, s[34:35]
	v_pk_fma_f32 v[6:7], v[66:67], s[14:15], v[6:7] op_sel_hi:[1,0,1]
	v_pk_fma_f32 v[4:5], v[64:65], s[14:15], v[4:5] op_sel_hi:[1,0,1]
	s_and_b64 vcc, exec, s[6:7]
	s_mov_b32 s34, s4
	s_mov_b32 s12, s2
	s_mov_b64 s[14:15], s[10:11]
	s_mov_b64 s[16:17], s[8:9]
	global_store_dwordx4 v[70:71], v[32:35], off offset:512
	global_store_dwordx4 v[68:69], v[24:27], off offset:512
	global_store_dwordx4 v[72:73], v[16:19], off offset:512
	global_store_dwordx4 v[74:75], v[8:11], off offset:512
	global_store_dwordx4 v[12:13], v[4:7], off offset:16
	s_cbranch_vccz .LBB0_616
	s_waitcnt vmcnt(0)
	s_cmpk_gt_u32 s20, 0xff
	s_cbranch_scc1 .LBB0_623
	s_barrier
